# saddr-form LDS-DMA in GEMM loops + setprio/waitcnt trimmed off MFMA segment edges + attention half-step stagger (waves 4-7)
# speedup vs baseline: 1.0084x; 1.0084x over previous
; #define PG8_STAGE(bufoff, gbase, voff) do { _Pragma("unroll") for (int _i = 0; _i < 2; ++_i) \
;         __builtin_amdgcn_global_load_lds((const unsigned*)((const char*)(gbase) + (voff)[_i]), (LAS unsigned*)(lds + (bufoff) + ldsw + _i * 8192), 16, 0, 0); } while (0)
; #define PG8_LDA(dst, b, h) do { _Pragma("unroll") for (int m = 0; m < 4; ++m) _Pragma("unroll") for (int k = 0; k < 2; ++k) dst[m][k] = *(const LAS bf16x8*)(lds + PG8_SA(b, h) + aoff + m * 2048 + k * 1024); } while (0)
; #define PG8_LDB(dst, b, h) do { _Pragma("unroll") for (int n = 0; n < 2; ++n) _Pragma("unroll") for (int k = 0; k < 2; ++k) dst[n][k] = *(const LAS bf16x8*)(lds + PG8_SB(b, h) + boff + n * 2048 + k * 1024); } while (0)
; #define PG8_MMA(ai, bj, At, Bt) do { __builtin_amdgcn_s_setprio(1); _Pragma("unroll") for (int m = 0; m < 4; ++m) _Pragma("unroll") for (int n = 0; n < 2; ++n) _Pragma("unroll") for (int k = 0; k < 2; ++k) \
;         acc[ai][bj][m][n] = __builtin_amdgcn_mfma_f32_16x16x32_bf16(Bt[n][k], At[m][k], acc[ai][bj][m][n], 0, 0, 0); __builtin_amdgcn_s_setprio(0); } while (0)
; #define PG8_WAIT_V(n) asm volatile("s_waitcnt vmcnt(" #n ")" ::: "memory")
; #define PG8_WAIT_L(n) asm volatile("s_waitcnt lgkmcnt(" #n ")" ::: "memory")
; #define PG8_BAR __builtin_amdgcn_s_barrier()
; #define PG8_SCHED __builtin_amdgcn_sched_barrier(0)
; template <class Epi>
; __device__ __forceinline__ void gemm_phase(LAS unsigned char* lds, const Gemm g, const StaticOrder& S, const Epi& E) {
;     ...
;             PG8_LDB(B0, 0, 0); PG8_LDB(B1, 0, 1); PG8_SCHED; PG8_LDA(At, 0, 0); PG8_STAGE(PG8_SA(1, 1), a1 + hstep, voffA);
;             PG8_WAIT_V(8); PG8_WAIT_L(0); PG8_BAR; PG8_MMA(0, 0, At, B0); PG8_MMA(0, 1, At, B1); PG8_BAR; PG8_SCHED;
;             PG8_LDA(At, 0, 1); PG8_STAGE(PG8_SB(0, 0), b2, voffB); PG8_STAGE(PG8_SB(0, 1), b2 + hstep, voffB); PG8_STAGE(PG8_SA(0, 0), a2, voffA);
;             PG8_WAIT_V(8); PG8_WAIT_L(0); PG8_BAR; PG8_MMA(1, 0, At, B0); PG8_MMA(1, 1, At, B1); PG8_BAR; PG8_SCHED;
.LBB0_134:
	ds_read_b128 v[156:159], v150
	ds_read_b128 v[160:163], v150 offset:1024
	ds_read_b128 v[164:167], v150 offset:2048
	ds_read_b128 v[172:175], v150 offset:3072
	ds_read_b128 v[176:179], v151
	ds_read_b128 v[180:183], v151 offset:1024
	ds_read_b128 v[184:187], v151 offset:2048
	ds_read_b128 v[188:191], v151 offset:3072
	s_add_u32 s66, s64, 0xfffc0080
	s_addc_u32 s67, s65, -1
	s_cmp_eq_u32 s92, 12
	s_cselect_b32 s69, s87, s67
	s_cselect_b32 s68, s88, s66
	s_cselect_b32 s67, s47, s91
	s_cselect_b32 s66, s89, s90
	s_add_i32 m0, s61, 0xc000
	ds_read_b128 v[192:195], v152
	ds_read_b128 v[196:199], v152 offset:1024
	ds_read_b128 v[200:203], v152 offset:2048
	ds_read_b128 v[204:207], v152 offset:3072
	ds_read_b128 v[208:211], v152 offset:4096
	ds_read_b128 v[212:215], v152 offset:5120
	ds_read_b128 v[216:219], v152 offset:6144
	ds_read_b128 v[220:223], v152 offset:7168
	global_load_lds_dwordx4 v140, s[64:65]
	s_add_i32 m0, s61, 0xe000
	s_nop 0
	global_load_lds_dwordx4 v142, s[64:65]
	s_waitcnt vmcnt(8)
	s_waitcnt lgkmcnt(0)
	s_setprio 1
	s_barrier
	v_mfma_f32_16x16x32_bf16 v[126:129], v[156:159], v[192:195], v[126:129]
	v_mfma_f32_16x16x32_bf16 v[118:121], v[164:167], v[192:195], v[118:121]
	v_mfma_f32_16x16x32_bf16 v[110:113], v[156:159], v[200:203], v[110:113]
	v_mfma_f32_16x16x32_bf16 v[102:105], v[164:167], v[200:203], v[102:105]
	v_mfma_f32_16x16x32_bf16 v[94:97], v[156:159], v[208:211], v[94:97]
	v_mfma_f32_16x16x32_bf16 v[86:89], v[164:167], v[208:211], v[86:89]
	v_mfma_f32_16x16x32_bf16 v[78:81], v[156:159], v[216:219], v[78:81]
	v_mfma_f32_16x16x32_bf16 v[70:73], v[164:167], v[216:219], v[70:73]
	v_mfma_f32_16x16x32_bf16 v[126:129], v[160:163], v[196:199], v[126:129]
	v_mfma_f32_16x16x32_bf16 v[118:121], v[172:175], v[196:199], v[118:121]
	v_mfma_f32_16x16x32_bf16 v[110:113], v[160:163], v[204:207], v[110:113]
	v_mfma_f32_16x16x32_bf16 v[102:105], v[172:175], v[204:207], v[102:105]
	v_mfma_f32_16x16x32_bf16 v[94:97], v[160:163], v[212:215], v[94:97]
	v_mfma_f32_16x16x32_bf16 v[86:89], v[172:175], v[212:215], v[86:89]
	v_mfma_f32_16x16x32_bf16 v[78:81], v[160:163], v[220:223], v[78:81]
	v_mfma_f32_16x16x32_bf16 v[70:73], v[172:175], v[220:223], v[70:73]
	v_mfma_f32_16x16x32_bf16 v[122:125], v[176:179], v[192:195], v[122:125]
	v_mfma_f32_16x16x32_bf16 v[114:117], v[184:187], v[192:195], v[114:117]
	v_mfma_f32_16x16x32_bf16 v[106:109], v[176:179], v[200:203], v[106:109]
	v_mfma_f32_16x16x32_bf16 v[98:101], v[184:187], v[200:203], v[98:101]
	v_mfma_f32_16x16x32_bf16 v[90:93], v[176:179], v[208:211], v[90:93]
	v_mfma_f32_16x16x32_bf16 v[82:85], v[184:187], v[208:211], v[82:85]
	v_mfma_f32_16x16x32_bf16 v[74:77], v[176:179], v[216:219], v[74:77]
	v_mfma_f32_16x16x32_bf16 v[66:69], v[184:187], v[216:219], v[66:69]
	v_mfma_f32_16x16x32_bf16 v[122:125], v[180:183], v[196:199], v[122:125]
	v_mfma_f32_16x16x32_bf16 v[114:117], v[188:191], v[196:199], v[114:117]
	v_mfma_f32_16x16x32_bf16 v[106:109], v[180:183], v[204:207], v[106:109]
	v_mfma_f32_16x16x32_bf16 v[98:101], v[188:191], v[204:207], v[98:101]
	v_mfma_f32_16x16x32_bf16 v[90:93], v[180:183], v[212:215], v[90:93]
	v_mfma_f32_16x16x32_bf16 v[82:85], v[188:191], v[212:215], v[82:85]
	v_mfma_f32_16x16x32_bf16 v[74:77], v[180:183], v[220:223], v[74:77]
	v_mfma_f32_16x16x32_bf16 v[66:69], v[188:191], v[220:223], v[66:69]
	s_barrier
	s_setprio 0
	s_add_u32 s98, s66, s8
	s_addc_u32 s99, s67, s9
	s_add_u32 s100, s68, s8
	s_addc_u32 s101, s69, s9
	s_add_i32 s93, s83, s6
	s_mov_b32 m0, s93
	ds_read_b128 v[192:195], v152 offset:16384
	ds_read_b128 v[196:199], v152 offset:17408
	ds_read_b128 v[200:203], v152 offset:18432
	ds_read_b128 v[204:207], v152 offset:19456
	ds_read_b128 v[208:211], v152 offset:20480
	ds_read_b128 v[212:215], v152 offset:21504
	ds_read_b128 v[216:219], v152 offset:22528
	ds_read_b128 v[220:223], v152 offset:23552
	global_load_lds_dwordx4 v132, s[66:67]
	s_add_i32 m0, s93, 0x2000
	s_add_u32 s94, s66, 0x40000
	s_addc_u32 s95, s67, 0
	s_add_i32 s93, s84, s6
	global_load_lds_dwordx4 v136, s[66:67]
	s_mov_b32 m0, s93
	s_nop 0
	global_load_lds_dwordx4 v132, s[94:95]
	s_add_i32 m0, s93, 0x2000
	s_nop 0
	global_load_lds_dwordx4 v136, s[94:95]
	s_mov_b32 m0, s61
	s_nop 0
	global_load_lds_dwordx4 v130, s[68:69]
	s_mov_b32 m0, s63
	s_nop 0
	global_load_lds_dwordx4 v134, s[68:69]
	s_waitcnt vmcnt(8)
	s_waitcnt lgkmcnt(0)
	s_setprio 1
	s_barrier
	v_mfma_f32_16x16x32_bf16 v[62:65], v[156:159], v[192:195], v[62:65]
	v_mfma_f32_16x16x32_bf16 v[54:57], v[164:167], v[192:195], v[54:57]
	v_mfma_f32_16x16x32_bf16 v[46:49], v[156:159], v[200:203], v[46:49]
	v_mfma_f32_16x16x32_bf16 v[38:41], v[164:167], v[200:203], v[38:41]
	v_mfma_f32_16x16x32_bf16 v[30:33], v[156:159], v[208:211], v[30:33]
	v_mfma_f32_16x16x32_bf16 v[22:25], v[164:167], v[208:211], v[22:25]
	v_mfma_f32_16x16x32_bf16 v[14:17], v[156:159], v[216:219], v[14:17]
	v_mfma_f32_16x16x32_bf16 v[6:9], v[164:167], v[216:219], v[6:9]
	v_mfma_f32_16x16x32_bf16 v[62:65], v[160:163], v[196:199], v[62:65]
	v_mfma_f32_16x16x32_bf16 v[54:57], v[172:175], v[196:199], v[54:57]
	v_mfma_f32_16x16x32_bf16 v[46:49], v[160:163], v[204:207], v[46:49]
	v_mfma_f32_16x16x32_bf16 v[38:41], v[172:175], v[204:207], v[38:41]
	v_mfma_f32_16x16x32_bf16 v[30:33], v[160:163], v[212:215], v[30:33]
	v_mfma_f32_16x16x32_bf16 v[22:25], v[172:175], v[212:215], v[22:25]
	v_mfma_f32_16x16x32_bf16 v[14:17], v[160:163], v[220:223], v[14:17]
	v_mfma_f32_16x16x32_bf16 v[6:9], v[172:175], v[220:223], v[6:9]
	v_mfma_f32_16x16x32_bf16 v[58:61], v[176:179], v[192:195], v[58:61]
	v_mfma_f32_16x16x32_bf16 v[50:53], v[184:187], v[192:195], v[50:53]
	v_mfma_f32_16x16x32_bf16 v[42:45], v[176:179], v[200:203], v[42:45]
	v_mfma_f32_16x16x32_bf16 v[34:37], v[184:187], v[200:203], v[34:37]
	v_mfma_f32_16x16x32_bf16 v[26:29], v[176:179], v[208:211], v[26:29]
	v_mfma_f32_16x16x32_bf16 v[18:21], v[184:187], v[208:211], v[18:21]
	v_mfma_f32_16x16x32_bf16 v[10:13], v[176:179], v[216:219], v[10:13]
	v_mfma_f32_16x16x32_bf16 v[2:5], v[184:187], v[216:219], v[2:5]
	v_mfma_f32_16x16x32_bf16 v[58:61], v[180:183], v[196:199], v[58:61]
	v_mfma_f32_16x16x32_bf16 v[50:53], v[188:191], v[196:199], v[50:53]
	v_mfma_f32_16x16x32_bf16 v[42:45], v[180:183], v[204:207], v[42:45]
	v_mfma_f32_16x16x32_bf16 v[34:37], v[188:191], v[204:207], v[34:37]
	v_mfma_f32_16x16x32_bf16 v[26:29], v[180:183], v[212:215], v[26:29]
	v_mfma_f32_16x16x32_bf16 v[18:21], v[188:191], v[212:215], v[18:21]
	v_mfma_f32_16x16x32_bf16 v[10:13], v[180:183], v[220:223], v[10:13]
	v_mfma_f32_16x16x32_bf16 v[2:5], v[188:191], v[220:223], v[2:5]
	s_barrier
; #define PG8_STAGE(bufoff, gbase, voff) do { _Pragma("unroll") for (int _i = 0; _i < 2; ++_i) \
;         __builtin_amdgcn_global_load_lds((const unsigned*)((const char*)(gbase) + (voff)[_i]), (LAS unsigned*)(lds + (bufoff) + ldsw + _i * 8192), 16, 0, 0); } while (0)
; #define PG8_LDA(dst, b, h) do { _Pragma("unroll") for (int m = 0; m < 4; ++m) _Pragma("unroll") for (int k = 0; k < 2; ++k) dst[m][k] = *(const LAS bf16x8*)(lds + PG8_SA(b, h) + aoff + m * 2048 + k * 1024); } while (0)
; #define PG8_LDB(dst, b, h) do { _Pragma("unroll") for (int n = 0; n < 2; ++n) _Pragma("unroll") for (int k = 0; k < 2; ++k) dst[n][k] = *(const LAS bf16x8*)(lds + PG8_SB(b, h) + boff + n * 2048 + k * 1024); } while (0)
; #define PG8_MMA(ai, bj, At, Bt) do { __builtin_amdgcn_s_setprio(1); _Pragma("unroll") for (int m = 0; m < 4; ++m) _Pragma("unroll") for (int n = 0; n < 2; ++n) _Pragma("unroll") for (int k = 0; k < 2; ++k) \
;         acc[ai][bj][m][n] = __builtin_amdgcn_mfma_f32_16x16x32_bf16(Bt[n][k], At[m][k], acc[ai][bj][m][n], 0, 0, 0); __builtin_amdgcn_s_setprio(0); } while (0)
; #define PG8_WAIT_V(n) asm volatile("s_waitcnt vmcnt(" #n ")" ::: "memory")
; #define PG8_WAIT_L(n) asm volatile("s_waitcnt lgkmcnt(" #n ")" ::: "memory")
; #define PG8_BAR __builtin_amdgcn_s_barrier()
; #define PG8_SCHED __builtin_amdgcn_sched_barrier(0)
; template <class Epi>
; __device__ __forceinline__ void gemm_phase(LAS unsigned char* lds, const Gemm g, const StaticOrder& S, const Epi& E) {
;     ...
;             PG8_LDB(B0, 1, 0); PG8_LDB(B1, 1, 1); PG8_SCHED; PG8_LDA(At, 1, 0); PG8_STAGE(PG8_SA(0, 1), a2 + hstep, voffA);
;             PG8_WAIT_V(8); PG8_WAIT_L(0); PG8_BAR; PG8_MMA(0, 0, At, B0); PG8_MMA(0, 1, At, B1); PG8_BAR; PG8_SCHED;
;             PG8_LDA(At, 1, 1); PG8_STAGE(PG8_SB(1, 0), b3, voffB); PG8_STAGE(PG8_SB(1, 1), b3 + hstep, voffB); PG8_STAGE(PG8_SA(1, 0), a3, voffA);
;             PG8_WAIT_V(8); PG8_WAIT_L(0); PG8_BAR; PG8_MMA(1, 0, At, B0); PG8_MMA(1, 1, At, B1); PG8_BAR; PG8_SCHED;
;         }
	s_setprio 0
	s_add_i32 s93, 0, 0x18000
	s_add_i32 s94, 0, 0x1c000
	v_add_u32_e32 v172, s93, v148
	v_add_u32_e32 v188, s94, v148
	ds_read_b128 v[156:159], v172
	ds_read_b128 v[160:163], v172 offset:1024
	ds_read_b128 v[164:167], v172 offset:2048
	ds_read_b128 v[172:175], v172 offset:3072
	ds_read_b128 v[176:179], v188
	ds_read_b128 v[180:183], v188 offset:1024
	ds_read_b128 v[184:187], v188 offset:2048
	ds_read_b128 v[188:191], v188 offset:3072
	s_add_u32 s68, s68, 0x40000
	s_addc_u32 s69, s69, 0
	s_mov_b32 m0, s77
	ds_read_b128 v[192:195], v152 offset:32768
	ds_read_b128 v[196:199], v152 offset:33792
	ds_read_b128 v[200:203], v152 offset:34816
	ds_read_b128 v[204:207], v152 offset:35840
	ds_read_b128 v[208:211], v152 offset:36864
	ds_read_b128 v[212:215], v152 offset:37888
	ds_read_b128 v[216:219], v152 offset:38912
	ds_read_b128 v[220:223], v152 offset:39936
	global_load_lds_dwordx4 v130, s[68:69]
	s_mov_b32 m0, s78
	s_nop 0
	global_load_lds_dwordx4 v134, s[68:69]
	s_waitcnt vmcnt(8)
	s_waitcnt lgkmcnt(0)
	s_setprio 1
	s_barrier
	v_mfma_f32_16x16x32_bf16 v[126:129], v[156:159], v[192:195], v[126:129]
	v_mfma_f32_16x16x32_bf16 v[118:121], v[164:167], v[192:195], v[118:121]
	v_mfma_f32_16x16x32_bf16 v[110:113], v[156:159], v[200:203], v[110:113]
	v_mfma_f32_16x16x32_bf16 v[102:105], v[164:167], v[200:203], v[102:105]
	v_mfma_f32_16x16x32_bf16 v[94:97], v[156:159], v[208:211], v[94:97]
	v_mfma_f32_16x16x32_bf16 v[86:89], v[164:167], v[208:211], v[86:89]
	v_mfma_f32_16x16x32_bf16 v[78:81], v[156:159], v[216:219], v[78:81]
	v_mfma_f32_16x16x32_bf16 v[70:73], v[164:167], v[216:219], v[70:73]
	v_mfma_f32_16x16x32_bf16 v[126:129], v[160:163], v[196:199], v[126:129]
	v_mfma_f32_16x16x32_bf16 v[118:121], v[172:175], v[196:199], v[118:121]
	v_mfma_f32_16x16x32_bf16 v[110:113], v[160:163], v[204:207], v[110:113]
	v_mfma_f32_16x16x32_bf16 v[102:105], v[172:175], v[204:207], v[102:105]
	v_mfma_f32_16x16x32_bf16 v[94:97], v[160:163], v[212:215], v[94:97]
	v_mfma_f32_16x16x32_bf16 v[86:89], v[172:175], v[212:215], v[86:89]
	v_mfma_f32_16x16x32_bf16 v[78:81], v[160:163], v[220:223], v[78:81]
	v_mfma_f32_16x16x32_bf16 v[70:73], v[172:175], v[220:223], v[70:73]
	v_mfma_f32_16x16x32_bf16 v[122:125], v[176:179], v[192:195], v[122:125]
	v_mfma_f32_16x16x32_bf16 v[114:117], v[184:187], v[192:195], v[114:117]
	v_mfma_f32_16x16x32_bf16 v[106:109], v[176:179], v[200:203], v[106:109]
	v_mfma_f32_16x16x32_bf16 v[98:101], v[184:187], v[200:203], v[98:101]
	v_mfma_f32_16x16x32_bf16 v[90:93], v[176:179], v[208:211], v[90:93]
	v_mfma_f32_16x16x32_bf16 v[82:85], v[184:187], v[208:211], v[82:85]
	v_mfma_f32_16x16x32_bf16 v[74:77], v[176:179], v[216:219], v[74:77]
	v_mfma_f32_16x16x32_bf16 v[66:69], v[184:187], v[216:219], v[66:69]
	v_mfma_f32_16x16x32_bf16 v[122:125], v[180:183], v[196:199], v[122:125]
	v_mfma_f32_16x16x32_bf16 v[114:117], v[188:191], v[196:199], v[114:117]
	v_mfma_f32_16x16x32_bf16 v[106:109], v[180:183], v[204:207], v[106:109]
	v_mfma_f32_16x16x32_bf16 v[98:101], v[188:191], v[204:207], v[98:101]
	v_mfma_f32_16x16x32_bf16 v[90:93], v[180:183], v[212:215], v[90:93]
	v_mfma_f32_16x16x32_bf16 v[82:85], v[188:191], v[212:215], v[82:85]
	v_mfma_f32_16x16x32_bf16 v[74:77], v[180:183], v[220:223], v[74:77]
	v_mfma_f32_16x16x32_bf16 v[66:69], v[188:191], v[220:223], v[66:69]
	s_barrier
	s_setprio 0
	s_add_i32 s68, s93, s6
	s_mov_b32 m0, s68
	ds_read_b128 v[192:195], v152 offset:49152
	ds_read_b128 v[196:199], v152 offset:50176
	ds_read_b128 v[200:203], v152 offset:51200
	ds_read_b128 v[204:207], v152 offset:52224
	ds_read_b128 v[208:211], v152 offset:53248
	ds_read_b128 v[212:215], v152 offset:54272
	ds_read_b128 v[216:219], v152 offset:55296
	ds_read_b128 v[220:223], v152 offset:56320
	global_load_lds_dwordx4 v132, s[98:99]
	s_add_i32 m0, s68, 0x2000
	s_add_u32 s66, s66, 0x40080
	s_addc_u32 s67, s67, 0
	s_add_i32 s68, s94, s6
	global_load_lds_dwordx4 v136, s[98:99]
	s_mov_b32 m0, s68
	s_nop 0
	global_load_lds_dwordx4 v132, s[66:67]
	s_add_i32 m0, s68, 0x2000
	s_nop 0
	global_load_lds_dwordx4 v136, s[66:67]
	s_mov_b32 m0, s79
	s_nop 0
	global_load_lds_dwordx4 v130, s[100:101]
	s_mov_b32 m0, s80
	s_nop 0
	global_load_lds_dwordx4 v134, s[100:101]
	s_waitcnt vmcnt(8)
	s_waitcnt lgkmcnt(0)
	s_setprio 1
	s_barrier
	v_mfma_f32_16x16x32_bf16 v[62:65], v[156:159], v[192:195], v[62:65]
	v_mfma_f32_16x16x32_bf16 v[54:57], v[164:167], v[192:195], v[54:57]
	v_mfma_f32_16x16x32_bf16 v[46:49], v[156:159], v[200:203], v[46:49]
	v_mfma_f32_16x16x32_bf16 v[38:41], v[164:167], v[200:203], v[38:41]
	v_mfma_f32_16x16x32_bf16 v[30:33], v[156:159], v[208:211], v[30:33]
	v_mfma_f32_16x16x32_bf16 v[22:25], v[164:167], v[208:211], v[22:25]
	v_mfma_f32_16x16x32_bf16 v[14:17], v[156:159], v[216:219], v[14:17]
	v_mfma_f32_16x16x32_bf16 v[6:9], v[164:167], v[216:219], v[6:9]
	v_mfma_f32_16x16x32_bf16 v[62:65], v[160:163], v[196:199], v[62:65]
	v_mfma_f32_16x16x32_bf16 v[54:57], v[172:175], v[196:199], v[54:57]
	v_mfma_f32_16x16x32_bf16 v[46:49], v[160:163], v[204:207], v[46:49]
	v_mfma_f32_16x16x32_bf16 v[38:41], v[172:175], v[204:207], v[38:41]
	v_mfma_f32_16x16x32_bf16 v[30:33], v[160:163], v[212:215], v[30:33]
	v_mfma_f32_16x16x32_bf16 v[22:25], v[172:175], v[212:215], v[22:25]
	v_mfma_f32_16x16x32_bf16 v[14:17], v[160:163], v[220:223], v[14:17]
	v_mfma_f32_16x16x32_bf16 v[6:9], v[172:175], v[220:223], v[6:9]
	v_mfma_f32_16x16x32_bf16 v[58:61], v[176:179], v[192:195], v[58:61]
	v_mfma_f32_16x16x32_bf16 v[50:53], v[184:187], v[192:195], v[50:53]
	v_mfma_f32_16x16x32_bf16 v[42:45], v[176:179], v[200:203], v[42:45]
	v_mfma_f32_16x16x32_bf16 v[34:37], v[184:187], v[200:203], v[34:37]
	v_mfma_f32_16x16x32_bf16 v[26:29], v[176:179], v[208:211], v[26:29]
	v_mfma_f32_16x16x32_bf16 v[18:21], v[184:187], v[208:211], v[18:21]
	v_mfma_f32_16x16x32_bf16 v[10:13], v[176:179], v[216:219], v[10:13]
	v_mfma_f32_16x16x32_bf16 v[2:5], v[184:187], v[216:219], v[2:5]
	v_mfma_f32_16x16x32_bf16 v[58:61], v[180:183], v[196:199], v[58:61]
	v_mfma_f32_16x16x32_bf16 v[50:53], v[188:191], v[196:199], v[50:53]
	v_mfma_f32_16x16x32_bf16 v[42:45], v[180:183], v[204:207], v[42:45]
	v_mfma_f32_16x16x32_bf16 v[34:37], v[188:191], v[204:207], v[34:37]
	v_mfma_f32_16x16x32_bf16 v[26:29], v[180:183], v[212:215], v[26:29]
	v_mfma_f32_16x16x32_bf16 v[18:21], v[188:191], v[212:215], v[18:21]
	v_mfma_f32_16x16x32_bf16 v[10:13], v[180:183], v[220:223], v[10:13]
	v_mfma_f32_16x16x32_bf16 v[2:5], v[188:191], v[220:223], v[2:5]
	s_barrier
	s_setprio 0
	s_add_i32 s92, s92, 2
	s_add_u32 s64, s64, 0x100
	s_addc_u32 s65, s65, 0
	s_add_u32 s90, s90, 0x100
	s_addc_u32 s91, s91, 0
	s_cmp_gt_u32 s92, 13
	s_cbranch_scc0 .LBB0_134
	s_and_b64 vcc, exec, s[38:39]
	s_cbranch_vccz .LBB0_137
	s_barrier

; #define PG8_STAGE(bufoff, gbase, voff) do { _Pragma("unroll") for (int _i = 0; _i < 2; ++_i) \
;         __builtin_amdgcn_global_load_lds((const unsigned*)((const char*)(gbase) + (voff)[_i]), (LAS unsigned*)(lds + (bufoff) + ldsw + _i * 8192), 16, 0, 0); } while (0)
; #define PG8_LDA(dst, b, h) do { _Pragma("unroll") for (int m = 0; m < 4; ++m) _Pragma("unroll") for (int k = 0; k < 2; ++k) dst[m][k] = *(const LAS bf16x8*)(lds + PG8_SA(b, h) + aoff + m * 2048 + k * 1024); } while (0)
; #define PG8_LDB(dst, b, h) do { _Pragma("unroll") for (int n = 0; n < 2; ++n) _Pragma("unroll") for (int k = 0; k < 2; ++k) dst[n][k] = *(const LAS bf16x8*)(lds + PG8_SB(b, h) + boff + n * 2048 + k * 1024); } while (0)
; #define PG8_MMA(ai, bj, At, Bt) do { __builtin_amdgcn_s_setprio(1); _Pragma("unroll") for (int m = 0; m < 4; ++m) _Pragma("unroll") for (int n = 0; n < 2; ++n) _Pragma("unroll") for (int k = 0; k < 2; ++k) \
;         acc[ai][bj][m][n] = __builtin_amdgcn_mfma_f32_16x16x32_bf16(Bt[n][k], At[m][k], acc[ai][bj][m][n], 0, 0, 0); __builtin_amdgcn_s_setprio(0); } while (0)
; #define PG8_WAIT_V(n) asm volatile("s_waitcnt vmcnt(" #n ")" ::: "memory")
; #define PG8_WAIT_L(n) asm volatile("s_waitcnt lgkmcnt(" #n ")" ::: "memory")
; #define PG8_BAR __builtin_amdgcn_s_barrier()
; #define PG8_SCHED __builtin_amdgcn_sched_barrier(0)
; template <class Epi>
; __device__ __forceinline__ void gemm_phase(LAS unsigned char* lds, const Gemm g, const StaticOrder& S, const Epi& E) {
;     ...
;             PG8_LDB(B0, 0, 0); PG8_LDB(B1, 0, 1); PG8_SCHED; PG8_LDA(At, 0, 0); PG8_STAGE(PG8_SA(1, 1), a1 + hstep, voffA);
;             PG8_WAIT_V(8); PG8_WAIT_L(0); PG8_BAR; PG8_MMA(0, 0, At, B0); PG8_MMA(0, 1, At, B1); PG8_BAR; PG8_SCHED;
;             PG8_LDA(At, 0, 1); PG8_STAGE(PG8_SB(0, 0), b2, voffB); PG8_STAGE(PG8_SB(0, 1), b2 + hstep, voffB); PG8_STAGE(PG8_SA(0, 0), a2, voffA);
;             PG8_WAIT_V(8); PG8_WAIT_L(0); PG8_BAR; PG8_MMA(1, 0, At, B0); PG8_MMA(1, 1, At, B1); PG8_BAR; PG8_SCHED;
.LBB0_221:
	ds_read_b128 v[130:133], v162
	ds_read_b128 v[134:137], v162 offset:1024
	ds_read_b128 v[154:157], v162 offset:2048
	ds_read_b128 v[166:169], v162 offset:3072
	ds_read_b128 v[172:175], v163
	ds_read_b128 v[176:179], v163 offset:1024
	ds_read_b128 v[180:183], v163 offset:2048
	ds_read_b128 v[184:187], v163 offset:3072
	s_add_u32 s48, s46, 0xfff50080
	s_addc_u32 s49, s47, -1
	s_cmp_eq_u32 s84, 40
	s_cselect_b32 s51, s5, s49
	s_cselect_b32 s50, s4, s48
	s_cselect_b32 s49, s45, s83
	s_cselect_b32 s48, s44, s82
	s_add_i32 m0, s59, 0xc000
	ds_read_b128 v[188:191], v164
	ds_read_b128 v[192:195], v164 offset:1024
	ds_read_b128 v[196:199], v164 offset:2048
	ds_read_b128 v[200:203], v164 offset:3072
	ds_read_b128 v[204:207], v164 offset:4096
	ds_read_b128 v[208:211], v164 offset:5120
	ds_read_b128 v[212:215], v164 offset:6144
	ds_read_b128 v[216:219], v164 offset:7168
	global_load_lds_dwordx4 v146, s[46:47]
	s_add_i32 m0, s59, 0xe000
	s_nop 0
	global_load_lds_dwordx4 v148, s[46:47]
	s_waitcnt vmcnt(8)
	s_waitcnt lgkmcnt(0)
	s_setprio 1
	s_barrier
	v_mfma_f32_16x16x32_bf16 v[126:129], v[130:133], v[188:191], v[126:129]
	v_mfma_f32_16x16x32_bf16 v[122:125], v[154:157], v[188:191], v[122:125]
	v_mfma_f32_16x16x32_bf16 v[110:113], v[130:133], v[196:199], v[110:113]
	v_mfma_f32_16x16x32_bf16 v[106:109], v[154:157], v[196:199], v[106:109]
	v_mfma_f32_16x16x32_bf16 v[94:97], v[130:133], v[204:207], v[94:97]
	v_mfma_f32_16x16x32_bf16 v[90:93], v[154:157], v[204:207], v[90:93]
	v_mfma_f32_16x16x32_bf16 v[78:81], v[130:133], v[212:215], v[78:81]
	v_mfma_f32_16x16x32_bf16 v[74:77], v[154:157], v[212:215], v[74:77]
	v_mfma_f32_16x16x32_bf16 v[126:129], v[134:137], v[192:195], v[126:129]
	v_mfma_f32_16x16x32_bf16 v[122:125], v[166:169], v[192:195], v[122:125]
	v_mfma_f32_16x16x32_bf16 v[110:113], v[134:137], v[200:203], v[110:113]
	v_mfma_f32_16x16x32_bf16 v[106:109], v[166:169], v[200:203], v[106:109]
	v_mfma_f32_16x16x32_bf16 v[94:97], v[134:137], v[208:211], v[94:97]
	v_mfma_f32_16x16x32_bf16 v[90:93], v[166:169], v[208:211], v[90:93]
	v_mfma_f32_16x16x32_bf16 v[78:81], v[134:137], v[216:219], v[78:81]
	v_mfma_f32_16x16x32_bf16 v[74:77], v[166:169], v[216:219], v[74:77]
	v_mfma_f32_16x16x32_bf16 v[118:121], v[172:175], v[188:191], v[118:121]
	v_mfma_f32_16x16x32_bf16 v[114:117], v[180:183], v[188:191], v[114:117]
	v_mfma_f32_16x16x32_bf16 v[102:105], v[172:175], v[196:199], v[102:105]
	v_mfma_f32_16x16x32_bf16 v[98:101], v[180:183], v[196:199], v[98:101]
	v_mfma_f32_16x16x32_bf16 v[86:89], v[172:175], v[204:207], v[86:89]
	v_mfma_f32_16x16x32_bf16 v[82:85], v[180:183], v[204:207], v[82:85]
	v_mfma_f32_16x16x32_bf16 v[70:73], v[172:175], v[212:215], v[70:73]
	v_mfma_f32_16x16x32_bf16 v[66:69], v[180:183], v[212:215], v[66:69]
	v_mfma_f32_16x16x32_bf16 v[118:121], v[176:179], v[192:195], v[118:121]
	v_mfma_f32_16x16x32_bf16 v[114:117], v[184:187], v[192:195], v[114:117]
	v_mfma_f32_16x16x32_bf16 v[102:105], v[176:179], v[200:203], v[102:105]
	v_mfma_f32_16x16x32_bf16 v[98:101], v[184:187], v[200:203], v[98:101]
	v_mfma_f32_16x16x32_bf16 v[86:89], v[176:179], v[208:211], v[86:89]
	v_mfma_f32_16x16x32_bf16 v[82:85], v[184:187], v[208:211], v[82:85]
	v_mfma_f32_16x16x32_bf16 v[70:73], v[176:179], v[216:219], v[70:73]
	v_mfma_f32_16x16x32_bf16 v[66:69], v[184:187], v[216:219], v[66:69]
	s_barrier
	s_setprio 0
	s_add_u32 s98, s48, s38
	s_addc_u32 s99, s49, s39
	s_add_u32 s100, s50, s38
	s_addc_u32 s101, s51, s39
	s_add_i32 s85, s76, s58
	s_mov_b32 m0, s85
	ds_read_b128 v[188:191], v164 offset:16384
	ds_read_b128 v[192:195], v164 offset:17408
	ds_read_b128 v[196:199], v164 offset:18432
	ds_read_b128 v[200:203], v164 offset:19456
	ds_read_b128 v[204:207], v164 offset:20480
	ds_read_b128 v[208:211], v164 offset:21504
	ds_read_b128 v[212:215], v164 offset:22528
	ds_read_b128 v[216:219], v164 offset:23552
	global_load_lds_dwordx4 v140, s[48:49]
	s_add_i32 m0, s85, 0x2000
	s_add_u32 s86, s48, 0xb0000
	s_addc_u32 s87, s49, 0
	s_add_i32 s85, s77, s58
	global_load_lds_dwordx4 v144, s[48:49]
	s_mov_b32 m0, s85
	s_nop 0
	global_load_lds_dwordx4 v140, s[86:87]
	s_add_i32 m0, s85, 0x2000
	s_nop 0
	global_load_lds_dwordx4 v144, s[86:87]
	s_mov_b32 m0, s59
	s_nop 0
	global_load_lds_dwordx4 v138, s[50:51]
	s_mov_b32 m0, s60
	s_nop 0
	global_load_lds_dwordx4 v142, s[50:51]
	s_waitcnt vmcnt(8)
	s_waitcnt lgkmcnt(0)
	s_setprio 1
	s_barrier
	v_mfma_f32_16x16x32_bf16 v[62:65], v[130:133], v[188:191], v[62:65]
	v_mfma_f32_16x16x32_bf16 v[58:61], v[154:157], v[188:191], v[58:61]
	v_mfma_f32_16x16x32_bf16 v[46:49], v[130:133], v[196:199], v[46:49]
	v_mfma_f32_16x16x32_bf16 v[42:45], v[154:157], v[196:199], v[42:45]
	v_mfma_f32_16x16x32_bf16 v[30:33], v[130:133], v[204:207], v[30:33]
	v_mfma_f32_16x16x32_bf16 v[26:29], v[154:157], v[204:207], v[26:29]
	v_mfma_f32_16x16x32_bf16 v[14:17], v[130:133], v[212:215], v[14:17]
	v_mfma_f32_16x16x32_bf16 v[10:13], v[154:157], v[212:215], v[10:13]
	v_mfma_f32_16x16x32_bf16 v[62:65], v[134:137], v[192:195], v[62:65]
	v_mfma_f32_16x16x32_bf16 v[58:61], v[166:169], v[192:195], v[58:61]
	v_mfma_f32_16x16x32_bf16 v[46:49], v[134:137], v[200:203], v[46:49]
	v_mfma_f32_16x16x32_bf16 v[42:45], v[166:169], v[200:203], v[42:45]
	v_mfma_f32_16x16x32_bf16 v[30:33], v[134:137], v[208:211], v[30:33]
	v_mfma_f32_16x16x32_bf16 v[26:29], v[166:169], v[208:211], v[26:29]
	v_mfma_f32_16x16x32_bf16 v[14:17], v[134:137], v[216:219], v[14:17]
	v_mfma_f32_16x16x32_bf16 v[10:13], v[166:169], v[216:219], v[10:13]
	v_mfma_f32_16x16x32_bf16 v[54:57], v[172:175], v[188:191], v[54:57]
	v_mfma_f32_16x16x32_bf16 v[50:53], v[180:183], v[188:191], v[50:53]
	v_mfma_f32_16x16x32_bf16 v[38:41], v[172:175], v[196:199], v[38:41]
	v_mfma_f32_16x16x32_bf16 v[34:37], v[180:183], v[196:199], v[34:37]
	v_mfma_f32_16x16x32_bf16 v[22:25], v[172:175], v[204:207], v[22:25]
	v_mfma_f32_16x16x32_bf16 v[18:21], v[180:183], v[204:207], v[18:21]
	v_mfma_f32_16x16x32_bf16 v[6:9], v[172:175], v[212:215], v[6:9]
	v_mfma_f32_16x16x32_bf16 v[2:5], v[180:183], v[212:215], v[2:5]
	v_mfma_f32_16x16x32_bf16 v[54:57], v[176:179], v[192:195], v[54:57]
	v_mfma_f32_16x16x32_bf16 v[50:53], v[184:187], v[192:195], v[50:53]
	v_mfma_f32_16x16x32_bf16 v[38:41], v[176:179], v[200:203], v[38:41]
	v_mfma_f32_16x16x32_bf16 v[34:37], v[184:187], v[200:203], v[34:37]
	v_mfma_f32_16x16x32_bf16 v[22:25], v[176:179], v[208:211], v[22:25]
	v_mfma_f32_16x16x32_bf16 v[18:21], v[184:187], v[208:211], v[18:21]
	v_mfma_f32_16x16x32_bf16 v[6:9], v[176:179], v[216:219], v[6:9]
	v_mfma_f32_16x16x32_bf16 v[2:5], v[184:187], v[216:219], v[2:5]
	s_barrier
; #define PG8_STAGE(bufoff, gbase, voff) do { _Pragma("unroll") for (int _i = 0; _i < 2; ++_i) \
;         __builtin_amdgcn_global_load_lds((const unsigned*)((const char*)(gbase) + (voff)[_i]), (LAS unsigned*)(lds + (bufoff) + ldsw + _i * 8192), 16, 0, 0); } while (0)
; #define PG8_LDA(dst, b, h) do { _Pragma("unroll") for (int m = 0; m < 4; ++m) _Pragma("unroll") for (int k = 0; k < 2; ++k) dst[m][k] = *(const LAS bf16x8*)(lds + PG8_SA(b, h) + aoff + m * 2048 + k * 1024); } while (0)
; #define PG8_LDB(dst, b, h) do { _Pragma("unroll") for (int n = 0; n < 2; ++n) _Pragma("unroll") for (int k = 0; k < 2; ++k) dst[n][k] = *(const LAS bf16x8*)(lds + PG8_SB(b, h) + boff + n * 2048 + k * 1024); } while (0)
; #define PG8_MMA(ai, bj, At, Bt) do { __builtin_amdgcn_s_setprio(1); _Pragma("unroll") for (int m = 0; m < 4; ++m) _Pragma("unroll") for (int n = 0; n < 2; ++n) _Pragma("unroll") for (int k = 0; k < 2; ++k) \
;         acc[ai][bj][m][n] = __builtin_amdgcn_mfma_f32_16x16x32_bf16(Bt[n][k], At[m][k], acc[ai][bj][m][n], 0, 0, 0); __builtin_amdgcn_s_setprio(0); } while (0)
; #define PG8_WAIT_V(n) asm volatile("s_waitcnt vmcnt(" #n ")" ::: "memory")
; #define PG8_WAIT_L(n) asm volatile("s_waitcnt lgkmcnt(" #n ")" ::: "memory")
; #define PG8_BAR __builtin_amdgcn_s_barrier()
; #define PG8_SCHED __builtin_amdgcn_sched_barrier(0)
; template <class Epi>
; __device__ __forceinline__ void gemm_phase(LAS unsigned char* lds, const Gemm g, const StaticOrder& S, const Epi& E) {
;     ...
;             PG8_LDB(B0, 1, 0); PG8_LDB(B1, 1, 1); PG8_SCHED; PG8_LDA(At, 1, 0); PG8_STAGE(PG8_SA(0, 1), a2 + hstep, voffA);
;             PG8_WAIT_V(8); PG8_WAIT_L(0); PG8_BAR; PG8_MMA(0, 0, At, B0); PG8_MMA(0, 1, At, B1); PG8_BAR; PG8_SCHED;
;             PG8_LDA(At, 1, 1); PG8_STAGE(PG8_SB(1, 0), b3, voffB); PG8_STAGE(PG8_SB(1, 1), b3 + hstep, voffB); PG8_STAGE(PG8_SA(1, 0), a3, voffA);
;             PG8_WAIT_V(8); PG8_WAIT_L(0); PG8_BAR; PG8_MMA(1, 0, At, B0); PG8_MMA(1, 1, At, B1); PG8_BAR; PG8_SCHED;
;         }
	s_setprio 0
	s_add_i32 s85, 0, 0x18000
	s_add_i32 s86, 0, 0x1c000
	v_add_u32_e32 v166, s85, v160
	v_add_u32_e32 v184, s86, v160
	ds_read_b128 v[130:133], v166
	ds_read_b128 v[134:137], v166 offset:1024
	ds_read_b128 v[154:157], v166 offset:2048
	ds_read_b128 v[166:169], v166 offset:3072
	ds_read_b128 v[172:175], v184
	ds_read_b128 v[176:179], v184 offset:1024
	ds_read_b128 v[180:183], v184 offset:2048
	ds_read_b128 v[184:187], v184 offset:3072
	s_add_u32 s50, s50, 0xb0000
	s_addc_u32 s51, s51, 0
	s_mov_b32 m0, s61
	ds_read_b128 v[188:191], v164 offset:32768
	ds_read_b128 v[192:195], v164 offset:33792
	ds_read_b128 v[196:199], v164 offset:34816
	ds_read_b128 v[200:203], v164 offset:35840
	ds_read_b128 v[204:207], v164 offset:36864
	ds_read_b128 v[208:211], v164 offset:37888
	ds_read_b128 v[212:215], v164 offset:38912
	ds_read_b128 v[216:219], v164 offset:39936
	global_load_lds_dwordx4 v138, s[50:51]
	s_mov_b32 m0, s62
	s_nop 0
	global_load_lds_dwordx4 v142, s[50:51]
	s_waitcnt vmcnt(8)
	s_waitcnt lgkmcnt(0)
	s_setprio 1
	s_barrier
	v_mfma_f32_16x16x32_bf16 v[126:129], v[130:133], v[188:191], v[126:129]
	v_mfma_f32_16x16x32_bf16 v[122:125], v[154:157], v[188:191], v[122:125]
	v_mfma_f32_16x16x32_bf16 v[110:113], v[130:133], v[196:199], v[110:113]
	v_mfma_f32_16x16x32_bf16 v[106:109], v[154:157], v[196:199], v[106:109]
	v_mfma_f32_16x16x32_bf16 v[94:97], v[130:133], v[204:207], v[94:97]
	v_mfma_f32_16x16x32_bf16 v[90:93], v[154:157], v[204:207], v[90:93]
	v_mfma_f32_16x16x32_bf16 v[78:81], v[130:133], v[212:215], v[78:81]
	v_mfma_f32_16x16x32_bf16 v[74:77], v[154:157], v[212:215], v[74:77]
	v_mfma_f32_16x16x32_bf16 v[126:129], v[134:137], v[192:195], v[126:129]
	v_mfma_f32_16x16x32_bf16 v[122:125], v[166:169], v[192:195], v[122:125]
	v_mfma_f32_16x16x32_bf16 v[110:113], v[134:137], v[200:203], v[110:113]
	v_mfma_f32_16x16x32_bf16 v[106:109], v[166:169], v[200:203], v[106:109]
	v_mfma_f32_16x16x32_bf16 v[94:97], v[134:137], v[208:211], v[94:97]
	v_mfma_f32_16x16x32_bf16 v[90:93], v[166:169], v[208:211], v[90:93]
	v_mfma_f32_16x16x32_bf16 v[78:81], v[134:137], v[216:219], v[78:81]
	v_mfma_f32_16x16x32_bf16 v[74:77], v[166:169], v[216:219], v[74:77]
	v_mfma_f32_16x16x32_bf16 v[118:121], v[172:175], v[188:191], v[118:121]
	v_mfma_f32_16x16x32_bf16 v[114:117], v[180:183], v[188:191], v[114:117]
	v_mfma_f32_16x16x32_bf16 v[102:105], v[172:175], v[196:199], v[102:105]
	v_mfma_f32_16x16x32_bf16 v[98:101], v[180:183], v[196:199], v[98:101]
	v_mfma_f32_16x16x32_bf16 v[86:89], v[172:175], v[204:207], v[86:89]
	v_mfma_f32_16x16x32_bf16 v[82:85], v[180:183], v[204:207], v[82:85]
	v_mfma_f32_16x16x32_bf16 v[70:73], v[172:175], v[212:215], v[70:73]
	v_mfma_f32_16x16x32_bf16 v[66:69], v[180:183], v[212:215], v[66:69]
	v_mfma_f32_16x16x32_bf16 v[118:121], v[176:179], v[192:195], v[118:121]
	v_mfma_f32_16x16x32_bf16 v[114:117], v[184:187], v[192:195], v[114:117]
	v_mfma_f32_16x16x32_bf16 v[102:105], v[176:179], v[200:203], v[102:105]
	v_mfma_f32_16x16x32_bf16 v[98:101], v[184:187], v[200:203], v[98:101]
	v_mfma_f32_16x16x32_bf16 v[86:89], v[176:179], v[208:211], v[86:89]
	v_mfma_f32_16x16x32_bf16 v[82:85], v[184:187], v[208:211], v[82:85]
	v_mfma_f32_16x16x32_bf16 v[70:73], v[176:179], v[216:219], v[70:73]
	v_mfma_f32_16x16x32_bf16 v[66:69], v[184:187], v[216:219], v[66:69]
	s_barrier
	s_setprio 0
	s_add_i32 s50, s85, s58
	s_mov_b32 m0, s50
	ds_read_b128 v[188:191], v164 offset:49152
	ds_read_b128 v[192:195], v164 offset:50176
	ds_read_b128 v[196:199], v164 offset:51200
	ds_read_b128 v[200:203], v164 offset:52224
	ds_read_b128 v[204:207], v164 offset:53248
	ds_read_b128 v[208:211], v164 offset:54272
	ds_read_b128 v[212:215], v164 offset:55296
	ds_read_b128 v[216:219], v164 offset:56320
	global_load_lds_dwordx4 v140, s[98:99]
	s_add_i32 m0, s50, 0x2000
	s_add_u32 s48, s48, 0xb0080
	s_addc_u32 s49, s49, 0
	s_add_i32 s50, s86, s58
	global_load_lds_dwordx4 v144, s[98:99]
	s_mov_b32 m0, s50
	s_nop 0
	global_load_lds_dwordx4 v140, s[48:49]
	s_add_i32 m0, s50, 0x2000
	s_nop 0
	global_load_lds_dwordx4 v144, s[48:49]
	s_mov_b32 m0, s64
	s_nop 0
	global_load_lds_dwordx4 v138, s[100:101]
	s_mov_b32 m0, s65
	s_nop 0
	global_load_lds_dwordx4 v142, s[100:101]
	s_waitcnt vmcnt(8)
	s_waitcnt lgkmcnt(0)
	s_setprio 1
	s_barrier
	v_mfma_f32_16x16x32_bf16 v[62:65], v[130:133], v[188:191], v[62:65]
	v_mfma_f32_16x16x32_bf16 v[58:61], v[154:157], v[188:191], v[58:61]
	v_mfma_f32_16x16x32_bf16 v[46:49], v[130:133], v[196:199], v[46:49]
	v_mfma_f32_16x16x32_bf16 v[42:45], v[154:157], v[196:199], v[42:45]
	v_mfma_f32_16x16x32_bf16 v[30:33], v[130:133], v[204:207], v[30:33]
	v_mfma_f32_16x16x32_bf16 v[26:29], v[154:157], v[204:207], v[26:29]
	v_mfma_f32_16x16x32_bf16 v[14:17], v[130:133], v[212:215], v[14:17]
	v_mfma_f32_16x16x32_bf16 v[10:13], v[154:157], v[212:215], v[10:13]
	v_mfma_f32_16x16x32_bf16 v[62:65], v[134:137], v[192:195], v[62:65]
	v_mfma_f32_16x16x32_bf16 v[58:61], v[166:169], v[192:195], v[58:61]
	v_mfma_f32_16x16x32_bf16 v[46:49], v[134:137], v[200:203], v[46:49]
	v_mfma_f32_16x16x32_bf16 v[42:45], v[166:169], v[200:203], v[42:45]
	v_mfma_f32_16x16x32_bf16 v[30:33], v[134:137], v[208:211], v[30:33]
	v_mfma_f32_16x16x32_bf16 v[26:29], v[166:169], v[208:211], v[26:29]
	v_mfma_f32_16x16x32_bf16 v[14:17], v[134:137], v[216:219], v[14:17]
	v_mfma_f32_16x16x32_bf16 v[10:13], v[166:169], v[216:219], v[10:13]
	v_mfma_f32_16x16x32_bf16 v[54:57], v[172:175], v[188:191], v[54:57]
	v_mfma_f32_16x16x32_bf16 v[50:53], v[180:183], v[188:191], v[50:53]
	v_mfma_f32_16x16x32_bf16 v[38:41], v[172:175], v[196:199], v[38:41]
	v_mfma_f32_16x16x32_bf16 v[34:37], v[180:183], v[196:199], v[34:37]
	v_mfma_f32_16x16x32_bf16 v[22:25], v[172:175], v[204:207], v[22:25]
	v_mfma_f32_16x16x32_bf16 v[18:21], v[180:183], v[204:207], v[18:21]
	v_mfma_f32_16x16x32_bf16 v[6:9], v[172:175], v[212:215], v[6:9]
	v_mfma_f32_16x16x32_bf16 v[2:5], v[180:183], v[212:215], v[2:5]
	v_mfma_f32_16x16x32_bf16 v[54:57], v[176:179], v[192:195], v[54:57]
	v_mfma_f32_16x16x32_bf16 v[50:53], v[184:187], v[192:195], v[50:53]
	v_mfma_f32_16x16x32_bf16 v[38:41], v[176:179], v[200:203], v[38:41]
	v_mfma_f32_16x16x32_bf16 v[34:37], v[184:187], v[200:203], v[34:37]
	v_mfma_f32_16x16x32_bf16 v[22:25], v[176:179], v[208:211], v[22:25]
	v_mfma_f32_16x16x32_bf16 v[18:21], v[184:187], v[208:211], v[18:21]
	v_mfma_f32_16x16x32_bf16 v[6:9], v[176:179], v[216:219], v[6:9]
	v_mfma_f32_16x16x32_bf16 v[2:5], v[184:187], v[216:219], v[2:5]
	s_barrier
	s_setprio 0
	s_add_i32 s84, s84, 2
	s_add_u32 s46, s46, 0x100
	s_addc_u32 s47, s47, 0
	s_add_u32 s82, s82, 0x100
	s_addc_u32 s83, s83, 0
	s_cmp_gt_u32 s84, 41
	s_cbranch_scc0 .LBB0_221
	s_and_b64 vcc, exec, s[42:43]
	s_cbranch_vccz .LBB0_224
	s_barrier

; #define PG8_STAGE(bufoff, gbase, voff) do { _Pragma("unroll") for (int _i = 0; _i < 2; ++_i) \
;         __builtin_amdgcn_global_load_lds((const unsigned*)((const char*)(gbase) + (voff)[_i]), (LAS unsigned*)(lds + (bufoff) + ldsw + _i * 8192), 16, 0, 0); } while (0)
; #define PG8_LDA(dst, b, h) do { _Pragma("unroll") for (int m = 0; m < 4; ++m) _Pragma("unroll") for (int k = 0; k < 2; ++k) dst[m][k] = *(const LAS bf16x8*)(lds + PG8_SA(b, h) + aoff + m * 2048 + k * 1024); } while (0)
; #define PG8_LDB(dst, b, h) do { _Pragma("unroll") for (int n = 0; n < 2; ++n) _Pragma("unroll") for (int k = 0; k < 2; ++k) dst[n][k] = *(const LAS bf16x8*)(lds + PG8_SB(b, h) + boff + n * 2048 + k * 1024); } while (0)
; #define PG8_MMA(ai, bj, At, Bt) do { __builtin_amdgcn_s_setprio(1); _Pragma("unroll") for (int m = 0; m < 4; ++m) _Pragma("unroll") for (int n = 0; n < 2; ++n) _Pragma("unroll") for (int k = 0; k < 2; ++k) \
;         acc[ai][bj][m][n] = __builtin_amdgcn_mfma_f32_16x16x32_bf16(Bt[n][k], At[m][k], acc[ai][bj][m][n], 0, 0, 0); __builtin_amdgcn_s_setprio(0); } while (0)
; #define PG8_WAIT_V(n) asm volatile("s_waitcnt vmcnt(" #n ")" ::: "memory")
; #define PG8_WAIT_L(n) asm volatile("s_waitcnt lgkmcnt(" #n ")" ::: "memory")
; #define PG8_BAR __builtin_amdgcn_s_barrier()
; #define PG8_SCHED __builtin_amdgcn_sched_barrier(0)
; template <class Epi>
; __device__ __forceinline__ void gemm_phase(LAS unsigned char* lds, const Gemm g, const StaticOrder& S, const Epi& E) {
;     ...
;             PG8_LDB(B0, 0, 0); PG8_LDB(B1, 0, 1); PG8_SCHED; PG8_LDA(At, 0, 0); PG8_STAGE(PG8_SA(1, 1), a1 + hstep, voffA);
;             PG8_WAIT_V(8); PG8_WAIT_L(0); PG8_BAR; PG8_MMA(0, 0, At, B0); PG8_MMA(0, 1, At, B1); PG8_BAR; PG8_SCHED;
;             PG8_LDA(At, 0, 1); PG8_STAGE(PG8_SB(0, 0), b2, voffB); PG8_STAGE(PG8_SB(0, 1), b2 + hstep, voffB); PG8_STAGE(PG8_SA(0, 0), a2, voffA);
;             PG8_WAIT_V(8); PG8_WAIT_L(0); PG8_BAR; PG8_MMA(1, 0, At, B0); PG8_MMA(1, 1, At, B1); PG8_BAR; PG8_SCHED;
.LBB0_322:
	ds_read_b128 v[130:133], v191
	ds_read_b128 v[134:137], v191 offset:1024
	ds_read_b128 v[138:141], v191 offset:2048
	ds_read_b128 v[142:145], v191 offset:3072
	ds_read_b128 v[166:169], v193
	ds_read_b128 v[172:175], v193 offset:1024
	ds_read_b128 v[176:179], v193 offset:2048
	ds_read_b128 v[180:183], v193 offset:3072
	s_add_u32 s76, s88, 0xfffc0080
	s_addc_u32 s77, s89, -1
	s_cmp_eq_u32 vcc_hi, 12
	s_cselect_b32 s93, s1, s77
	s_cselect_b32 s92, s7, s76
	s_cselect_b32 s91, s9, vcc_lo
	s_cselect_b32 s90, s46, s81
	s_add_i32 m0, s96, 0xc000
	ds_read_b128 v[200:203], v194
	ds_read_b128 v[204:207], v194 offset:1024
	ds_read_b128 v[208:211], v194 offset:2048
	ds_read_b128 v[212:215], v194 offset:3072
	ds_read_b128 v[216:219], v194 offset:4096
	ds_read_b128 v[220:223], v194 offset:5120
	ds_read_b128 v[224:227], v194 offset:6144
	ds_read_b128 v[228:231], v194 offset:7168
	global_load_lds_dwordx4 v158, s[88:89]
	s_add_i32 m0, s96, 0xe000
	s_nop 0
	global_load_lds_dwordx4 v160, s[88:89]
	s_waitcnt vmcnt(8)
	s_waitcnt lgkmcnt(0)
	s_setprio 1
	s_barrier
	v_mfma_f32_16x16x32_bf16 v[126:129], v[130:133], v[200:203], v[126:129]
	v_mfma_f32_16x16x32_bf16 v[122:125], v[138:141], v[200:203], v[122:125]
	v_mfma_f32_16x16x32_bf16 v[110:113], v[130:133], v[208:211], v[110:113]
	v_mfma_f32_16x16x32_bf16 v[106:109], v[138:141], v[208:211], v[106:109]
	v_mfma_f32_16x16x32_bf16 v[94:97], v[130:133], v[216:219], v[94:97]
	v_mfma_f32_16x16x32_bf16 v[90:93], v[138:141], v[216:219], v[90:93]
	v_mfma_f32_16x16x32_bf16 v[78:81], v[130:133], v[224:227], v[78:81]
	v_mfma_f32_16x16x32_bf16 v[74:77], v[138:141], v[224:227], v[74:77]
	v_mfma_f32_16x16x32_bf16 v[126:129], v[134:137], v[204:207], v[126:129]
	v_mfma_f32_16x16x32_bf16 v[122:125], v[142:145], v[204:207], v[122:125]
	v_mfma_f32_16x16x32_bf16 v[110:113], v[134:137], v[212:215], v[110:113]
	v_mfma_f32_16x16x32_bf16 v[106:109], v[142:145], v[212:215], v[106:109]
	v_mfma_f32_16x16x32_bf16 v[94:97], v[134:137], v[220:223], v[94:97]
	v_mfma_f32_16x16x32_bf16 v[90:93], v[142:145], v[220:223], v[90:93]
	v_mfma_f32_16x16x32_bf16 v[78:81], v[134:137], v[228:231], v[78:81]
	v_mfma_f32_16x16x32_bf16 v[74:77], v[142:145], v[228:231], v[74:77]
	v_mfma_f32_16x16x32_bf16 v[118:121], v[166:169], v[200:203], v[118:121]
	v_mfma_f32_16x16x32_bf16 v[114:117], v[176:179], v[200:203], v[114:117]
	v_mfma_f32_16x16x32_bf16 v[102:105], v[166:169], v[208:211], v[102:105]
	v_mfma_f32_16x16x32_bf16 v[98:101], v[176:179], v[208:211], v[98:101]
	v_mfma_f32_16x16x32_bf16 v[86:89], v[166:169], v[216:219], v[86:89]
	v_mfma_f32_16x16x32_bf16 v[82:85], v[176:179], v[216:219], v[82:85]
	v_mfma_f32_16x16x32_bf16 v[70:73], v[166:169], v[224:227], v[70:73]
	v_mfma_f32_16x16x32_bf16 v[66:69], v[176:179], v[224:227], v[66:69]
	v_mfma_f32_16x16x32_bf16 v[118:121], v[172:175], v[204:207], v[118:121]
	v_mfma_f32_16x16x32_bf16 v[114:117], v[180:183], v[204:207], v[114:117]
	v_mfma_f32_16x16x32_bf16 v[102:105], v[172:175], v[212:215], v[102:105]
	v_mfma_f32_16x16x32_bf16 v[98:101], v[180:183], v[212:215], v[98:101]
	v_mfma_f32_16x16x32_bf16 v[86:89], v[172:175], v[220:223], v[86:89]
	v_mfma_f32_16x16x32_bf16 v[82:85], v[180:183], v[220:223], v[82:85]
	v_mfma_f32_16x16x32_bf16 v[70:73], v[172:175], v[228:231], v[70:73]
	v_mfma_f32_16x16x32_bf16 v[66:69], v[180:183], v[228:231], v[66:69]
	s_barrier
	s_setprio 0
	s_add_u32 s98, s90, s50
	s_addc_u32 s99, s91, s51
	s_add_u32 s100, s92, s50
	s_addc_u32 s101, s93, s51
	s_add_i32 s76, s42, s44
	s_mov_b32 m0, s76
	ds_read_b128 v[200:203], v194 offset:16384
	ds_read_b128 v[204:207], v194 offset:17408
	ds_read_b128 v[208:211], v194 offset:18432
	ds_read_b128 v[212:215], v194 offset:19456
	ds_read_b128 v[216:219], v194 offset:20480
	ds_read_b128 v[220:223], v194 offset:21504
	ds_read_b128 v[224:227], v194 offset:22528
	ds_read_b128 v[228:231], v194 offset:23552
	global_load_lds_dwordx4 v148, s[90:91]
	s_add_i32 m0, s76, 0x2000
	s_add_u32 s76, s90, 0x40000
	s_addc_u32 s77, s91, 0
	s_add_i32 s60, s43, s44
	global_load_lds_dwordx4 v152, s[90:91]
	s_mov_b32 m0, s60
	s_nop 0
	global_load_lds_dwordx4 v148, s[76:77]
	s_add_i32 m0, s60, 0x2000
	s_nop 0
	global_load_lds_dwordx4 v152, s[76:77]
	s_mov_b32 m0, s96
	s_nop 0
	global_load_lds_dwordx4 v146, s[92:93]
	s_mov_b32 m0, s97
	s_nop 0
	global_load_lds_dwordx4 v150, s[92:93]
	s_waitcnt vmcnt(8)
	s_waitcnt lgkmcnt(0)
	s_setprio 1
	s_barrier
	v_mfma_f32_16x16x32_bf16 v[62:65], v[130:133], v[200:203], v[62:65]
	v_mfma_f32_16x16x32_bf16 v[58:61], v[138:141], v[200:203], v[58:61]
	v_mfma_f32_16x16x32_bf16 v[46:49], v[130:133], v[208:211], v[46:49]
	v_mfma_f32_16x16x32_bf16 v[42:45], v[138:141], v[208:211], v[42:45]
	v_mfma_f32_16x16x32_bf16 v[30:33], v[130:133], v[216:219], v[30:33]
	v_mfma_f32_16x16x32_bf16 v[26:29], v[138:141], v[216:219], v[26:29]
	v_mfma_f32_16x16x32_bf16 v[14:17], v[130:133], v[224:227], v[14:17]
	v_mfma_f32_16x16x32_bf16 v[10:13], v[138:141], v[224:227], v[10:13]
	v_mfma_f32_16x16x32_bf16 v[62:65], v[134:137], v[204:207], v[62:65]
	v_mfma_f32_16x16x32_bf16 v[58:61], v[142:145], v[204:207], v[58:61]
	v_mfma_f32_16x16x32_bf16 v[46:49], v[134:137], v[212:215], v[46:49]
	v_mfma_f32_16x16x32_bf16 v[42:45], v[142:145], v[212:215], v[42:45]
	v_mfma_f32_16x16x32_bf16 v[30:33], v[134:137], v[220:223], v[30:33]
	v_mfma_f32_16x16x32_bf16 v[26:29], v[142:145], v[220:223], v[26:29]
	v_mfma_f32_16x16x32_bf16 v[14:17], v[134:137], v[228:231], v[14:17]
	v_mfma_f32_16x16x32_bf16 v[10:13], v[142:145], v[228:231], v[10:13]
	v_mfma_f32_16x16x32_bf16 v[54:57], v[166:169], v[200:203], v[54:57]
	v_mfma_f32_16x16x32_bf16 v[50:53], v[176:179], v[200:203], v[50:53]
	v_mfma_f32_16x16x32_bf16 v[38:41], v[166:169], v[208:211], v[38:41]
	v_mfma_f32_16x16x32_bf16 v[34:37], v[176:179], v[208:211], v[34:37]
	v_mfma_f32_16x16x32_bf16 v[22:25], v[166:169], v[216:219], v[22:25]
	v_mfma_f32_16x16x32_bf16 v[18:21], v[176:179], v[216:219], v[18:21]
	v_mfma_f32_16x16x32_bf16 v[6:9], v[166:169], v[224:227], v[6:9]
	v_mfma_f32_16x16x32_bf16 v[2:5], v[176:179], v[224:227], v[2:5]
	v_mfma_f32_16x16x32_bf16 v[54:57], v[172:175], v[204:207], v[54:57]
	v_mfma_f32_16x16x32_bf16 v[50:53], v[180:183], v[204:207], v[50:53]
	v_mfma_f32_16x16x32_bf16 v[38:41], v[172:175], v[212:215], v[38:41]
	v_mfma_f32_16x16x32_bf16 v[34:37], v[180:183], v[212:215], v[34:37]
	v_mfma_f32_16x16x32_bf16 v[22:25], v[172:175], v[220:223], v[22:25]
	v_mfma_f32_16x16x32_bf16 v[18:21], v[180:183], v[220:223], v[18:21]
	v_mfma_f32_16x16x32_bf16 v[6:9], v[172:175], v[228:231], v[6:9]
	v_mfma_f32_16x16x32_bf16 v[2:5], v[180:183], v[228:231], v[2:5]
	s_barrier
; #define PG8_STAGE(bufoff, gbase, voff) do { _Pragma("unroll") for (int _i = 0; _i < 2; ++_i) \
;         __builtin_amdgcn_global_load_lds((const unsigned*)((const char*)(gbase) + (voff)[_i]), (LAS unsigned*)(lds + (bufoff) + ldsw + _i * 8192), 16, 0, 0); } while (0)
; #define PG8_LDA(dst, b, h) do { _Pragma("unroll") for (int m = 0; m < 4; ++m) _Pragma("unroll") for (int k = 0; k < 2; ++k) dst[m][k] = *(const LAS bf16x8*)(lds + PG8_SA(b, h) + aoff + m * 2048 + k * 1024); } while (0)
; #define PG8_LDB(dst, b, h) do { _Pragma("unroll") for (int n = 0; n < 2; ++n) _Pragma("unroll") for (int k = 0; k < 2; ++k) dst[n][k] = *(const LAS bf16x8*)(lds + PG8_SB(b, h) + boff + n * 2048 + k * 1024); } while (0)
; #define PG8_MMA(ai, bj, At, Bt) do { __builtin_amdgcn_s_setprio(1); _Pragma("unroll") for (int m = 0; m < 4; ++m) _Pragma("unroll") for (int n = 0; n < 2; ++n) _Pragma("unroll") for (int k = 0; k < 2; ++k) \
;         acc[ai][bj][m][n] = __builtin_amdgcn_mfma_f32_16x16x32_bf16(Bt[n][k], At[m][k], acc[ai][bj][m][n], 0, 0, 0); __builtin_amdgcn_s_setprio(0); } while (0)
; #define PG8_WAIT_V(n) asm volatile("s_waitcnt vmcnt(" #n ")" ::: "memory")
; #define PG8_WAIT_L(n) asm volatile("s_waitcnt lgkmcnt(" #n ")" ::: "memory")
; #define PG8_BAR __builtin_amdgcn_s_barrier()
; #define PG8_SCHED __builtin_amdgcn_sched_barrier(0)
; template <class Epi>
; __device__ __forceinline__ void gemm_phase(LAS unsigned char* lds, const Gemm g, const StaticOrder& S, const Epi& E) {
;     ...
;             PG8_LDB(B0, 1, 0); PG8_LDB(B1, 1, 1); PG8_SCHED; PG8_LDA(At, 1, 0); PG8_STAGE(PG8_SA(0, 1), a2 + hstep, voffA);
;             PG8_WAIT_V(8); PG8_WAIT_L(0); PG8_BAR; PG8_MMA(0, 0, At, B0); PG8_MMA(0, 1, At, B1); PG8_BAR; PG8_SCHED;
;             PG8_LDA(At, 1, 1); PG8_STAGE(PG8_SB(1, 0), b3, voffB); PG8_STAGE(PG8_SB(1, 1), b3 + hstep, voffB); PG8_STAGE(PG8_SA(1, 0), a3, voffA);
;             PG8_WAIT_V(8); PG8_WAIT_L(0); PG8_BAR; PG8_MMA(1, 0, At, B0); PG8_MMA(1, 1, At, B1); PG8_BAR; PG8_SCHED;
;         }
	s_setprio 0
	s_add_i32 s60, 0, 0x18000
	s_add_i32 s61, 0, 0x1c000
	v_add_u32_e32 v142, s60, v187
	v_add_u32_e32 v180, s61, v187
	ds_read_b128 v[130:133], v142
	ds_read_b128 v[134:137], v142 offset:1024
	ds_read_b128 v[138:141], v142 offset:2048
	ds_read_b128 v[142:145], v142 offset:3072
	ds_read_b128 v[166:169], v180
	ds_read_b128 v[172:175], v180 offset:1024
	ds_read_b128 v[176:179], v180 offset:2048
	ds_read_b128 v[180:183], v180 offset:3072
	s_add_u32 s76, s92, 0x40000
	s_addc_u32 s77, s93, 0
	s_mov_b32 m0, s11
	ds_read_b128 v[200:203], v194 offset:32768
	ds_read_b128 v[204:207], v194 offset:33792
	ds_read_b128 v[208:211], v194 offset:34816
	ds_read_b128 v[212:215], v194 offset:35840
	ds_read_b128 v[216:219], v194 offset:36864
	ds_read_b128 v[220:223], v194 offset:37888
	ds_read_b128 v[224:227], v194 offset:38912
	ds_read_b128 v[228:231], v194 offset:39936
	global_load_lds_dwordx4 v146, s[76:77]
	s_mov_b32 m0, s94
	s_nop 0
	global_load_lds_dwordx4 v150, s[76:77]
	s_waitcnt vmcnt(8)
	s_waitcnt lgkmcnt(0)
	s_setprio 1
	s_barrier
	v_mfma_f32_16x16x32_bf16 v[126:129], v[130:133], v[200:203], v[126:129]
	v_mfma_f32_16x16x32_bf16 v[122:125], v[138:141], v[200:203], v[122:125]
	v_mfma_f32_16x16x32_bf16 v[110:113], v[130:133], v[208:211], v[110:113]
	v_mfma_f32_16x16x32_bf16 v[106:109], v[138:141], v[208:211], v[106:109]
	v_mfma_f32_16x16x32_bf16 v[94:97], v[130:133], v[216:219], v[94:97]
	v_mfma_f32_16x16x32_bf16 v[90:93], v[138:141], v[216:219], v[90:93]
	v_mfma_f32_16x16x32_bf16 v[78:81], v[130:133], v[224:227], v[78:81]
	v_mfma_f32_16x16x32_bf16 v[74:77], v[138:141], v[224:227], v[74:77]
	v_mfma_f32_16x16x32_bf16 v[126:129], v[134:137], v[204:207], v[126:129]
	v_mfma_f32_16x16x32_bf16 v[122:125], v[142:145], v[204:207], v[122:125]
	v_mfma_f32_16x16x32_bf16 v[110:113], v[134:137], v[212:215], v[110:113]
	v_mfma_f32_16x16x32_bf16 v[106:109], v[142:145], v[212:215], v[106:109]
	v_mfma_f32_16x16x32_bf16 v[94:97], v[134:137], v[220:223], v[94:97]
	v_mfma_f32_16x16x32_bf16 v[90:93], v[142:145], v[220:223], v[90:93]
	v_mfma_f32_16x16x32_bf16 v[78:81], v[134:137], v[228:231], v[78:81]
	v_mfma_f32_16x16x32_bf16 v[74:77], v[142:145], v[228:231], v[74:77]
	v_mfma_f32_16x16x32_bf16 v[118:121], v[166:169], v[200:203], v[118:121]
	v_mfma_f32_16x16x32_bf16 v[114:117], v[176:179], v[200:203], v[114:117]
	v_mfma_f32_16x16x32_bf16 v[102:105], v[166:169], v[208:211], v[102:105]
	v_mfma_f32_16x16x32_bf16 v[98:101], v[176:179], v[208:211], v[98:101]
	v_mfma_f32_16x16x32_bf16 v[86:89], v[166:169], v[216:219], v[86:89]
	v_mfma_f32_16x16x32_bf16 v[82:85], v[176:179], v[216:219], v[82:85]
	v_mfma_f32_16x16x32_bf16 v[70:73], v[166:169], v[224:227], v[70:73]
	v_mfma_f32_16x16x32_bf16 v[66:69], v[176:179], v[224:227], v[66:69]
	v_mfma_f32_16x16x32_bf16 v[118:121], v[172:175], v[204:207], v[118:121]
	v_mfma_f32_16x16x32_bf16 v[114:117], v[180:183], v[204:207], v[114:117]
	v_mfma_f32_16x16x32_bf16 v[102:105], v[172:175], v[212:215], v[102:105]
	v_mfma_f32_16x16x32_bf16 v[98:101], v[180:183], v[212:215], v[98:101]
	v_mfma_f32_16x16x32_bf16 v[86:89], v[172:175], v[220:223], v[86:89]
	v_mfma_f32_16x16x32_bf16 v[82:85], v[180:183], v[220:223], v[82:85]
	v_mfma_f32_16x16x32_bf16 v[70:73], v[172:175], v[228:231], v[70:73]
	v_mfma_f32_16x16x32_bf16 v[66:69], v[180:183], v[228:231], v[66:69]
	s_barrier
	s_setprio 0
	s_add_i32 s60, s60, s44
	s_mov_b32 m0, s60
	ds_read_b128 v[200:203], v194 offset:49152
	ds_read_b128 v[204:207], v194 offset:50176
	ds_read_b128 v[208:211], v194 offset:51200
	ds_read_b128 v[212:215], v194 offset:52224
	ds_read_b128 v[216:219], v194 offset:53248
	ds_read_b128 v[220:223], v194 offset:54272
	ds_read_b128 v[224:227], v194 offset:55296
	ds_read_b128 v[228:231], v194 offset:56320
	global_load_lds_dwordx4 v148, s[98:99]
	s_add_i32 m0, s60, 0x2000
	s_add_u32 s76, s90, 0x40080
	s_addc_u32 s77, s91, 0
	s_add_i32 s60, s61, s44
	global_load_lds_dwordx4 v152, s[98:99]
	s_mov_b32 m0, s60
	s_nop 0
	global_load_lds_dwordx4 v148, s[76:77]
	s_add_i32 m0, s60, 0x2000
	s_nop 0
	global_load_lds_dwordx4 v152, s[76:77]
	s_mov_b32 m0, s79
	s_nop 0
	global_load_lds_dwordx4 v146, s[100:101]
	s_mov_b32 m0, s33
	s_nop 0
	global_load_lds_dwordx4 v150, s[100:101]
	s_waitcnt vmcnt(8)
	s_waitcnt lgkmcnt(0)
	s_setprio 1
	s_barrier
	v_mfma_f32_16x16x32_bf16 v[62:65], v[130:133], v[200:203], v[62:65]
	v_mfma_f32_16x16x32_bf16 v[58:61], v[138:141], v[200:203], v[58:61]
	v_mfma_f32_16x16x32_bf16 v[46:49], v[130:133], v[208:211], v[46:49]
	v_mfma_f32_16x16x32_bf16 v[42:45], v[138:141], v[208:211], v[42:45]
	v_mfma_f32_16x16x32_bf16 v[30:33], v[130:133], v[216:219], v[30:33]
	v_mfma_f32_16x16x32_bf16 v[26:29], v[138:141], v[216:219], v[26:29]
	v_mfma_f32_16x16x32_bf16 v[14:17], v[130:133], v[224:227], v[14:17]
	v_mfma_f32_16x16x32_bf16 v[10:13], v[138:141], v[224:227], v[10:13]
	v_mfma_f32_16x16x32_bf16 v[62:65], v[134:137], v[204:207], v[62:65]
	v_mfma_f32_16x16x32_bf16 v[58:61], v[142:145], v[204:207], v[58:61]
	v_mfma_f32_16x16x32_bf16 v[46:49], v[134:137], v[212:215], v[46:49]
	v_mfma_f32_16x16x32_bf16 v[42:45], v[142:145], v[212:215], v[42:45]
	v_mfma_f32_16x16x32_bf16 v[30:33], v[134:137], v[220:223], v[30:33]
	v_mfma_f32_16x16x32_bf16 v[26:29], v[142:145], v[220:223], v[26:29]
	v_mfma_f32_16x16x32_bf16 v[14:17], v[134:137], v[228:231], v[14:17]
	v_mfma_f32_16x16x32_bf16 v[10:13], v[142:145], v[228:231], v[10:13]
	v_mfma_f32_16x16x32_bf16 v[54:57], v[166:169], v[200:203], v[54:57]
	v_mfma_f32_16x16x32_bf16 v[50:53], v[176:179], v[200:203], v[50:53]
	v_mfma_f32_16x16x32_bf16 v[38:41], v[166:169], v[208:211], v[38:41]
	v_mfma_f32_16x16x32_bf16 v[34:37], v[176:179], v[208:211], v[34:37]
	v_mfma_f32_16x16x32_bf16 v[22:25], v[166:169], v[216:219], v[22:25]
	v_mfma_f32_16x16x32_bf16 v[18:21], v[176:179], v[216:219], v[18:21]
	v_mfma_f32_16x16x32_bf16 v[6:9], v[166:169], v[224:227], v[6:9]
	v_mfma_f32_16x16x32_bf16 v[2:5], v[176:179], v[224:227], v[2:5]
	v_mfma_f32_16x16x32_bf16 v[54:57], v[172:175], v[204:207], v[54:57]
	v_mfma_f32_16x16x32_bf16 v[50:53], v[180:183], v[204:207], v[50:53]
	v_mfma_f32_16x16x32_bf16 v[38:41], v[172:175], v[212:215], v[38:41]
	v_mfma_f32_16x16x32_bf16 v[34:37], v[180:183], v[212:215], v[34:37]
	v_mfma_f32_16x16x32_bf16 v[22:25], v[172:175], v[220:223], v[22:25]
	v_mfma_f32_16x16x32_bf16 v[18:21], v[180:183], v[220:223], v[18:21]
	v_mfma_f32_16x16x32_bf16 v[6:9], v[172:175], v[228:231], v[6:9]
	v_mfma_f32_16x16x32_bf16 v[2:5], v[180:183], v[228:231], v[2:5]
	s_barrier
	s_setprio 0
	s_add_i32 vcc_hi, vcc_hi, 2
	s_add_u32 s88, s88, 0x100
	s_addc_u32 s89, s89, 0
	s_add_u32 s81, s81, 0x100
	s_addc_u32 vcc_lo, vcc_lo, 0
	s_cmp_gt_u32 vcc_hi, 13
	s_cbranch_scc0 .LBB0_322
	s_and_b64 vcc, exec, s[58:59]
	s_cbranch_vccz .LBB0_325
	s_barrier

; #define PG8_STAGE(bufoff, gbase, voff) do { _Pragma("unroll") for (int _i = 0; _i < 2; ++_i) \
;         __builtin_amdgcn_global_load_lds((const unsigned*)((const char*)(gbase) + (voff)[_i]), (LAS unsigned*)(lds + (bufoff) + ldsw + _i * 8192), 16, 0, 0); } while (0)
; #define PG8_LDA(dst, b, h) do { _Pragma("unroll") for (int m = 0; m < 4; ++m) _Pragma("unroll") for (int k = 0; k < 2; ++k) dst[m][k] = *(const LAS bf16x8*)(lds + PG8_SA(b, h) + aoff + m * 2048 + k * 1024); } while (0)
; #define PG8_LDB(dst, b, h) do { _Pragma("unroll") for (int n = 0; n < 2; ++n) _Pragma("unroll") for (int k = 0; k < 2; ++k) dst[n][k] = *(const LAS bf16x8*)(lds + PG8_SB(b, h) + boff + n * 2048 + k * 1024); } while (0)
; #define PG8_MMA(ai, bj, At, Bt) do { __builtin_amdgcn_s_setprio(1); _Pragma("unroll") for (int m = 0; m < 4; ++m) _Pragma("unroll") for (int n = 0; n < 2; ++n) _Pragma("unroll") for (int k = 0; k < 2; ++k) \
;         acc[ai][bj][m][n] = __builtin_amdgcn_mfma_f32_16x16x32_bf16(Bt[n][k], At[m][k], acc[ai][bj][m][n], 0, 0, 0); __builtin_amdgcn_s_setprio(0); } while (0)
; #define PG8_WAIT_V(n) asm volatile("s_waitcnt vmcnt(" #n ")" ::: "memory")
; #define PG8_WAIT_L(n) asm volatile("s_waitcnt lgkmcnt(" #n ")" ::: "memory")
; #define PG8_BAR __builtin_amdgcn_s_barrier()
; #define PG8_SCHED __builtin_amdgcn_sched_barrier(0)
; template <class Epi>
; __device__ __forceinline__ void gemm_phase(LAS unsigned char* lds, const Gemm g, const StaticOrder& S, const Epi& E) {
;     ...
;             PG8_LDB(B0, 0, 0); PG8_LDB(B1, 0, 1); PG8_SCHED; PG8_LDA(At, 0, 0); PG8_STAGE(PG8_SA(1, 1), a1 + hstep, voffA);
;             PG8_WAIT_V(8); PG8_WAIT_L(0); PG8_BAR; PG8_MMA(0, 0, At, B0); PG8_MMA(0, 1, At, B1); PG8_BAR; PG8_SCHED;
;             PG8_LDA(At, 0, 1); PG8_STAGE(PG8_SB(0, 0), b2, voffB); PG8_STAGE(PG8_SB(0, 1), b2 + hstep, voffB); PG8_STAGE(PG8_SA(0, 0), a2, voffA);
;             PG8_WAIT_V(8); PG8_WAIT_L(0); PG8_BAR; PG8_MMA(1, 0, At, B0); PG8_MMA(1, 1, At, B1); PG8_BAR; PG8_SCHED;
.LBB0_619:
	ds_read_b128 v[152:155], v174
	ds_read_b128 v[156:159], v174 offset:1024
	ds_read_b128 v[160:163], v174 offset:2048
	ds_read_b128 v[164:167], v174 offset:3072
	ds_read_b128 v[180:183], v175
	ds_read_b128 v[184:187], v175 offset:1024
	ds_read_b128 v[188:191], v175 offset:2048
	ds_read_b128 v[192:195], v175 offset:3072
	s_add_u32 s46, s44, 0xfffc0080
	s_addc_u32 s47, s45, -1
	s_cmp_eq_u32 s69, 12
	s_cselect_b32 s49, s64, s47
	s_cselect_b32 s48, s65, s46
	s_cselect_b32 s47, s25, s68
	s_cselect_b32 s46, s66, s67
	s_add_i32 m0, s43, 0xc000
	ds_read_b128 v[196:199], v176
	ds_read_b128 v[200:203], v176 offset:1024
	ds_read_b128 v[204:207], v176 offset:2048
	ds_read_b128 v[208:211], v176 offset:3072
	ds_read_b128 v[212:215], v176 offset:4096
	ds_read_b128 v[216:219], v176 offset:5120
	ds_read_b128 v[220:223], v176 offset:6144
	ds_read_b128 v[224:227], v176 offset:7168
	global_load_lds_dwordx4 v144, s[44:45]
	s_add_i32 m0, s43, 0xe000
	s_nop 0
	global_load_lds_dwordx4 v146, s[44:45]
	s_waitcnt vmcnt(8)
	s_waitcnt lgkmcnt(0)
	s_setprio 1
	s_barrier
	v_mfma_f32_16x16x32_bf16 v[126:129], v[152:155], v[196:199], v[126:129]
	v_mfma_f32_16x16x32_bf16 v[122:125], v[160:163], v[196:199], v[122:125]
	v_mfma_f32_16x16x32_bf16 v[110:113], v[152:155], v[204:207], v[110:113]
	v_mfma_f32_16x16x32_bf16 v[106:109], v[160:163], v[204:207], v[106:109]
	v_mfma_f32_16x16x32_bf16 v[94:97], v[152:155], v[212:215], v[94:97]
	v_mfma_f32_16x16x32_bf16 v[90:93], v[160:163], v[212:215], v[90:93]
	v_mfma_f32_16x16x32_bf16 v[78:81], v[152:155], v[220:223], v[78:81]
	v_mfma_f32_16x16x32_bf16 v[74:77], v[160:163], v[220:223], v[74:77]
	v_mfma_f32_16x16x32_bf16 v[126:129], v[156:159], v[200:203], v[126:129]
	v_mfma_f32_16x16x32_bf16 v[122:125], v[164:167], v[200:203], v[122:125]
	v_mfma_f32_16x16x32_bf16 v[110:113], v[156:159], v[208:211], v[110:113]
	v_mfma_f32_16x16x32_bf16 v[106:109], v[164:167], v[208:211], v[106:109]
	v_mfma_f32_16x16x32_bf16 v[94:97], v[156:159], v[216:219], v[94:97]
	v_mfma_f32_16x16x32_bf16 v[90:93], v[164:167], v[216:219], v[90:93]
	v_mfma_f32_16x16x32_bf16 v[78:81], v[156:159], v[224:227], v[78:81]
	v_mfma_f32_16x16x32_bf16 v[74:77], v[164:167], v[224:227], v[74:77]
	v_mfma_f32_16x16x32_bf16 v[118:121], v[180:183], v[196:199], v[118:121]
	v_mfma_f32_16x16x32_bf16 v[114:117], v[188:191], v[196:199], v[114:117]
	v_mfma_f32_16x16x32_bf16 v[102:105], v[180:183], v[204:207], v[102:105]
	v_mfma_f32_16x16x32_bf16 v[98:101], v[188:191], v[204:207], v[98:101]
	v_mfma_f32_16x16x32_bf16 v[86:89], v[180:183], v[212:215], v[86:89]
	v_mfma_f32_16x16x32_bf16 v[82:85], v[188:191], v[212:215], v[82:85]
	v_mfma_f32_16x16x32_bf16 v[70:73], v[180:183], v[220:223], v[70:73]
	v_mfma_f32_16x16x32_bf16 v[66:69], v[188:191], v[220:223], v[66:69]
	v_mfma_f32_16x16x32_bf16 v[118:121], v[184:187], v[200:203], v[118:121]
	v_mfma_f32_16x16x32_bf16 v[114:117], v[192:195], v[200:203], v[114:117]
	v_mfma_f32_16x16x32_bf16 v[102:105], v[184:187], v[208:211], v[102:105]
	v_mfma_f32_16x16x32_bf16 v[98:101], v[192:195], v[208:211], v[98:101]
	v_mfma_f32_16x16x32_bf16 v[86:89], v[184:187], v[216:219], v[86:89]
	v_mfma_f32_16x16x32_bf16 v[82:85], v[192:195], v[216:219], v[82:85]
	v_mfma_f32_16x16x32_bf16 v[70:73], v[184:187], v[224:227], v[70:73]
	v_mfma_f32_16x16x32_bf16 v[66:69], v[192:195], v[224:227], v[66:69]
	s_barrier
	s_setprio 0
	s_add_u32 s98, s46, s8
	s_addc_u32 s99, s47, s9
	s_add_u32 s100, s48, s8
	s_addc_u32 s101, s49, s9
	s_add_i32 s76, s60, s6
	s_mov_b32 m0, s76
	ds_read_b128 v[196:199], v176 offset:16384
	ds_read_b128 v[200:203], v176 offset:17408
	ds_read_b128 v[204:207], v176 offset:18432
	ds_read_b128 v[208:211], v176 offset:19456
	ds_read_b128 v[212:215], v176 offset:20480
	ds_read_b128 v[216:219], v176 offset:21504
	ds_read_b128 v[220:223], v176 offset:22528
	ds_read_b128 v[224:227], v176 offset:23552
	global_load_lds_dwordx4 v132, s[46:47]
	s_add_i32 m0, s76, 0x2000
	s_add_u32 s76, s46, 0x40000
	s_addc_u32 s77, s47, 0
	s_add_i32 s78, s61, s6
	global_load_lds_dwordx4 v136, s[46:47]
	s_mov_b32 m0, s78
	s_nop 0
	global_load_lds_dwordx4 v132, s[76:77]
	s_add_i32 m0, s78, 0x2000
	s_nop 0
	global_load_lds_dwordx4 v136, s[76:77]
	s_mov_b32 m0, s43
	s_nop 0
	global_load_lds_dwordx4 v130, s[48:49]
	s_mov_b32 m0, s51
	s_nop 0
	global_load_lds_dwordx4 v134, s[48:49]
	s_waitcnt vmcnt(8)
	s_waitcnt lgkmcnt(0)
	s_setprio 1
	s_barrier
	v_mfma_f32_16x16x32_bf16 v[62:65], v[152:155], v[196:199], v[62:65]
	v_mfma_f32_16x16x32_bf16 v[58:61], v[160:163], v[196:199], v[58:61]
	v_mfma_f32_16x16x32_bf16 v[46:49], v[152:155], v[204:207], v[46:49]
	v_mfma_f32_16x16x32_bf16 v[42:45], v[160:163], v[204:207], v[42:45]
	v_mfma_f32_16x16x32_bf16 v[30:33], v[152:155], v[212:215], v[30:33]
	v_mfma_f32_16x16x32_bf16 v[26:29], v[160:163], v[212:215], v[26:29]
	v_mfma_f32_16x16x32_bf16 v[14:17], v[152:155], v[220:223], v[14:17]
	v_mfma_f32_16x16x32_bf16 v[10:13], v[160:163], v[220:223], v[10:13]
	v_mfma_f32_16x16x32_bf16 v[62:65], v[156:159], v[200:203], v[62:65]
	v_mfma_f32_16x16x32_bf16 v[58:61], v[164:167], v[200:203], v[58:61]
	v_mfma_f32_16x16x32_bf16 v[46:49], v[156:159], v[208:211], v[46:49]
	v_mfma_f32_16x16x32_bf16 v[42:45], v[164:167], v[208:211], v[42:45]
	v_mfma_f32_16x16x32_bf16 v[30:33], v[156:159], v[216:219], v[30:33]
	v_mfma_f32_16x16x32_bf16 v[26:29], v[164:167], v[216:219], v[26:29]
	v_mfma_f32_16x16x32_bf16 v[14:17], v[156:159], v[224:227], v[14:17]
	v_mfma_f32_16x16x32_bf16 v[10:13], v[164:167], v[224:227], v[10:13]
	v_mfma_f32_16x16x32_bf16 v[54:57], v[180:183], v[196:199], v[54:57]
	v_mfma_f32_16x16x32_bf16 v[50:53], v[188:191], v[196:199], v[50:53]
	v_mfma_f32_16x16x32_bf16 v[38:41], v[180:183], v[204:207], v[38:41]
	v_mfma_f32_16x16x32_bf16 v[34:37], v[188:191], v[204:207], v[34:37]
	v_mfma_f32_16x16x32_bf16 v[22:25], v[180:183], v[212:215], v[22:25]
	v_mfma_f32_16x16x32_bf16 v[18:21], v[188:191], v[212:215], v[18:21]
	v_mfma_f32_16x16x32_bf16 v[6:9], v[180:183], v[220:223], v[6:9]
	v_mfma_f32_16x16x32_bf16 v[2:5], v[188:191], v[220:223], v[2:5]
	v_mfma_f32_16x16x32_bf16 v[54:57], v[184:187], v[200:203], v[54:57]
	v_mfma_f32_16x16x32_bf16 v[50:53], v[192:195], v[200:203], v[50:53]
	v_mfma_f32_16x16x32_bf16 v[38:41], v[184:187], v[208:211], v[38:41]
	v_mfma_f32_16x16x32_bf16 v[34:37], v[192:195], v[208:211], v[34:37]
	v_mfma_f32_16x16x32_bf16 v[22:25], v[184:187], v[216:219], v[22:25]
	v_mfma_f32_16x16x32_bf16 v[18:21], v[192:195], v[216:219], v[18:21]
	v_mfma_f32_16x16x32_bf16 v[6:9], v[184:187], v[224:227], v[6:9]
	v_mfma_f32_16x16x32_bf16 v[2:5], v[192:195], v[224:227], v[2:5]
	s_barrier
; #define PG8_STAGE(bufoff, gbase, voff) do { _Pragma("unroll") for (int _i = 0; _i < 2; ++_i) \
;         __builtin_amdgcn_global_load_lds((const unsigned*)((const char*)(gbase) + (voff)[_i]), (LAS unsigned*)(lds + (bufoff) + ldsw + _i * 8192), 16, 0, 0); } while (0)
; #define PG8_LDA(dst, b, h) do { _Pragma("unroll") for (int m = 0; m < 4; ++m) _Pragma("unroll") for (int k = 0; k < 2; ++k) dst[m][k] = *(const LAS bf16x8*)(lds + PG8_SA(b, h) + aoff + m * 2048 + k * 1024); } while (0)
; #define PG8_LDB(dst, b, h) do { _Pragma("unroll") for (int n = 0; n < 2; ++n) _Pragma("unroll") for (int k = 0; k < 2; ++k) dst[n][k] = *(const LAS bf16x8*)(lds + PG8_SB(b, h) + boff + n * 2048 + k * 1024); } while (0)
; #define PG8_MMA(ai, bj, At, Bt) do { __builtin_amdgcn_s_setprio(1); _Pragma("unroll") for (int m = 0; m < 4; ++m) _Pragma("unroll") for (int n = 0; n < 2; ++n) _Pragma("unroll") for (int k = 0; k < 2; ++k) \
;         acc[ai][bj][m][n] = __builtin_amdgcn_mfma_f32_16x16x32_bf16(Bt[n][k], At[m][k], acc[ai][bj][m][n], 0, 0, 0); __builtin_amdgcn_s_setprio(0); } while (0)
; #define PG8_WAIT_V(n) asm volatile("s_waitcnt vmcnt(" #n ")" ::: "memory")
; #define PG8_WAIT_L(n) asm volatile("s_waitcnt lgkmcnt(" #n ")" ::: "memory")
; #define PG8_BAR __builtin_amdgcn_s_barrier()
; #define PG8_SCHED __builtin_amdgcn_sched_barrier(0)
; template <class Epi>
; __device__ __forceinline__ void gemm_phase(LAS unsigned char* lds, const Gemm g, const StaticOrder& S, const Epi& E) {
;     ...
;             PG8_LDB(B0, 1, 0); PG8_LDB(B1, 1, 1); PG8_SCHED; PG8_LDA(At, 1, 0); PG8_STAGE(PG8_SA(0, 1), a2 + hstep, voffA);
;             PG8_WAIT_V(8); PG8_WAIT_L(0); PG8_BAR; PG8_MMA(0, 0, At, B0); PG8_MMA(0, 1, At, B1); PG8_BAR; PG8_SCHED;
;             PG8_LDA(At, 1, 1); PG8_STAGE(PG8_SB(1, 0), b3, voffB); PG8_STAGE(PG8_SB(1, 1), b3 + hstep, voffB); PG8_STAGE(PG8_SA(1, 0), a3, voffA);
;             PG8_WAIT_V(8); PG8_WAIT_L(0); PG8_BAR; PG8_MMA(1, 0, At, B0); PG8_MMA(1, 1, At, B1); PG8_BAR; PG8_SCHED;
;         }
	s_setprio 0
	s_add_i32 s76, 0, 0x18000
	v_add_u32_e32 v138, s76, v172
	s_add_i32 s77, 0, 0x1c000
	ds_read_b128 v[152:155], v138
	ds_read_b128 v[156:159], v138 offset:1024
	ds_read_b128 v[160:163], v138 offset:2048
	ds_read_b128 v[164:167], v138 offset:3072
	v_add_u32_e32 v138, s77, v172
	ds_read_b128 v[180:183], v138
	ds_read_b128 v[184:187], v138 offset:1024
	ds_read_b128 v[188:191], v138 offset:2048
	ds_read_b128 v[192:195], v138 offset:3072
	s_add_u32 s48, s48, 0x40000
	s_addc_u32 s49, s49, 0
	s_mov_b32 m0, s52
	ds_read_b128 v[196:199], v176 offset:32768
	ds_read_b128 v[200:203], v176 offset:33792
	ds_read_b128 v[204:207], v176 offset:34816
	ds_read_b128 v[208:211], v176 offset:35840
	ds_read_b128 v[212:215], v176 offset:36864
	ds_read_b128 v[216:219], v176 offset:37888
	ds_read_b128 v[220:223], v176 offset:38912
	ds_read_b128 v[224:227], v176 offset:39936
	global_load_lds_dwordx4 v130, s[48:49]
	s_mov_b32 m0, s53
	s_nop 0
	global_load_lds_dwordx4 v134, s[48:49]
	s_waitcnt vmcnt(8)
	s_waitcnt lgkmcnt(0)
	s_setprio 1
	s_barrier
	v_mfma_f32_16x16x32_bf16 v[126:129], v[152:155], v[196:199], v[126:129]
	v_mfma_f32_16x16x32_bf16 v[122:125], v[160:163], v[196:199], v[122:125]
	v_mfma_f32_16x16x32_bf16 v[110:113], v[152:155], v[204:207], v[110:113]
	v_mfma_f32_16x16x32_bf16 v[106:109], v[160:163], v[204:207], v[106:109]
	v_mfma_f32_16x16x32_bf16 v[94:97], v[152:155], v[212:215], v[94:97]
	v_mfma_f32_16x16x32_bf16 v[90:93], v[160:163], v[212:215], v[90:93]
	v_mfma_f32_16x16x32_bf16 v[78:81], v[152:155], v[220:223], v[78:81]
	v_mfma_f32_16x16x32_bf16 v[74:77], v[160:163], v[220:223], v[74:77]
	v_mfma_f32_16x16x32_bf16 v[126:129], v[156:159], v[200:203], v[126:129]
	v_mfma_f32_16x16x32_bf16 v[122:125], v[164:167], v[200:203], v[122:125]
	v_mfma_f32_16x16x32_bf16 v[110:113], v[156:159], v[208:211], v[110:113]
	v_mfma_f32_16x16x32_bf16 v[106:109], v[164:167], v[208:211], v[106:109]
	v_mfma_f32_16x16x32_bf16 v[94:97], v[156:159], v[216:219], v[94:97]
	v_mfma_f32_16x16x32_bf16 v[90:93], v[164:167], v[216:219], v[90:93]
	v_mfma_f32_16x16x32_bf16 v[78:81], v[156:159], v[224:227], v[78:81]
	v_mfma_f32_16x16x32_bf16 v[74:77], v[164:167], v[224:227], v[74:77]
	v_mfma_f32_16x16x32_bf16 v[118:121], v[180:183], v[196:199], v[118:121]
	v_mfma_f32_16x16x32_bf16 v[114:117], v[188:191], v[196:199], v[114:117]
	v_mfma_f32_16x16x32_bf16 v[102:105], v[180:183], v[204:207], v[102:105]
	v_mfma_f32_16x16x32_bf16 v[98:101], v[188:191], v[204:207], v[98:101]
	v_mfma_f32_16x16x32_bf16 v[86:89], v[180:183], v[212:215], v[86:89]
	v_mfma_f32_16x16x32_bf16 v[82:85], v[188:191], v[212:215], v[82:85]
	v_mfma_f32_16x16x32_bf16 v[70:73], v[180:183], v[220:223], v[70:73]
	v_mfma_f32_16x16x32_bf16 v[66:69], v[188:191], v[220:223], v[66:69]
	v_mfma_f32_16x16x32_bf16 v[118:121], v[184:187], v[200:203], v[118:121]
	v_mfma_f32_16x16x32_bf16 v[114:117], v[192:195], v[200:203], v[114:117]
	v_mfma_f32_16x16x32_bf16 v[102:105], v[184:187], v[208:211], v[102:105]
	v_mfma_f32_16x16x32_bf16 v[98:101], v[192:195], v[208:211], v[98:101]
	v_mfma_f32_16x16x32_bf16 v[86:89], v[184:187], v[216:219], v[86:89]
	v_mfma_f32_16x16x32_bf16 v[82:85], v[192:195], v[216:219], v[82:85]
	v_mfma_f32_16x16x32_bf16 v[70:73], v[184:187], v[224:227], v[70:73]
	v_mfma_f32_16x16x32_bf16 v[66:69], v[192:195], v[224:227], v[66:69]
	s_barrier
	s_setprio 0
	s_add_i32 s48, s76, s6
	s_mov_b32 m0, s48
	ds_read_b128 v[196:199], v176 offset:49152
	ds_read_b128 v[200:203], v176 offset:50176
	ds_read_b128 v[204:207], v176 offset:51200
	ds_read_b128 v[208:211], v176 offset:52224
	ds_read_b128 v[212:215], v176 offset:53248
	ds_read_b128 v[216:219], v176 offset:54272
	ds_read_b128 v[220:223], v176 offset:55296
	ds_read_b128 v[224:227], v176 offset:56320
	global_load_lds_dwordx4 v132, s[98:99]
	s_add_i32 m0, s48, 0x2000
	s_add_u32 s46, s46, 0x40080
	s_addc_u32 s47, s47, 0
	s_add_i32 s48, s77, s6
	global_load_lds_dwordx4 v136, s[98:99]
	s_mov_b32 m0, s48
	s_nop 0
	global_load_lds_dwordx4 v132, s[46:47]
	s_add_i32 m0, s48, 0x2000
	s_nop 0
	global_load_lds_dwordx4 v136, s[46:47]
	s_mov_b32 m0, s56
	s_nop 0
	global_load_lds_dwordx4 v130, s[100:101]
	s_mov_b32 m0, s57
	s_nop 0
	global_load_lds_dwordx4 v134, s[100:101]
	s_waitcnt vmcnt(8)
	s_waitcnt lgkmcnt(0)
	s_setprio 1
	s_barrier
	v_mfma_f32_16x16x32_bf16 v[62:65], v[152:155], v[196:199], v[62:65]
	v_mfma_f32_16x16x32_bf16 v[58:61], v[160:163], v[196:199], v[58:61]
	v_mfma_f32_16x16x32_bf16 v[46:49], v[152:155], v[204:207], v[46:49]
	v_mfma_f32_16x16x32_bf16 v[42:45], v[160:163], v[204:207], v[42:45]
	v_mfma_f32_16x16x32_bf16 v[30:33], v[152:155], v[212:215], v[30:33]
	v_mfma_f32_16x16x32_bf16 v[26:29], v[160:163], v[212:215], v[26:29]
	v_mfma_f32_16x16x32_bf16 v[14:17], v[152:155], v[220:223], v[14:17]
	v_mfma_f32_16x16x32_bf16 v[10:13], v[160:163], v[220:223], v[10:13]
	v_mfma_f32_16x16x32_bf16 v[62:65], v[156:159], v[200:203], v[62:65]
	v_mfma_f32_16x16x32_bf16 v[58:61], v[164:167], v[200:203], v[58:61]
	v_mfma_f32_16x16x32_bf16 v[46:49], v[156:159], v[208:211], v[46:49]
	v_mfma_f32_16x16x32_bf16 v[42:45], v[164:167], v[208:211], v[42:45]
	v_mfma_f32_16x16x32_bf16 v[30:33], v[156:159], v[216:219], v[30:33]
	v_mfma_f32_16x16x32_bf16 v[26:29], v[164:167], v[216:219], v[26:29]
	v_mfma_f32_16x16x32_bf16 v[14:17], v[156:159], v[224:227], v[14:17]
	v_mfma_f32_16x16x32_bf16 v[10:13], v[164:167], v[224:227], v[10:13]
	v_mfma_f32_16x16x32_bf16 v[54:57], v[180:183], v[196:199], v[54:57]
	v_mfma_f32_16x16x32_bf16 v[50:53], v[188:191], v[196:199], v[50:53]
	v_mfma_f32_16x16x32_bf16 v[38:41], v[180:183], v[204:207], v[38:41]
	v_mfma_f32_16x16x32_bf16 v[34:37], v[188:191], v[204:207], v[34:37]
	v_mfma_f32_16x16x32_bf16 v[22:25], v[180:183], v[212:215], v[22:25]
	v_mfma_f32_16x16x32_bf16 v[18:21], v[188:191], v[212:215], v[18:21]
	v_mfma_f32_16x16x32_bf16 v[6:9], v[180:183], v[220:223], v[6:9]
	v_mfma_f32_16x16x32_bf16 v[2:5], v[188:191], v[220:223], v[2:5]
	v_mfma_f32_16x16x32_bf16 v[54:57], v[184:187], v[200:203], v[54:57]
	v_mfma_f32_16x16x32_bf16 v[50:53], v[192:195], v[200:203], v[50:53]
	v_mfma_f32_16x16x32_bf16 v[38:41], v[184:187], v[208:211], v[38:41]
	v_mfma_f32_16x16x32_bf16 v[34:37], v[192:195], v[208:211], v[34:37]
	v_mfma_f32_16x16x32_bf16 v[22:25], v[184:187], v[216:219], v[22:25]
	v_mfma_f32_16x16x32_bf16 v[18:21], v[192:195], v[216:219], v[18:21]
	v_mfma_f32_16x16x32_bf16 v[6:9], v[184:187], v[224:227], v[6:9]
	v_mfma_f32_16x16x32_bf16 v[2:5], v[192:195], v[224:227], v[2:5]
	s_barrier
	s_setprio 0
	s_add_i32 s69, s69, 2
	s_add_u32 s44, s44, 0x100
	s_addc_u32 s45, s45, 0
	s_add_u32 s67, s67, 0x100
	s_addc_u32 s68, s68, 0
	s_cmp_gt_u32 s69, 13
	s_cbranch_scc0 .LBB0_619
	s_and_b64 vcc, exec, s[18:19]
	s_cbranch_vccz .LBB0_622
	s_barrier

; #define PG8_STAGE(bufoff, gbase, voff) do { _Pragma("unroll") for (int _i = 0; _i < 2; ++_i) \
;         __builtin_amdgcn_global_load_lds((const unsigned*)((const char*)(gbase) + (voff)[_i]), (LAS unsigned*)(lds + (bufoff) + ldsw + _i * 8192), 16, 0, 0); } while (0)
; #define PG8_LDA(dst, b, h) do { _Pragma("unroll") for (int m = 0; m < 4; ++m) _Pragma("unroll") for (int k = 0; k < 2; ++k) dst[m][k] = *(const LAS bf16x8*)(lds + PG8_SA(b, h) + aoff + m * 2048 + k * 1024); } while (0)
; #define PG8_LDB(dst, b, h) do { _Pragma("unroll") for (int n = 0; n < 2; ++n) _Pragma("unroll") for (int k = 0; k < 2; ++k) dst[n][k] = *(const LAS bf16x8*)(lds + PG8_SB(b, h) + boff + n * 2048 + k * 1024); } while (0)
; #define PG8_MMA(ai, bj, At, Bt) do { __builtin_amdgcn_s_setprio(1); _Pragma("unroll") for (int m = 0; m < 4; ++m) _Pragma("unroll") for (int n = 0; n < 2; ++n) _Pragma("unroll") for (int k = 0; k < 2; ++k) \
;         acc[ai][bj][m][n] = __builtin_amdgcn_mfma_f32_16x16x32_bf16(Bt[n][k], At[m][k], acc[ai][bj][m][n], 0, 0, 0); __builtin_amdgcn_s_setprio(0); } while (0)
; #define PG8_WAIT_V(n) asm volatile("s_waitcnt vmcnt(" #n ")" ::: "memory")
; #define PG8_WAIT_L(n) asm volatile("s_waitcnt lgkmcnt(" #n ")" ::: "memory")
; #define PG8_BAR __builtin_amdgcn_s_barrier()
; #define PG8_SCHED __builtin_amdgcn_sched_barrier(0)
; template <class Epi>
; __device__ __forceinline__ void gemm_phase(LAS unsigned char* lds, const Gemm g, const StaticOrder& S, const Epi& E) {
;     ...
;             PG8_LDB(B0, 0, 0); PG8_LDB(B1, 0, 1); PG8_SCHED; PG8_LDA(At, 0, 0); PG8_STAGE(PG8_SA(1, 1), a1 + hstep, voffA);
;             PG8_WAIT_V(8); PG8_WAIT_L(0); PG8_BAR; PG8_MMA(0, 0, At, B0); PG8_MMA(0, 1, At, B1); PG8_BAR; PG8_SCHED;
;             PG8_LDA(At, 0, 1); PG8_STAGE(PG8_SB(0, 0), b2, voffB); PG8_STAGE(PG8_SB(0, 1), b2 + hstep, voffB); PG8_STAGE(PG8_SA(0, 0), a2, voffA);
;             PG8_WAIT_V(8); PG8_WAIT_L(0); PG8_BAR; PG8_MMA(1, 0, At, B0); PG8_MMA(1, 1, At, B1); PG8_BAR; PG8_SCHED;
.LBB0_700:
	v_add_u32_e32 v3, s68, v198
	ds_read_b128 v[134:137], v3
	ds_read_b128 v[138:141], v3 offset:1024
	ds_read_b128 v[142:145], v3 offset:2048
	ds_read_b128 v[146:149], v3 offset:3072
	v_add_u32_e32 v3, s69, v198
	s_add_u32 s52, s48, s50
	ds_read_b128 v[158:161], v3
	ds_read_b128 v[162:165], v3 offset:1024
	ds_read_b128 v[166:169], v3 offset:2048
	ds_read_b128 v[188:191], v3 offset:3072
	s_addc_u32 s53, s49, s51
	s_add_u32 s52, s52, 0x100
	s_addc_u32 s53, s53, 0
	s_add_u32 s81, s78, s50
	s_addc_u32 s82, s79, s51
	s_cmpk_eq_i32 s50, 0x700
	s_cselect_b32 s55, s43, s53
	s_cselect_b32 s54, s76, s52
	s_cselect_b32 s53, s41, s82
	s_cselect_b32 s52, s77, s81
	v_lshl_add_u64 v[4:5], v[154:155], 0, s[50:51]
	s_add_i32 m0, s59, 0xc000
	ds_read_b128 v[192:195], v200
	ds_read_b128 v[202:205], v200 offset:1024
	ds_read_b128 v[206:209], v200 offset:2048
	ds_read_b128 v[210:213], v200 offset:3072
	ds_read_b128 v[214:217], v200 offset:4096
	ds_read_b128 v[218:221], v200 offset:5120
	ds_read_b128 v[222:225], v200 offset:6144
	ds_read_b128 v[226:229], v200 offset:7168
	global_load_lds_dwordx4 v[4:5], off
	v_lshl_add_u64 v[4:5], v[156:157], 0, s[50:51]
	s_add_i32 m0, s59, 0xe000
	s_nop 0
	global_load_lds_dwordx4 v[4:5], off
	s_waitcnt vmcnt(8)
	s_waitcnt lgkmcnt(0)
	s_setprio 1
	s_barrier
	v_mfma_f32_16x16x32_bf16 v[130:133], v[134:137], v[192:195], v[130:133]
	v_mfma_f32_16x16x32_bf16 v[126:129], v[142:145], v[192:195], v[126:129]
	v_mfma_f32_16x16x32_bf16 v[114:117], v[134:137], v[206:209], v[114:117]
	v_mfma_f32_16x16x32_bf16 v[110:113], v[142:145], v[206:209], v[110:113]
	v_mfma_f32_16x16x32_bf16 v[98:101], v[134:137], v[214:217], v[98:101]
	v_mfma_f32_16x16x32_bf16 v[94:97], v[142:145], v[214:217], v[94:97]
	v_mfma_f32_16x16x32_bf16 v[82:85], v[134:137], v[222:225], v[82:85]
	v_mfma_f32_16x16x32_bf16 v[78:81], v[142:145], v[222:225], v[78:81]
	v_mfma_f32_16x16x32_bf16 v[130:133], v[138:141], v[202:205], v[130:133]
	v_mfma_f32_16x16x32_bf16 v[126:129], v[146:149], v[202:205], v[126:129]
	v_mfma_f32_16x16x32_bf16 v[114:117], v[138:141], v[210:213], v[114:117]
	v_mfma_f32_16x16x32_bf16 v[110:113], v[146:149], v[210:213], v[110:113]
	v_mfma_f32_16x16x32_bf16 v[98:101], v[138:141], v[218:221], v[98:101]
	v_mfma_f32_16x16x32_bf16 v[94:97], v[146:149], v[218:221], v[94:97]
	v_mfma_f32_16x16x32_bf16 v[82:85], v[138:141], v[226:229], v[82:85]
	v_mfma_f32_16x16x32_bf16 v[78:81], v[146:149], v[226:229], v[78:81]
	v_mfma_f32_16x16x32_bf16 v[122:125], v[158:161], v[192:195], v[122:125]
	v_mfma_f32_16x16x32_bf16 v[118:121], v[166:169], v[192:195], v[118:121]
	v_mfma_f32_16x16x32_bf16 v[106:109], v[158:161], v[206:209], v[106:109]
	v_mfma_f32_16x16x32_bf16 v[102:105], v[166:169], v[206:209], v[102:105]
	v_mfma_f32_16x16x32_bf16 v[90:93], v[158:161], v[214:217], v[90:93]
	v_mfma_f32_16x16x32_bf16 v[86:89], v[166:169], v[214:217], v[86:89]
	v_mfma_f32_16x16x32_bf16 v[74:77], v[158:161], v[222:225], v[74:77]
	v_mfma_f32_16x16x32_bf16 v[70:73], v[166:169], v[222:225], v[70:73]
	v_mfma_f32_16x16x32_bf16 v[122:125], v[162:165], v[202:205], v[122:125]
	v_mfma_f32_16x16x32_bf16 v[118:121], v[188:191], v[202:205], v[118:121]
	v_mfma_f32_16x16x32_bf16 v[106:109], v[162:165], v[210:213], v[106:109]
	v_mfma_f32_16x16x32_bf16 v[102:105], v[188:191], v[210:213], v[102:105]
	v_mfma_f32_16x16x32_bf16 v[90:93], v[162:165], v[218:221], v[90:93]
	v_mfma_f32_16x16x32_bf16 v[86:89], v[188:191], v[218:221], v[86:89]
	v_mfma_f32_16x16x32_bf16 v[74:77], v[162:165], v[226:229], v[74:77]
	v_mfma_f32_16x16x32_bf16 v[70:73], v[188:191], v[226:229], v[70:73]
	s_barrier
	s_setprio 0
	s_add_u32 s98, s52, s12
	s_addc_u32 s99, s53, s13
	s_add_u32 s100, s54, s12
	s_addc_u32 s101, s55, s13
	s_add_i32 s81, s68, s56
	s_mov_b32 m0, s81
	ds_read_b128 v[192:195], v200 offset:16384
	ds_read_b128 v[202:205], v200 offset:17408
	ds_read_b128 v[206:209], v200 offset:18432
	ds_read_b128 v[210:213], v200 offset:19456
	ds_read_b128 v[214:217], v200 offset:20480
	ds_read_b128 v[218:221], v200 offset:21504
	ds_read_b128 v[222:225], v200 offset:22528
	ds_read_b128 v[226:229], v200 offset:23552
	global_load_lds_dwordx4 v176, s[52:53]
	s_add_i32 m0, s81, 0x2000
	s_add_u32 s82, s52, 0x40000
	s_addc_u32 s83, s53, 0
	s_add_i32 s81, s69, s56
	global_load_lds_dwordx4 v172, s[52:53]
	s_mov_b32 m0, s81
	s_nop 0
	global_load_lds_dwordx4 v176, s[82:83]
	v_lshl_add_u64 v[4:5], s[82:83], 0, v[172:173]
	s_add_i32 m0, s81, 0x2000
	v_lshl_add_u64 v[234:235], s[54:55], 0, v[174:175]
	global_load_lds_dwordx4 v172, s[82:83]
	s_mov_b32 m0, s59
	s_nop 0
	global_load_lds_dwordx4 v178, s[54:55]
	s_mov_b32 m0, s60
	s_nop 0
	global_load_lds_dwordx4 v174, s[54:55]
	s_waitcnt vmcnt(8)
	s_waitcnt lgkmcnt(0)
	s_setprio 1
	s_barrier
; #define PG8_STAGE(bufoff, gbase, voff) do { _Pragma("unroll") for (int _i = 0; _i < 2; ++_i) \
;         __builtin_amdgcn_global_load_lds((const unsigned*)((const char*)(gbase) + (voff)[_i]), (LAS unsigned*)(lds + (bufoff) + ldsw + _i * 8192), 16, 0, 0); } while (0)
; #define PG8_LDA(dst, b, h) do { _Pragma("unroll") for (int m = 0; m < 4; ++m) _Pragma("unroll") for (int k = 0; k < 2; ++k) dst[m][k] = *(const LAS bf16x8*)(lds + PG8_SA(b, h) + aoff + m * 2048 + k * 1024); } while (0)
; #define PG8_LDB(dst, b, h) do { _Pragma("unroll") for (int n = 0; n < 2; ++n) _Pragma("unroll") for (int k = 0; k < 2; ++k) dst[n][k] = *(const LAS bf16x8*)(lds + PG8_SB(b, h) + boff + n * 2048 + k * 1024); } while (0)
; #define PG8_MMA(ai, bj, At, Bt) do { __builtin_amdgcn_s_setprio(1); _Pragma("unroll") for (int m = 0; m < 4; ++m) _Pragma("unroll") for (int n = 0; n < 2; ++n) _Pragma("unroll") for (int k = 0; k < 2; ++k) \
;         acc[ai][bj][m][n] = __builtin_amdgcn_mfma_f32_16x16x32_bf16(Bt[n][k], At[m][k], acc[ai][bj][m][n], 0, 0, 0); __builtin_amdgcn_s_setprio(0); } while (0)
; #define PG8_WAIT_V(n) asm volatile("s_waitcnt vmcnt(" #n ")" ::: "memory")
; #define PG8_WAIT_L(n) asm volatile("s_waitcnt lgkmcnt(" #n ")" ::: "memory")
; #define PG8_BAR __builtin_amdgcn_s_barrier()
; #define PG8_SCHED __builtin_amdgcn_sched_barrier(0)
; template <class Epi>
; __device__ __forceinline__ void gemm_phase(LAS unsigned char* lds, const Gemm g, const StaticOrder& S, const Epi& E) {
;     ...
;             PG8_LDA(At, 0, 1); PG8_STAGE(PG8_SB(0, 0), b2, voffB); PG8_STAGE(PG8_SB(0, 1), b2 + hstep, voffB); PG8_STAGE(PG8_SA(0, 0), a2, voffA);
;             PG8_WAIT_V(8); PG8_WAIT_L(0); PG8_BAR; PG8_MMA(1, 0, At, B0); PG8_MMA(1, 1, At, B1); PG8_BAR; PG8_SCHED;
;             PG8_LDB(B0, 1, 0); PG8_LDB(B1, 1, 1); PG8_SCHED; PG8_LDA(At, 1, 0); PG8_STAGE(PG8_SA(0, 1), a2 + hstep, voffA);
;             PG8_WAIT_V(8); PG8_WAIT_L(0); PG8_BAR; PG8_MMA(0, 0, At, B0); PG8_MMA(0, 1, At, B1); PG8_BAR; PG8_SCHED;
	v_mfma_f32_16x16x32_bf16 v[66:69], v[134:137], v[192:195], v[66:69]
	v_mfma_f32_16x16x32_bf16 v[62:65], v[142:145], v[192:195], v[62:65]
	v_mfma_f32_16x16x32_bf16 v[50:53], v[134:137], v[206:209], v[50:53]
	v_mfma_f32_16x16x32_bf16 v[46:49], v[142:145], v[206:209], v[46:49]
	v_mfma_f32_16x16x32_bf16 v[34:37], v[134:137], v[214:217], v[34:37]
	v_mfma_f32_16x16x32_bf16 v[30:33], v[142:145], v[214:217], v[30:33]
	v_mfma_f32_16x16x32_bf16 v[18:21], v[134:137], v[222:225], v[18:21]
	v_mfma_f32_16x16x32_bf16 v[14:17], v[142:145], v[222:225], v[14:17]
	v_mfma_f32_16x16x32_bf16 v[66:69], v[138:141], v[202:205], v[66:69]
	v_mfma_f32_16x16x32_bf16 v[62:65], v[146:149], v[202:205], v[62:65]
	v_mfma_f32_16x16x32_bf16 v[50:53], v[138:141], v[210:213], v[50:53]
	v_mfma_f32_16x16x32_bf16 v[46:49], v[146:149], v[210:213], v[46:49]
	v_mfma_f32_16x16x32_bf16 v[34:37], v[138:141], v[218:221], v[34:37]
	v_mfma_f32_16x16x32_bf16 v[30:33], v[146:149], v[218:221], v[30:33]
	v_mfma_f32_16x16x32_bf16 v[18:21], v[138:141], v[226:229], v[18:21]
	v_mfma_f32_16x16x32_bf16 v[14:17], v[146:149], v[226:229], v[14:17]
	v_mfma_f32_16x16x32_bf16 v[58:61], v[158:161], v[192:195], v[58:61]
	v_mfma_f32_16x16x32_bf16 v[54:57], v[166:169], v[192:195], v[54:57]
	v_mfma_f32_16x16x32_bf16 v[42:45], v[158:161], v[206:209], v[42:45]
	v_mfma_f32_16x16x32_bf16 v[38:41], v[166:169], v[206:209], v[38:41]
	v_mfma_f32_16x16x32_bf16 v[26:29], v[158:161], v[214:217], v[26:29]
	v_mfma_f32_16x16x32_bf16 v[22:25], v[166:169], v[214:217], v[22:25]
	v_mfma_f32_16x16x32_bf16 v[10:13], v[158:161], v[222:225], v[10:13]
	v_mfma_f32_16x16x32_bf16 v[4:7], v[166:169], v[222:225], v[6:9]
	v_mfma_f32_16x16x32_bf16 v[58:61], v[162:165], v[202:205], v[58:61]
	v_mfma_f32_16x16x32_bf16 v[54:57], v[188:191], v[202:205], v[54:57]
	v_mfma_f32_16x16x32_bf16 v[42:45], v[162:165], v[210:213], v[42:45]
	v_mfma_f32_16x16x32_bf16 v[38:41], v[188:191], v[210:213], v[38:41]
	v_mfma_f32_16x16x32_bf16 v[26:29], v[162:165], v[218:221], v[26:29]
	v_mfma_f32_16x16x32_bf16 v[22:25], v[188:191], v[218:221], v[22:25]
	v_mfma_f32_16x16x32_bf16 v[10:13], v[162:165], v[226:229], v[10:13]
	v_mfma_f32_16x16x32_bf16 v[4:7], v[188:191], v[226:229], v[4:7]
	s_barrier
	s_setprio 0
	s_add_i32 s81, 0, 0x18000
	v_add_u32_e32 v3, s81, v198
	s_add_i32 s82, 0, 0x1c000
	ds_read_b128 v[134:137], v3
	ds_read_b128 v[138:141], v3 offset:1024
	ds_read_b128 v[142:145], v3 offset:2048
	ds_read_b128 v[146:149], v3 offset:3072
	v_add_u32_e32 v3, s82, v198
	ds_read_b128 v[158:161], v3
	ds_read_b128 v[162:165], v3 offset:1024
	ds_read_b128 v[166:169], v3 offset:2048
	ds_read_b128 v[188:191], v3 offset:3072
	s_add_u32 s54, s54, 0x40000
	s_addc_u32 s55, s55, 0
	s_mov_b32 m0, s61
	ds_read_b128 v[192:195], v200 offset:32768
	ds_read_b128 v[202:205], v200 offset:33792
	ds_read_b128 v[206:209], v200 offset:34816
	ds_read_b128 v[210:213], v200 offset:35840
	ds_read_b128 v[214:217], v200 offset:36864
	ds_read_b128 v[218:221], v200 offset:37888
	ds_read_b128 v[222:225], v200 offset:38912
	ds_read_b128 v[226:229], v200 offset:39936
	global_load_lds_dwordx4 v178, s[54:55]
	s_mov_b32 m0, s62
	s_nop 0
	global_load_lds_dwordx4 v174, s[54:55]
	s_waitcnt vmcnt(8)
	s_waitcnt lgkmcnt(0)
	s_setprio 1
	s_barrier
	v_mfma_f32_16x16x32_bf16 v[130:133], v[134:137], v[192:195], v[130:133]
	v_mfma_f32_16x16x32_bf16 v[126:129], v[142:145], v[192:195], v[126:129]
	v_mfma_f32_16x16x32_bf16 v[114:117], v[134:137], v[206:209], v[114:117]
	v_mfma_f32_16x16x32_bf16 v[110:113], v[142:145], v[206:209], v[110:113]
	v_mfma_f32_16x16x32_bf16 v[98:101], v[134:137], v[214:217], v[98:101]
	v_mfma_f32_16x16x32_bf16 v[94:97], v[142:145], v[214:217], v[94:97]
	v_mfma_f32_16x16x32_bf16 v[82:85], v[134:137], v[222:225], v[82:85]
	v_mfma_f32_16x16x32_bf16 v[78:81], v[142:145], v[222:225], v[78:81]
	v_mfma_f32_16x16x32_bf16 v[130:133], v[138:141], v[202:205], v[130:133]
	v_mfma_f32_16x16x32_bf16 v[126:129], v[146:149], v[202:205], v[126:129]
	v_mfma_f32_16x16x32_bf16 v[114:117], v[138:141], v[210:213], v[114:117]
	v_mfma_f32_16x16x32_bf16 v[110:113], v[146:149], v[210:213], v[110:113]
	v_mfma_f32_16x16x32_bf16 v[98:101], v[138:141], v[218:221], v[98:101]
	v_mfma_f32_16x16x32_bf16 v[94:97], v[146:149], v[218:221], v[94:97]
	v_mfma_f32_16x16x32_bf16 v[82:85], v[138:141], v[226:229], v[82:85]
	v_mfma_f32_16x16x32_bf16 v[78:81], v[146:149], v[226:229], v[78:81]
	v_mfma_f32_16x16x32_bf16 v[122:125], v[158:161], v[192:195], v[122:125]
	v_mfma_f32_16x16x32_bf16 v[118:121], v[166:169], v[192:195], v[118:121]
	v_mfma_f32_16x16x32_bf16 v[106:109], v[158:161], v[206:209], v[106:109]
	v_mfma_f32_16x16x32_bf16 v[102:105], v[166:169], v[206:209], v[102:105]
	v_mfma_f32_16x16x32_bf16 v[90:93], v[158:161], v[214:217], v[90:93]
	v_mfma_f32_16x16x32_bf16 v[86:89], v[166:169], v[214:217], v[86:89]
	v_mfma_f32_16x16x32_bf16 v[74:77], v[158:161], v[222:225], v[74:77]
	v_mfma_f32_16x16x32_bf16 v[70:73], v[166:169], v[222:225], v[70:73]
	v_mfma_f32_16x16x32_bf16 v[122:125], v[162:165], v[202:205], v[122:125]
	v_mfma_f32_16x16x32_bf16 v[118:121], v[188:191], v[202:205], v[118:121]
	v_mfma_f32_16x16x32_bf16 v[106:109], v[162:165], v[210:213], v[106:109]
	v_mfma_f32_16x16x32_bf16 v[102:105], v[188:191], v[210:213], v[102:105]
	v_mfma_f32_16x16x32_bf16 v[90:93], v[162:165], v[218:221], v[90:93]
	v_mfma_f32_16x16x32_bf16 v[86:89], v[188:191], v[218:221], v[86:89]
	v_mfma_f32_16x16x32_bf16 v[74:77], v[162:165], v[226:229], v[74:77]
	v_mfma_f32_16x16x32_bf16 v[70:73], v[188:191], v[226:229], v[70:73]
	s_barrier
; #define PG8_STAGE(bufoff, gbase, voff) do { _Pragma("unroll") for (int _i = 0; _i < 2; ++_i) \
;         __builtin_amdgcn_global_load_lds((const unsigned*)((const char*)(gbase) + (voff)[_i]), (LAS unsigned*)(lds + (bufoff) + ldsw + _i * 8192), 16, 0, 0); } while (0)
; #define PG8_LDA(dst, b, h) do { _Pragma("unroll") for (int m = 0; m < 4; ++m) _Pragma("unroll") for (int k = 0; k < 2; ++k) dst[m][k] = *(const LAS bf16x8*)(lds + PG8_SA(b, h) + aoff + m * 2048 + k * 1024); } while (0)
; #define PG8_MMA(ai, bj, At, Bt) do { __builtin_amdgcn_s_setprio(1); _Pragma("unroll") for (int m = 0; m < 4; ++m) _Pragma("unroll") for (int n = 0; n < 2; ++n) _Pragma("unroll") for (int k = 0; k < 2; ++k) \
;         acc[ai][bj][m][n] = __builtin_amdgcn_mfma_f32_16x16x32_bf16(Bt[n][k], At[m][k], acc[ai][bj][m][n], 0, 0, 0); __builtin_amdgcn_s_setprio(0); } while (0)
; #define PG8_WAIT_V(n) asm volatile("s_waitcnt vmcnt(" #n ")" ::: "memory")
; #define PG8_WAIT_L(n) asm volatile("s_waitcnt lgkmcnt(" #n ")" ::: "memory")
; #define PG8_BAR __builtin_amdgcn_s_barrier()
; #define PG8_SCHED __builtin_amdgcn_sched_barrier(0)
; template <class Epi>
; __device__ __forceinline__ void gemm_phase(LAS unsigned char* lds, const Gemm g, const StaticOrder& S, const Epi& E) {
;     ...
;             PG8_LDA(At, 1, 1); PG8_STAGE(PG8_SB(1, 0), b3, voffB); PG8_STAGE(PG8_SB(1, 1), b3 + hstep, voffB); PG8_STAGE(PG8_SA(1, 0), a3, voffA);
;             PG8_WAIT_V(8); PG8_WAIT_L(0); PG8_BAR; PG8_MMA(1, 0, At, B0); PG8_MMA(1, 1, At, B1); PG8_BAR; PG8_SCHED;
;         }
	s_setprio 0
	s_add_i32 s54, s81, s56
	s_mov_b32 m0, s54
	ds_read_b128 v[192:195], v200 offset:49152
	ds_read_b128 v[202:205], v200 offset:50176
	ds_read_b128 v[206:209], v200 offset:51200
	ds_read_b128 v[210:213], v200 offset:52224
	ds_read_b128 v[214:217], v200 offset:53248
	ds_read_b128 v[218:221], v200 offset:54272
	ds_read_b128 v[222:225], v200 offset:55296
	ds_read_b128 v[226:229], v200 offset:56320
	global_load_lds_dwordx4 v176, s[98:99]
	s_add_i32 m0, s54, 0x2000
	s_add_u32 s52, s52, 0x40080
	s_addc_u32 s53, s53, 0
	s_add_i32 s54, s82, s56
	global_load_lds_dwordx4 v172, s[98:99]
	s_mov_b32 m0, s54
	s_nop 0
	global_load_lds_dwordx4 v176, s[52:53]
	s_add_i32 m0, s54, 0x2000
	s_nop 0
	global_load_lds_dwordx4 v172, s[52:53]
	s_mov_b32 m0, s64
	s_nop 0
	global_load_lds_dwordx4 v178, s[100:101]
	v_lshl_add_u64 v[8:9], v[234:235], 0, s[12:13]
	s_mov_b32 m0, s65
	s_nop 0
	global_load_lds_dwordx4 v174, s[100:101]
	s_waitcnt vmcnt(8)
	s_waitcnt lgkmcnt(0)
	s_setprio 1
	s_barrier
	v_mfma_f32_16x16x32_bf16 v[66:69], v[134:137], v[192:195], v[66:69]
	v_mfma_f32_16x16x32_bf16 v[62:65], v[142:145], v[192:195], v[62:65]
	v_mfma_f32_16x16x32_bf16 v[50:53], v[134:137], v[206:209], v[50:53]
	v_mfma_f32_16x16x32_bf16 v[46:49], v[142:145], v[206:209], v[46:49]
	v_mfma_f32_16x16x32_bf16 v[34:37], v[134:137], v[214:217], v[34:37]
	v_mfma_f32_16x16x32_bf16 v[30:33], v[142:145], v[214:217], v[30:33]
	v_mfma_f32_16x16x32_bf16 v[18:21], v[134:137], v[222:225], v[18:21]
	v_mfma_f32_16x16x32_bf16 v[14:17], v[142:145], v[222:225], v[14:17]
	v_mfma_f32_16x16x32_bf16 v[66:69], v[138:141], v[202:205], v[66:69]
	v_mfma_f32_16x16x32_bf16 v[62:65], v[146:149], v[202:205], v[62:65]
	v_mfma_f32_16x16x32_bf16 v[50:53], v[138:141], v[210:213], v[50:53]
	v_mfma_f32_16x16x32_bf16 v[46:49], v[146:149], v[210:213], v[46:49]
	v_mfma_f32_16x16x32_bf16 v[34:37], v[138:141], v[218:221], v[34:37]
	v_mfma_f32_16x16x32_bf16 v[30:33], v[146:149], v[218:221], v[30:33]
	v_mfma_f32_16x16x32_bf16 v[18:21], v[138:141], v[226:229], v[18:21]
	v_mfma_f32_16x16x32_bf16 v[14:17], v[146:149], v[226:229], v[14:17]
	v_mfma_f32_16x16x32_bf16 v[58:61], v[158:161], v[192:195], v[58:61]
	v_mfma_f32_16x16x32_bf16 v[54:57], v[166:169], v[192:195], v[54:57]
	v_mfma_f32_16x16x32_bf16 v[42:45], v[158:161], v[206:209], v[42:45]
	v_mfma_f32_16x16x32_bf16 v[38:41], v[166:169], v[206:209], v[38:41]
	v_mfma_f32_16x16x32_bf16 v[26:29], v[158:161], v[214:217], v[26:29]
	v_mfma_f32_16x16x32_bf16 v[22:25], v[166:169], v[214:217], v[22:25]
	v_mfma_f32_16x16x32_bf16 v[8:11], v[158:161], v[222:225], v[10:13]
	v_mfma_f32_16x16x32_bf16 v[4:7], v[166:169], v[222:225], v[4:7]
	v_mfma_f32_16x16x32_bf16 v[58:61], v[162:165], v[202:205], v[58:61]
	v_mfma_f32_16x16x32_bf16 v[54:57], v[188:191], v[202:205], v[54:57]
	v_mfma_f32_16x16x32_bf16 v[42:45], v[162:165], v[210:213], v[42:45]
	v_mfma_f32_16x16x32_bf16 v[38:41], v[188:191], v[210:213], v[38:41]
	v_mfma_f32_16x16x32_bf16 v[26:29], v[162:165], v[218:221], v[26:29]
	v_mfma_f32_16x16x32_bf16 v[22:25], v[188:191], v[218:221], v[22:25]
	v_mfma_f32_16x16x32_bf16 v[10:13], v[162:165], v[226:229], v[8:11]
	v_mfma_f32_16x16x32_bf16 v[6:9], v[188:191], v[226:229], v[4:7]
	s_barrier
	s_setprio 0
	s_add_i32 s80, s80, 2
	s_add_u32 s50, s50, 0x100
	s_addc_u32 s51, s51, 0
	s_cmp_gt_u32 s80, 13
	s_cbranch_scc1 .LBB0_703

; #define PG8_STAGE(bufoff, gbase, voff) do { _Pragma("unroll") for (int _i = 0; _i < 2; ++_i) \
;         __builtin_amdgcn_global_load_lds((const unsigned*)((const char*)(gbase) + (voff)[_i]), (LAS unsigned*)(lds + (bufoff) + ldsw + _i * 8192), 16, 0, 0); } while (0)
; #define PG8_LDA(dst, b, h) do { _Pragma("unroll") for (int m = 0; m < 4; ++m) _Pragma("unroll") for (int k = 0; k < 2; ++k) dst[m][k] = *(const LAS bf16x8*)(lds + PG8_SA(b, h) + aoff + m * 2048 + k * 1024); } while (0)
; #define PG8_LDB(dst, b, h) do { _Pragma("unroll") for (int n = 0; n < 2; ++n) _Pragma("unroll") for (int k = 0; k < 2; ++k) dst[n][k] = *(const LAS bf16x8*)(lds + PG8_SB(b, h) + boff + n * 2048 + k * 1024); } while (0)
; #define PG8_MMA(ai, bj, At, Bt) do { __builtin_amdgcn_s_setprio(1); _Pragma("unroll") for (int m = 0; m < 4; ++m) _Pragma("unroll") for (int n = 0; n < 2; ++n) _Pragma("unroll") for (int k = 0; k < 2; ++k) \
;         acc[ai][bj][m][n] = __builtin_amdgcn_mfma_f32_16x16x32_bf16(Bt[n][k], At[m][k], acc[ai][bj][m][n], 0, 0, 0); __builtin_amdgcn_s_setprio(0); } while (0)
; #define PG8_WAIT_V(n) asm volatile("s_waitcnt vmcnt(" #n ")" ::: "memory")
; #define PG8_WAIT_L(n) asm volatile("s_waitcnt lgkmcnt(" #n ")" ::: "memory")
; #define PG8_BAR __builtin_amdgcn_s_barrier()
; #define PG8_SCHED __builtin_amdgcn_sched_barrier(0)
; template <class Epi>
; __device__ __forceinline__ void gemm_phase(LAS unsigned char* lds, const Gemm g, const StaticOrder& S, const Epi& E) {
;     ...
;             PG8_LDB(B0, 0, 0); PG8_LDB(B1, 0, 1); PG8_SCHED; PG8_LDA(At, 0, 0); PG8_STAGE(PG8_SA(1, 1), a1 + hstep, voffA);
;             PG8_WAIT_V(8); PG8_WAIT_L(0); PG8_BAR; PG8_MMA(0, 0, At, B0); PG8_MMA(0, 1, At, B1); PG8_BAR; PG8_SCHED;
;             PG8_LDA(At, 0, 1); PG8_STAGE(PG8_SB(0, 0), b2, voffB); PG8_STAGE(PG8_SB(0, 1), b2 + hstep, voffB); PG8_STAGE(PG8_SA(0, 0), a2, voffA);
;             PG8_WAIT_V(8); PG8_WAIT_L(0); PG8_BAR; PG8_MMA(1, 0, At, B0); PG8_MMA(1, 1, At, B1); PG8_BAR; PG8_SCHED;
.LBB0_785:
	ds_read_b128 v[130:133], v162
	ds_read_b128 v[134:137], v162 offset:1024
	ds_read_b128 v[154:157], v162 offset:2048
	ds_read_b128 v[166:169], v162 offset:3072
	ds_read_b128 v[172:175], v163
	ds_read_b128 v[176:179], v163 offset:1024
	ds_read_b128 v[180:183], v163 offset:2048
	ds_read_b128 v[184:187], v163 offset:3072
	s_add_u32 s40, s38, 0xfffc0080
	s_addc_u32 s41, s39, -1
	s_cmp_eq_u32 s63, 12
	s_cselect_b32 s43, s21, s41
	s_cselect_b32 s42, s27, s40
	s_cselect_b32 s41, s19, s62
	s_cselect_b32 s40, s60, s61
	s_add_i32 m0, s45, 0xc000
	ds_read_b128 v[188:191], v164
	ds_read_b128 v[192:195], v164 offset:1024
	ds_read_b128 v[196:199], v164 offset:2048
	ds_read_b128 v[200:203], v164 offset:3072
	ds_read_b128 v[204:207], v164 offset:4096
	ds_read_b128 v[208:211], v164 offset:5120
	ds_read_b128 v[212:215], v164 offset:6144
	ds_read_b128 v[216:219], v164 offset:7168
	global_load_lds_dwordx4 v146, s[38:39]
	s_add_i32 m0, s45, 0xe000
	s_nop 0
	global_load_lds_dwordx4 v148, s[38:39]
	s_waitcnt vmcnt(8)
	s_waitcnt lgkmcnt(0)
	s_setprio 1
	s_barrier
	v_mfma_f32_16x16x32_bf16 v[126:129], v[130:133], v[188:191], v[126:129]
	v_mfma_f32_16x16x32_bf16 v[122:125], v[154:157], v[188:191], v[122:125]
	v_mfma_f32_16x16x32_bf16 v[110:113], v[130:133], v[196:199], v[110:113]
	v_mfma_f32_16x16x32_bf16 v[106:109], v[154:157], v[196:199], v[106:109]
	v_mfma_f32_16x16x32_bf16 v[94:97], v[130:133], v[204:207], v[94:97]
	v_mfma_f32_16x16x32_bf16 v[90:93], v[154:157], v[204:207], v[90:93]
	v_mfma_f32_16x16x32_bf16 v[78:81], v[130:133], v[212:215], v[78:81]
	v_mfma_f32_16x16x32_bf16 v[74:77], v[154:157], v[212:215], v[74:77]
	v_mfma_f32_16x16x32_bf16 v[126:129], v[134:137], v[192:195], v[126:129]
	v_mfma_f32_16x16x32_bf16 v[122:125], v[166:169], v[192:195], v[122:125]
	v_mfma_f32_16x16x32_bf16 v[110:113], v[134:137], v[200:203], v[110:113]
	v_mfma_f32_16x16x32_bf16 v[106:109], v[166:169], v[200:203], v[106:109]
	v_mfma_f32_16x16x32_bf16 v[94:97], v[134:137], v[208:211], v[94:97]
	v_mfma_f32_16x16x32_bf16 v[90:93], v[166:169], v[208:211], v[90:93]
	v_mfma_f32_16x16x32_bf16 v[78:81], v[134:137], v[216:219], v[78:81]
	v_mfma_f32_16x16x32_bf16 v[74:77], v[166:169], v[216:219], v[74:77]
	v_mfma_f32_16x16x32_bf16 v[118:121], v[172:175], v[188:191], v[118:121]
	v_mfma_f32_16x16x32_bf16 v[114:117], v[180:183], v[188:191], v[114:117]
	v_mfma_f32_16x16x32_bf16 v[102:105], v[172:175], v[196:199], v[102:105]
	v_mfma_f32_16x16x32_bf16 v[98:101], v[180:183], v[196:199], v[98:101]
	v_mfma_f32_16x16x32_bf16 v[86:89], v[172:175], v[204:207], v[86:89]
	v_mfma_f32_16x16x32_bf16 v[82:85], v[180:183], v[204:207], v[82:85]
	v_mfma_f32_16x16x32_bf16 v[70:73], v[172:175], v[212:215], v[70:73]
	v_mfma_f32_16x16x32_bf16 v[66:69], v[180:183], v[212:215], v[66:69]
	v_mfma_f32_16x16x32_bf16 v[118:121], v[176:179], v[192:195], v[118:121]
	v_mfma_f32_16x16x32_bf16 v[114:117], v[184:187], v[192:195], v[114:117]
	v_mfma_f32_16x16x32_bf16 v[102:105], v[176:179], v[200:203], v[102:105]
	v_mfma_f32_16x16x32_bf16 v[98:101], v[184:187], v[200:203], v[98:101]
	v_mfma_f32_16x16x32_bf16 v[86:89], v[176:179], v[208:211], v[86:89]
	v_mfma_f32_16x16x32_bf16 v[82:85], v[184:187], v[208:211], v[82:85]
	v_mfma_f32_16x16x32_bf16 v[70:73], v[176:179], v[216:219], v[70:73]
	v_mfma_f32_16x16x32_bf16 v[66:69], v[184:187], v[216:219], v[66:69]
	s_barrier
	s_setprio 0
	s_add_u32 s98, s40, s12
	s_addc_u32 s99, s41, s13
	s_add_u32 s100, s42, s12
	s_addc_u32 s101, s43, s13
	s_add_i32 s64, s57, s44
	s_mov_b32 m0, s64
	ds_read_b128 v[188:191], v164 offset:16384
	ds_read_b128 v[192:195], v164 offset:17408
	ds_read_b128 v[196:199], v164 offset:18432
	ds_read_b128 v[200:203], v164 offset:19456
	ds_read_b128 v[204:207], v164 offset:20480
	ds_read_b128 v[208:211], v164 offset:21504
	ds_read_b128 v[212:215], v164 offset:22528
	ds_read_b128 v[216:219], v164 offset:23552
	global_load_lds_dwordx4 v140, s[40:41]
	s_add_i32 m0, s64, 0x2000
	s_add_u32 s64, s40, 0x40000
	s_addc_u32 s65, s41, 0
	s_add_i32 s66, s58, s44
	global_load_lds_dwordx4 v144, s[40:41]
	s_mov_b32 m0, s66
	s_nop 0
	global_load_lds_dwordx4 v140, s[64:65]
	s_add_i32 m0, s66, 0x2000
	s_nop 0
	global_load_lds_dwordx4 v144, s[64:65]
	s_mov_b32 m0, s45
	s_nop 0
	global_load_lds_dwordx4 v138, s[42:43]
	s_mov_b32 m0, s46
	s_nop 0
	global_load_lds_dwordx4 v142, s[42:43]
	s_waitcnt vmcnt(8)
	s_waitcnt lgkmcnt(0)
	s_setprio 1
	s_barrier
	v_mfma_f32_16x16x32_bf16 v[62:65], v[130:133], v[188:191], v[62:65]
	v_mfma_f32_16x16x32_bf16 v[58:61], v[154:157], v[188:191], v[58:61]
	v_mfma_f32_16x16x32_bf16 v[46:49], v[130:133], v[196:199], v[46:49]
	v_mfma_f32_16x16x32_bf16 v[42:45], v[154:157], v[196:199], v[42:45]
	v_mfma_f32_16x16x32_bf16 v[30:33], v[130:133], v[204:207], v[30:33]
	v_mfma_f32_16x16x32_bf16 v[26:29], v[154:157], v[204:207], v[26:29]
	v_mfma_f32_16x16x32_bf16 v[14:17], v[130:133], v[212:215], v[14:17]
	v_mfma_f32_16x16x32_bf16 v[10:13], v[154:157], v[212:215], v[10:13]
	v_mfma_f32_16x16x32_bf16 v[62:65], v[134:137], v[192:195], v[62:65]
	v_mfma_f32_16x16x32_bf16 v[58:61], v[166:169], v[192:195], v[58:61]
	v_mfma_f32_16x16x32_bf16 v[46:49], v[134:137], v[200:203], v[46:49]
	v_mfma_f32_16x16x32_bf16 v[42:45], v[166:169], v[200:203], v[42:45]
	v_mfma_f32_16x16x32_bf16 v[30:33], v[134:137], v[208:211], v[30:33]
	v_mfma_f32_16x16x32_bf16 v[26:29], v[166:169], v[208:211], v[26:29]
	v_mfma_f32_16x16x32_bf16 v[14:17], v[134:137], v[216:219], v[14:17]
	v_mfma_f32_16x16x32_bf16 v[10:13], v[166:169], v[216:219], v[10:13]
	v_mfma_f32_16x16x32_bf16 v[54:57], v[172:175], v[188:191], v[54:57]
	v_mfma_f32_16x16x32_bf16 v[50:53], v[180:183], v[188:191], v[50:53]
	v_mfma_f32_16x16x32_bf16 v[38:41], v[172:175], v[196:199], v[38:41]
	v_mfma_f32_16x16x32_bf16 v[34:37], v[180:183], v[196:199], v[34:37]
	v_mfma_f32_16x16x32_bf16 v[22:25], v[172:175], v[204:207], v[22:25]
	v_mfma_f32_16x16x32_bf16 v[18:21], v[180:183], v[204:207], v[18:21]
	v_mfma_f32_16x16x32_bf16 v[6:9], v[172:175], v[212:215], v[6:9]
	v_mfma_f32_16x16x32_bf16 v[2:5], v[180:183], v[212:215], v[2:5]
	v_mfma_f32_16x16x32_bf16 v[54:57], v[176:179], v[192:195], v[54:57]
	v_mfma_f32_16x16x32_bf16 v[50:53], v[184:187], v[192:195], v[50:53]
	v_mfma_f32_16x16x32_bf16 v[38:41], v[176:179], v[200:203], v[38:41]
	v_mfma_f32_16x16x32_bf16 v[34:37], v[184:187], v[200:203], v[34:37]
	v_mfma_f32_16x16x32_bf16 v[22:25], v[176:179], v[208:211], v[22:25]
	v_mfma_f32_16x16x32_bf16 v[18:21], v[184:187], v[208:211], v[18:21]
	v_mfma_f32_16x16x32_bf16 v[6:9], v[176:179], v[216:219], v[6:9]
	v_mfma_f32_16x16x32_bf16 v[2:5], v[184:187], v[216:219], v[2:5]
	s_barrier
; #define PG8_STAGE(bufoff, gbase, voff) do { _Pragma("unroll") for (int _i = 0; _i < 2; ++_i) \
;         __builtin_amdgcn_global_load_lds((const unsigned*)((const char*)(gbase) + (voff)[_i]), (LAS unsigned*)(lds + (bufoff) + ldsw + _i * 8192), 16, 0, 0); } while (0)
; #define PG8_LDA(dst, b, h) do { _Pragma("unroll") for (int m = 0; m < 4; ++m) _Pragma("unroll") for (int k = 0; k < 2; ++k) dst[m][k] = *(const LAS bf16x8*)(lds + PG8_SA(b, h) + aoff + m * 2048 + k * 1024); } while (0)
; #define PG8_LDB(dst, b, h) do { _Pragma("unroll") for (int n = 0; n < 2; ++n) _Pragma("unroll") for (int k = 0; k < 2; ++k) dst[n][k] = *(const LAS bf16x8*)(lds + PG8_SB(b, h) + boff + n * 2048 + k * 1024); } while (0)
; #define PG8_MMA(ai, bj, At, Bt) do { __builtin_amdgcn_s_setprio(1); _Pragma("unroll") for (int m = 0; m < 4; ++m) _Pragma("unroll") for (int n = 0; n < 2; ++n) _Pragma("unroll") for (int k = 0; k < 2; ++k) \
;         acc[ai][bj][m][n] = __builtin_amdgcn_mfma_f32_16x16x32_bf16(Bt[n][k], At[m][k], acc[ai][bj][m][n], 0, 0, 0); __builtin_amdgcn_s_setprio(0); } while (0)
; #define PG8_WAIT_V(n) asm volatile("s_waitcnt vmcnt(" #n ")" ::: "memory")
; #define PG8_WAIT_L(n) asm volatile("s_waitcnt lgkmcnt(" #n ")" ::: "memory")
; #define PG8_BAR __builtin_amdgcn_s_barrier()
; #define PG8_SCHED __builtin_amdgcn_sched_barrier(0)
; template <class Epi>
; __device__ __forceinline__ void gemm_phase(LAS unsigned char* lds, const Gemm g, const StaticOrder& S, const Epi& E) {
;     ...
;             PG8_LDB(B0, 1, 0); PG8_LDB(B1, 1, 1); PG8_SCHED; PG8_LDA(At, 1, 0); PG8_STAGE(PG8_SA(0, 1), a2 + hstep, voffA);
;             PG8_WAIT_V(8); PG8_WAIT_L(0); PG8_BAR; PG8_MMA(0, 0, At, B0); PG8_MMA(0, 1, At, B1); PG8_BAR; PG8_SCHED;
;             PG8_LDA(At, 1, 1); PG8_STAGE(PG8_SB(1, 0), b3, voffB); PG8_STAGE(PG8_SB(1, 1), b3 + hstep, voffB); PG8_STAGE(PG8_SA(1, 0), a3, voffA);
;             PG8_WAIT_V(8); PG8_WAIT_L(0); PG8_BAR; PG8_MMA(1, 0, At, B0); PG8_MMA(1, 1, At, B1); PG8_BAR; PG8_SCHED;
;         }
;         if (wr == 0) PG8_BAR;
	s_setprio 0
	s_add_i32 s64, 0, 0x18000
	s_add_i32 s65, 0, 0x1c000
	v_add_u32_e32 v166, s64, v160
	v_add_u32_e32 v184, s65, v160
	ds_read_b128 v[130:133], v166
	ds_read_b128 v[134:137], v166 offset:1024
	ds_read_b128 v[154:157], v166 offset:2048
	ds_read_b128 v[166:169], v166 offset:3072
	ds_read_b128 v[172:175], v184
	ds_read_b128 v[176:179], v184 offset:1024
	ds_read_b128 v[180:183], v184 offset:2048
	ds_read_b128 v[184:187], v184 offset:3072
	s_add_u32 s42, s42, 0x40000
	s_addc_u32 s43, s43, 0
	s_mov_b32 m0, s47
	ds_read_b128 v[188:191], v164 offset:32768
	ds_read_b128 v[192:195], v164 offset:33792
	ds_read_b128 v[196:199], v164 offset:34816
	ds_read_b128 v[200:203], v164 offset:35840
	ds_read_b128 v[204:207], v164 offset:36864
	ds_read_b128 v[208:211], v164 offset:37888
	ds_read_b128 v[212:215], v164 offset:38912
	ds_read_b128 v[216:219], v164 offset:39936
	global_load_lds_dwordx4 v138, s[42:43]
	s_mov_b32 m0, s48
	s_nop 0
	global_load_lds_dwordx4 v142, s[42:43]
	s_waitcnt vmcnt(8)
	s_waitcnt lgkmcnt(0)
	s_setprio 1
	s_barrier
	v_mfma_f32_16x16x32_bf16 v[126:129], v[130:133], v[188:191], v[126:129]
	v_mfma_f32_16x16x32_bf16 v[122:125], v[154:157], v[188:191], v[122:125]
	v_mfma_f32_16x16x32_bf16 v[110:113], v[130:133], v[196:199], v[110:113]
	v_mfma_f32_16x16x32_bf16 v[106:109], v[154:157], v[196:199], v[106:109]
	v_mfma_f32_16x16x32_bf16 v[94:97], v[130:133], v[204:207], v[94:97]
	v_mfma_f32_16x16x32_bf16 v[90:93], v[154:157], v[204:207], v[90:93]
	v_mfma_f32_16x16x32_bf16 v[78:81], v[130:133], v[212:215], v[78:81]
	v_mfma_f32_16x16x32_bf16 v[74:77], v[154:157], v[212:215], v[74:77]
	v_mfma_f32_16x16x32_bf16 v[126:129], v[134:137], v[192:195], v[126:129]
	v_mfma_f32_16x16x32_bf16 v[122:125], v[166:169], v[192:195], v[122:125]
	v_mfma_f32_16x16x32_bf16 v[110:113], v[134:137], v[200:203], v[110:113]
	v_mfma_f32_16x16x32_bf16 v[106:109], v[166:169], v[200:203], v[106:109]
	v_mfma_f32_16x16x32_bf16 v[94:97], v[134:137], v[208:211], v[94:97]
	v_mfma_f32_16x16x32_bf16 v[90:93], v[166:169], v[208:211], v[90:93]
	v_mfma_f32_16x16x32_bf16 v[78:81], v[134:137], v[216:219], v[78:81]
	v_mfma_f32_16x16x32_bf16 v[74:77], v[166:169], v[216:219], v[74:77]
	v_mfma_f32_16x16x32_bf16 v[118:121], v[172:175], v[188:191], v[118:121]
	v_mfma_f32_16x16x32_bf16 v[114:117], v[180:183], v[188:191], v[114:117]
	v_mfma_f32_16x16x32_bf16 v[102:105], v[172:175], v[196:199], v[102:105]
	v_mfma_f32_16x16x32_bf16 v[98:101], v[180:183], v[196:199], v[98:101]
	v_mfma_f32_16x16x32_bf16 v[86:89], v[172:175], v[204:207], v[86:89]
	v_mfma_f32_16x16x32_bf16 v[82:85], v[180:183], v[204:207], v[82:85]
	v_mfma_f32_16x16x32_bf16 v[70:73], v[172:175], v[212:215], v[70:73]
	v_mfma_f32_16x16x32_bf16 v[66:69], v[180:183], v[212:215], v[66:69]
	v_mfma_f32_16x16x32_bf16 v[118:121], v[176:179], v[192:195], v[118:121]
	v_mfma_f32_16x16x32_bf16 v[114:117], v[184:187], v[192:195], v[114:117]
	v_mfma_f32_16x16x32_bf16 v[102:105], v[176:179], v[200:203], v[102:105]
	v_mfma_f32_16x16x32_bf16 v[98:101], v[184:187], v[200:203], v[98:101]
	v_mfma_f32_16x16x32_bf16 v[86:89], v[176:179], v[208:211], v[86:89]
	v_mfma_f32_16x16x32_bf16 v[82:85], v[184:187], v[208:211], v[82:85]
	v_mfma_f32_16x16x32_bf16 v[70:73], v[176:179], v[216:219], v[70:73]
	v_mfma_f32_16x16x32_bf16 v[66:69], v[184:187], v[216:219], v[66:69]
	s_barrier
	s_setprio 0
	s_add_i32 s42, s64, s44
	s_mov_b32 m0, s42
	ds_read_b128 v[188:191], v164 offset:49152
	ds_read_b128 v[192:195], v164 offset:50176
	ds_read_b128 v[196:199], v164 offset:51200
	ds_read_b128 v[200:203], v164 offset:52224
	ds_read_b128 v[204:207], v164 offset:53248
	ds_read_b128 v[208:211], v164 offset:54272
	ds_read_b128 v[212:215], v164 offset:55296
	ds_read_b128 v[216:219], v164 offset:56320
	global_load_lds_dwordx4 v140, s[98:99]
	s_add_i32 m0, s42, 0x2000
	s_add_u32 s40, s40, 0x40080
	s_addc_u32 s41, s41, 0
	s_add_i32 s42, s65, s44
	global_load_lds_dwordx4 v144, s[98:99]
	s_mov_b32 m0, s42
	s_nop 0
	global_load_lds_dwordx4 v140, s[40:41]
	s_add_i32 m0, s42, 0x2000
	s_nop 0
	global_load_lds_dwordx4 v144, s[40:41]
	s_mov_b32 m0, s50
	s_nop 0
	global_load_lds_dwordx4 v138, s[100:101]
	s_mov_b32 m0, s51
	s_nop 0
	global_load_lds_dwordx4 v142, s[100:101]
	s_waitcnt vmcnt(8)
	s_waitcnt lgkmcnt(0)
	s_setprio 1
	s_barrier
	v_mfma_f32_16x16x32_bf16 v[62:65], v[130:133], v[188:191], v[62:65]
	v_mfma_f32_16x16x32_bf16 v[58:61], v[154:157], v[188:191], v[58:61]
	v_mfma_f32_16x16x32_bf16 v[46:49], v[130:133], v[196:199], v[46:49]
	v_mfma_f32_16x16x32_bf16 v[42:45], v[154:157], v[196:199], v[42:45]
	v_mfma_f32_16x16x32_bf16 v[30:33], v[130:133], v[204:207], v[30:33]
	v_mfma_f32_16x16x32_bf16 v[26:29], v[154:157], v[204:207], v[26:29]
	v_mfma_f32_16x16x32_bf16 v[14:17], v[130:133], v[212:215], v[14:17]
	v_mfma_f32_16x16x32_bf16 v[10:13], v[154:157], v[212:215], v[10:13]
	v_mfma_f32_16x16x32_bf16 v[62:65], v[134:137], v[192:195], v[62:65]
	v_mfma_f32_16x16x32_bf16 v[58:61], v[166:169], v[192:195], v[58:61]
	v_mfma_f32_16x16x32_bf16 v[46:49], v[134:137], v[200:203], v[46:49]
	v_mfma_f32_16x16x32_bf16 v[42:45], v[166:169], v[200:203], v[42:45]
	v_mfma_f32_16x16x32_bf16 v[30:33], v[134:137], v[208:211], v[30:33]
	v_mfma_f32_16x16x32_bf16 v[26:29], v[166:169], v[208:211], v[26:29]
	v_mfma_f32_16x16x32_bf16 v[14:17], v[134:137], v[216:219], v[14:17]
	v_mfma_f32_16x16x32_bf16 v[10:13], v[166:169], v[216:219], v[10:13]
	v_mfma_f32_16x16x32_bf16 v[54:57], v[172:175], v[188:191], v[54:57]
	v_mfma_f32_16x16x32_bf16 v[50:53], v[180:183], v[188:191], v[50:53]
	v_mfma_f32_16x16x32_bf16 v[38:41], v[172:175], v[196:199], v[38:41]
	v_mfma_f32_16x16x32_bf16 v[34:37], v[180:183], v[196:199], v[34:37]
	v_mfma_f32_16x16x32_bf16 v[22:25], v[172:175], v[204:207], v[22:25]
	v_mfma_f32_16x16x32_bf16 v[18:21], v[180:183], v[204:207], v[18:21]
	v_mfma_f32_16x16x32_bf16 v[6:9], v[172:175], v[212:215], v[6:9]
	v_mfma_f32_16x16x32_bf16 v[2:5], v[180:183], v[212:215], v[2:5]
	v_mfma_f32_16x16x32_bf16 v[54:57], v[176:179], v[192:195], v[54:57]
	v_mfma_f32_16x16x32_bf16 v[50:53], v[184:187], v[192:195], v[50:53]
	v_mfma_f32_16x16x32_bf16 v[38:41], v[176:179], v[200:203], v[38:41]
	v_mfma_f32_16x16x32_bf16 v[34:37], v[184:187], v[200:203], v[34:37]
	v_mfma_f32_16x16x32_bf16 v[22:25], v[176:179], v[208:211], v[22:25]
	v_mfma_f32_16x16x32_bf16 v[18:21], v[184:187], v[208:211], v[18:21]
	v_mfma_f32_16x16x32_bf16 v[6:9], v[176:179], v[216:219], v[6:9]
	v_mfma_f32_16x16x32_bf16 v[2:5], v[184:187], v[216:219], v[2:5]
	s_barrier
	s_setprio 0
	s_add_i32 s63, s63, 2
	s_add_u32 s38, s38, 0x100
	s_addc_u32 s39, s39, 0
	s_add_u32 s61, s61, 0x100
	s_addc_u32 s62, s62, 0
	s_cmp_gt_u32 s63, 13
	s_cbranch_scc0 .LBB0_785
	s_and_b64 vcc, exec, s[14:15]
	s_cbranch_vccz .LBB0_788
	s_barrier

; #define PG8_STAGE(bufoff, gbase, voff) do { _Pragma("unroll") for (int _i = 0; _i < 2; ++_i) \
;         __builtin_amdgcn_global_load_lds((const unsigned*)((const char*)(gbase) + (voff)[_i]), (LAS unsigned*)(lds + (bufoff) + ldsw + _i * 8192), 16, 0, 0); } while (0)
; #define PG8_LDA(dst, b, h) do { _Pragma("unroll") for (int m = 0; m < 4; ++m) _Pragma("unroll") for (int k = 0; k < 2; ++k) dst[m][k] = *(const LAS bf16x8*)(lds + PG8_SA(b, h) + aoff + m * 2048 + k * 1024); } while (0)
; #define PG8_LDB(dst, b, h) do { _Pragma("unroll") for (int n = 0; n < 2; ++n) _Pragma("unroll") for (int k = 0; k < 2; ++k) dst[n][k] = *(const LAS bf16x8*)(lds + PG8_SB(b, h) + boff + n * 2048 + k * 1024); } while (0)
; #define PG8_MMA(ai, bj, At, Bt) do { __builtin_amdgcn_s_setprio(1); _Pragma("unroll") for (int m = 0; m < 4; ++m) _Pragma("unroll") for (int n = 0; n < 2; ++n) _Pragma("unroll") for (int k = 0; k < 2; ++k) \
;         acc[ai][bj][m][n] = __builtin_amdgcn_mfma_f32_16x16x32_bf16(Bt[n][k], At[m][k], acc[ai][bj][m][n], 0, 0, 0); __builtin_amdgcn_s_setprio(0); } while (0)
; #define PG8_WAIT_V(n) asm volatile("s_waitcnt vmcnt(" #n ")" ::: "memory")
; #define PG8_WAIT_L(n) asm volatile("s_waitcnt lgkmcnt(" #n ")" ::: "memory")
; #define PG8_BAR __builtin_amdgcn_s_barrier()
; template <class Epi>
; __device__ __forceinline__ void gemm_phase(LAS unsigned char* lds, const Gemm g, const StaticOrder& S, const Epi& E) {
;     ...
;             const bool last = (t == nt - 2);
;             const char* a1 = cA + (size_t)(t + 1) * kstep;
;             const char* a2 = last ? nA : cA + (size_t)(t + 2) * kstep; const char* b2 = last ? nB : cB + (size_t)(t + 2) * kstep;
;             const char* a3 = a2 + kstep; const char* b3 = b2 + kstep;
;             if constexpr (Epi::MIDK > 0) { if (t == Epi::MIDK) E.mid(acc, cur, wr, wc, fr, fq); }
;             PG8_LDB(B0, 0, 0); PG8_LDB(B1, 0, 1); PG8_SCHED; PG8_LDA(At, 0, 0); PG8_STAGE(PG8_SA(1, 1), a1 + hstep, voffA);
;             PG8_WAIT_V(8); PG8_WAIT_L(0); PG8_BAR; PG8_MMA(0, 0, At, B0); PG8_MMA(0, 1, At, B1); PG8_BAR; PG8_SCHED;
;             PG8_LDA(At, 0, 1); PG8_STAGE(PG8_SB(0, 0), b2, voffB); PG8_STAGE(PG8_SB(0, 1), b2 + hstep, voffB); PG8_STAGE(PG8_SA(0, 0), a2, voffA);
;             PG8_WAIT_V(8); PG8_WAIT_L(0); PG8_BAR; PG8_MMA(1, 0, At, B0); PG8_MMA(1, 1, At, B1); PG8_BAR; PG8_SCHED;
.LBB0_884:
	ds_read_b128 v[156:159], v150
	ds_read_b128 v[160:163], v150 offset:1024
	ds_read_b128 v[164:167], v150 offset:2048
	ds_read_b128 v[172:175], v150 offset:3072
	ds_read_b128 v[176:179], v151
	ds_read_b128 v[180:183], v151 offset:1024
	ds_read_b128 v[184:187], v151 offset:2048
	ds_read_b128 v[188:191], v151 offset:3072
	s_add_u32 s46, s44, 0xfffc0080
	s_addc_u32 s47, s45, -1
	s_cmp_eq_u32 s67, 12
	s_cselect_b32 s49, s62, s47
	s_cselect_b32 s48, s63, s46
	s_cselect_b32 s47, s23, s66
	s_cselect_b32 s46, s64, s65
	s_add_i32 m0, s41, 0xc000
	ds_read_b128 v[192:195], v152
	ds_read_b128 v[196:199], v152 offset:1024
	ds_read_b128 v[200:203], v152 offset:2048
	ds_read_b128 v[204:207], v152 offset:3072
	ds_read_b128 v[208:211], v152 offset:4096
	ds_read_b128 v[212:215], v152 offset:5120
	ds_read_b128 v[216:219], v152 offset:6144
	ds_read_b128 v[220:223], v152 offset:7168
	global_load_lds_dwordx4 v140, s[44:45]
	s_add_i32 m0, s41, 0xe000
	s_nop 0
	global_load_lds_dwordx4 v142, s[44:45]
	s_waitcnt vmcnt(8)
	s_waitcnt lgkmcnt(0)
	s_setprio 1
	s_barrier
	v_mfma_f32_16x16x32_bf16 v[126:129], v[156:159], v[192:195], v[126:129]
	v_mfma_f32_16x16x32_bf16 v[118:121], v[164:167], v[192:195], v[118:121]
	v_mfma_f32_16x16x32_bf16 v[110:113], v[156:159], v[200:203], v[110:113]
	v_mfma_f32_16x16x32_bf16 v[102:105], v[164:167], v[200:203], v[102:105]
	v_mfma_f32_16x16x32_bf16 v[94:97], v[156:159], v[208:211], v[94:97]
	v_mfma_f32_16x16x32_bf16 v[86:89], v[164:167], v[208:211], v[86:89]
	v_mfma_f32_16x16x32_bf16 v[78:81], v[156:159], v[216:219], v[78:81]
	v_mfma_f32_16x16x32_bf16 v[70:73], v[164:167], v[216:219], v[70:73]
	v_mfma_f32_16x16x32_bf16 v[126:129], v[160:163], v[196:199], v[126:129]
	v_mfma_f32_16x16x32_bf16 v[118:121], v[172:175], v[196:199], v[118:121]
	v_mfma_f32_16x16x32_bf16 v[110:113], v[160:163], v[204:207], v[110:113]
	v_mfma_f32_16x16x32_bf16 v[102:105], v[172:175], v[204:207], v[102:105]
	v_mfma_f32_16x16x32_bf16 v[94:97], v[160:163], v[212:215], v[94:97]
	v_mfma_f32_16x16x32_bf16 v[86:89], v[172:175], v[212:215], v[86:89]
	v_mfma_f32_16x16x32_bf16 v[78:81], v[160:163], v[220:223], v[78:81]
	v_mfma_f32_16x16x32_bf16 v[70:73], v[172:175], v[220:223], v[70:73]
	v_mfma_f32_16x16x32_bf16 v[122:125], v[176:179], v[192:195], v[122:125]
	v_mfma_f32_16x16x32_bf16 v[114:117], v[184:187], v[192:195], v[114:117]
	v_mfma_f32_16x16x32_bf16 v[106:109], v[176:179], v[200:203], v[106:109]
	v_mfma_f32_16x16x32_bf16 v[98:101], v[184:187], v[200:203], v[98:101]
	v_mfma_f32_16x16x32_bf16 v[90:93], v[176:179], v[208:211], v[90:93]
	v_mfma_f32_16x16x32_bf16 v[82:85], v[184:187], v[208:211], v[82:85]
	v_mfma_f32_16x16x32_bf16 v[74:77], v[176:179], v[216:219], v[74:77]
	v_mfma_f32_16x16x32_bf16 v[66:69], v[184:187], v[216:219], v[66:69]
	v_mfma_f32_16x16x32_bf16 v[122:125], v[180:183], v[196:199], v[122:125]
	v_mfma_f32_16x16x32_bf16 v[114:117], v[188:191], v[196:199], v[114:117]
	v_mfma_f32_16x16x32_bf16 v[106:109], v[180:183], v[204:207], v[106:109]
	v_mfma_f32_16x16x32_bf16 v[98:101], v[188:191], v[204:207], v[98:101]
	v_mfma_f32_16x16x32_bf16 v[90:93], v[180:183], v[212:215], v[90:93]
	v_mfma_f32_16x16x32_bf16 v[82:85], v[188:191], v[212:215], v[82:85]
	v_mfma_f32_16x16x32_bf16 v[74:77], v[180:183], v[220:223], v[74:77]
	v_mfma_f32_16x16x32_bf16 v[66:69], v[188:191], v[220:223], v[66:69]
	s_barrier
	s_setprio 0
	s_add_u32 s98, s46, s8
	s_addc_u32 s99, s47, s9
	s_add_u32 s100, s48, s8
	s_addc_u32 s101, s49, s9
	s_add_i32 s68, s58, s6
	s_mov_b32 m0, s68
	ds_read_b128 v[192:195], v152 offset:16384
	ds_read_b128 v[196:199], v152 offset:17408
	ds_read_b128 v[200:203], v152 offset:18432
	ds_read_b128 v[204:207], v152 offset:19456
	ds_read_b128 v[208:211], v152 offset:20480
	ds_read_b128 v[212:215], v152 offset:21504
	ds_read_b128 v[216:219], v152 offset:22528
	ds_read_b128 v[220:223], v152 offset:23552
	global_load_lds_dwordx4 v132, s[46:47]
	s_add_i32 m0, s68, 0x2000
	s_add_u32 s68, s46, 0x40000
	s_addc_u32 s69, s47, 0
	s_add_i32 s76, s59, s6
	global_load_lds_dwordx4 v136, s[46:47]
	s_mov_b32 m0, s76
	s_nop 0
	global_load_lds_dwordx4 v132, s[68:69]
	s_add_i32 m0, s76, 0x2000
	s_nop 0
	global_load_lds_dwordx4 v136, s[68:69]
	s_mov_b32 m0, s41
	s_nop 0
	global_load_lds_dwordx4 v130, s[48:49]
	s_mov_b32 m0, s43
	s_nop 0
	global_load_lds_dwordx4 v134, s[48:49]
	s_waitcnt vmcnt(8)
	s_waitcnt lgkmcnt(0)
	s_setprio 1
	s_barrier
	v_mfma_f32_16x16x32_bf16 v[62:65], v[156:159], v[192:195], v[62:65]
	v_mfma_f32_16x16x32_bf16 v[54:57], v[164:167], v[192:195], v[54:57]
	v_mfma_f32_16x16x32_bf16 v[46:49], v[156:159], v[200:203], v[46:49]
	v_mfma_f32_16x16x32_bf16 v[38:41], v[164:167], v[200:203], v[38:41]
	v_mfma_f32_16x16x32_bf16 v[30:33], v[156:159], v[208:211], v[30:33]
	v_mfma_f32_16x16x32_bf16 v[22:25], v[164:167], v[208:211], v[22:25]
	v_mfma_f32_16x16x32_bf16 v[14:17], v[156:159], v[216:219], v[14:17]
	v_mfma_f32_16x16x32_bf16 v[6:9], v[164:167], v[216:219], v[6:9]
	v_mfma_f32_16x16x32_bf16 v[62:65], v[160:163], v[196:199], v[62:65]
	v_mfma_f32_16x16x32_bf16 v[54:57], v[172:175], v[196:199], v[54:57]
	v_mfma_f32_16x16x32_bf16 v[46:49], v[160:163], v[204:207], v[46:49]
	v_mfma_f32_16x16x32_bf16 v[38:41], v[172:175], v[204:207], v[38:41]
	v_mfma_f32_16x16x32_bf16 v[30:33], v[160:163], v[212:215], v[30:33]
	v_mfma_f32_16x16x32_bf16 v[22:25], v[172:175], v[212:215], v[22:25]
	v_mfma_f32_16x16x32_bf16 v[14:17], v[160:163], v[220:223], v[14:17]
	v_mfma_f32_16x16x32_bf16 v[6:9], v[172:175], v[220:223], v[6:9]
	v_mfma_f32_16x16x32_bf16 v[58:61], v[176:179], v[192:195], v[58:61]
	v_mfma_f32_16x16x32_bf16 v[50:53], v[184:187], v[192:195], v[50:53]
	v_mfma_f32_16x16x32_bf16 v[42:45], v[176:179], v[200:203], v[42:45]
	v_mfma_f32_16x16x32_bf16 v[34:37], v[184:187], v[200:203], v[34:37]
	v_mfma_f32_16x16x32_bf16 v[26:29], v[176:179], v[208:211], v[26:29]
	v_mfma_f32_16x16x32_bf16 v[18:21], v[184:187], v[208:211], v[18:21]
	v_mfma_f32_16x16x32_bf16 v[10:13], v[176:179], v[216:219], v[10:13]
	v_mfma_f32_16x16x32_bf16 v[2:5], v[184:187], v[216:219], v[2:5]
	v_mfma_f32_16x16x32_bf16 v[58:61], v[180:183], v[196:199], v[58:61]
	v_mfma_f32_16x16x32_bf16 v[50:53], v[188:191], v[196:199], v[50:53]
	v_mfma_f32_16x16x32_bf16 v[42:45], v[180:183], v[204:207], v[42:45]
	v_mfma_f32_16x16x32_bf16 v[34:37], v[188:191], v[204:207], v[34:37]
	v_mfma_f32_16x16x32_bf16 v[26:29], v[180:183], v[212:215], v[26:29]
	v_mfma_f32_16x16x32_bf16 v[18:21], v[188:191], v[212:215], v[18:21]
	v_mfma_f32_16x16x32_bf16 v[10:13], v[180:183], v[220:223], v[10:13]
	v_mfma_f32_16x16x32_bf16 v[2:5], v[188:191], v[220:223], v[2:5]
	s_barrier
; #define PG8_STAGE(bufoff, gbase, voff) do { _Pragma("unroll") for (int _i = 0; _i < 2; ++_i) \
;         __builtin_amdgcn_global_load_lds((const unsigned*)((const char*)(gbase) + (voff)[_i]), (LAS unsigned*)(lds + (bufoff) + ldsw + _i * 8192), 16, 0, 0); } while (0)
; #define PG8_LDA(dst, b, h) do { _Pragma("unroll") for (int m = 0; m < 4; ++m) _Pragma("unroll") for (int k = 0; k < 2; ++k) dst[m][k] = *(const LAS bf16x8*)(lds + PG8_SA(b, h) + aoff + m * 2048 + k * 1024); } while (0)
; #define PG8_LDB(dst, b, h) do { _Pragma("unroll") for (int n = 0; n < 2; ++n) _Pragma("unroll") for (int k = 0; k < 2; ++k) dst[n][k] = *(const LAS bf16x8*)(lds + PG8_SB(b, h) + boff + n * 2048 + k * 1024); } while (0)
; #define PG8_MMA(ai, bj, At, Bt) do { __builtin_amdgcn_s_setprio(1); _Pragma("unroll") for (int m = 0; m < 4; ++m) _Pragma("unroll") for (int n = 0; n < 2; ++n) _Pragma("unroll") for (int k = 0; k < 2; ++k) \
;         acc[ai][bj][m][n] = __builtin_amdgcn_mfma_f32_16x16x32_bf16(Bt[n][k], At[m][k], acc[ai][bj][m][n], 0, 0, 0); __builtin_amdgcn_s_setprio(0); } while (0)
; #define PG8_WAIT_V(n) asm volatile("s_waitcnt vmcnt(" #n ")" ::: "memory")
; #define PG8_WAIT_L(n) asm volatile("s_waitcnt lgkmcnt(" #n ")" ::: "memory")
; #define PG8_BAR __builtin_amdgcn_s_barrier()
; #define PG8_SCHED __builtin_amdgcn_sched_barrier(0)
; template <class Epi>
; __device__ __forceinline__ void gemm_phase(LAS unsigned char* lds, const Gemm g, const StaticOrder& S, const Epi& E) {
;     ...
;             PG8_LDB(B0, 1, 0); PG8_LDB(B1, 1, 1); PG8_SCHED; PG8_LDA(At, 1, 0); PG8_STAGE(PG8_SA(0, 1), a2 + hstep, voffA);
;             PG8_WAIT_V(8); PG8_WAIT_L(0); PG8_BAR; PG8_MMA(0, 0, At, B0); PG8_MMA(0, 1, At, B1); PG8_BAR; PG8_SCHED;
;             PG8_LDA(At, 1, 1); PG8_STAGE(PG8_SB(1, 0), b3, voffB); PG8_STAGE(PG8_SB(1, 1), b3 + hstep, voffB); PG8_STAGE(PG8_SA(1, 0), a3, voffA);
;             PG8_WAIT_V(8); PG8_WAIT_L(0); PG8_BAR; PG8_MMA(1, 0, At, B0); PG8_MMA(1, 1, At, B1); PG8_BAR; PG8_SCHED;
;         }
	s_setprio 0
	s_add_i32 s68, 0, 0x18000
	s_add_i32 s69, 0, 0x1c000
	v_add_u32_e32 v172, s68, v148
	v_add_u32_e32 v188, s69, v148
	ds_read_b128 v[156:159], v172
	ds_read_b128 v[160:163], v172 offset:1024
	ds_read_b128 v[164:167], v172 offset:2048
	ds_read_b128 v[172:175], v172 offset:3072
	ds_read_b128 v[176:179], v188
	ds_read_b128 v[180:183], v188 offset:1024
	ds_read_b128 v[184:187], v188 offset:2048
	ds_read_b128 v[188:191], v188 offset:3072
	s_add_u32 s48, s48, 0x40000
	s_addc_u32 s49, s49, 0
	s_mov_b32 m0, s51
	ds_read_b128 v[192:195], v152 offset:32768
	ds_read_b128 v[196:199], v152 offset:33792
	ds_read_b128 v[200:203], v152 offset:34816
	ds_read_b128 v[204:207], v152 offset:35840
	ds_read_b128 v[208:211], v152 offset:36864
	ds_read_b128 v[212:215], v152 offset:37888
	ds_read_b128 v[216:219], v152 offset:38912
	ds_read_b128 v[220:223], v152 offset:39936
	global_load_lds_dwordx4 v130, s[48:49]
	s_mov_b32 m0, s52
	s_nop 0
	global_load_lds_dwordx4 v134, s[48:49]
	s_waitcnt vmcnt(8)
	s_waitcnt lgkmcnt(0)
	s_setprio 1
	s_barrier
	v_mfma_f32_16x16x32_bf16 v[126:129], v[156:159], v[192:195], v[126:129]
	v_mfma_f32_16x16x32_bf16 v[118:121], v[164:167], v[192:195], v[118:121]
	v_mfma_f32_16x16x32_bf16 v[110:113], v[156:159], v[200:203], v[110:113]
	v_mfma_f32_16x16x32_bf16 v[102:105], v[164:167], v[200:203], v[102:105]
	v_mfma_f32_16x16x32_bf16 v[94:97], v[156:159], v[208:211], v[94:97]
	v_mfma_f32_16x16x32_bf16 v[86:89], v[164:167], v[208:211], v[86:89]
	v_mfma_f32_16x16x32_bf16 v[78:81], v[156:159], v[216:219], v[78:81]
	v_mfma_f32_16x16x32_bf16 v[70:73], v[164:167], v[216:219], v[70:73]
	v_mfma_f32_16x16x32_bf16 v[126:129], v[160:163], v[196:199], v[126:129]
	v_mfma_f32_16x16x32_bf16 v[118:121], v[172:175], v[196:199], v[118:121]
	v_mfma_f32_16x16x32_bf16 v[110:113], v[160:163], v[204:207], v[110:113]
	v_mfma_f32_16x16x32_bf16 v[102:105], v[172:175], v[204:207], v[102:105]
	v_mfma_f32_16x16x32_bf16 v[94:97], v[160:163], v[212:215], v[94:97]
	v_mfma_f32_16x16x32_bf16 v[86:89], v[172:175], v[212:215], v[86:89]
	v_mfma_f32_16x16x32_bf16 v[78:81], v[160:163], v[220:223], v[78:81]
	v_mfma_f32_16x16x32_bf16 v[70:73], v[172:175], v[220:223], v[70:73]
	v_mfma_f32_16x16x32_bf16 v[122:125], v[176:179], v[192:195], v[122:125]
	v_mfma_f32_16x16x32_bf16 v[114:117], v[184:187], v[192:195], v[114:117]
	v_mfma_f32_16x16x32_bf16 v[106:109], v[176:179], v[200:203], v[106:109]
	v_mfma_f32_16x16x32_bf16 v[98:101], v[184:187], v[200:203], v[98:101]
	v_mfma_f32_16x16x32_bf16 v[90:93], v[176:179], v[208:211], v[90:93]
	v_mfma_f32_16x16x32_bf16 v[82:85], v[184:187], v[208:211], v[82:85]
	v_mfma_f32_16x16x32_bf16 v[74:77], v[176:179], v[216:219], v[74:77]
	v_mfma_f32_16x16x32_bf16 v[66:69], v[184:187], v[216:219], v[66:69]
	v_mfma_f32_16x16x32_bf16 v[122:125], v[180:183], v[196:199], v[122:125]
	v_mfma_f32_16x16x32_bf16 v[114:117], v[188:191], v[196:199], v[114:117]
	v_mfma_f32_16x16x32_bf16 v[106:109], v[180:183], v[204:207], v[106:109]
	v_mfma_f32_16x16x32_bf16 v[98:101], v[188:191], v[204:207], v[98:101]
	v_mfma_f32_16x16x32_bf16 v[90:93], v[180:183], v[212:215], v[90:93]
	v_mfma_f32_16x16x32_bf16 v[82:85], v[188:191], v[212:215], v[82:85]
	v_mfma_f32_16x16x32_bf16 v[74:77], v[180:183], v[220:223], v[74:77]
	v_mfma_f32_16x16x32_bf16 v[66:69], v[188:191], v[220:223], v[66:69]
	s_barrier
	s_setprio 0
	s_add_i32 s48, s68, s6
	s_mov_b32 m0, s48
	ds_read_b128 v[192:195], v152 offset:49152
	ds_read_b128 v[196:199], v152 offset:50176
	ds_read_b128 v[200:203], v152 offset:51200
	ds_read_b128 v[204:207], v152 offset:52224
	ds_read_b128 v[208:211], v152 offset:53248
	ds_read_b128 v[212:215], v152 offset:54272
	ds_read_b128 v[216:219], v152 offset:55296
	ds_read_b128 v[220:223], v152 offset:56320
	global_load_lds_dwordx4 v132, s[98:99]
	s_add_i32 m0, s48, 0x2000
	s_add_u32 s46, s46, 0x40080
	s_addc_u32 s47, s47, 0
	s_add_i32 s48, s69, s6
	global_load_lds_dwordx4 v136, s[98:99]
	s_mov_b32 m0, s48
	s_nop 0
	global_load_lds_dwordx4 v132, s[46:47]
	s_add_i32 m0, s48, 0x2000
	s_nop 0
	global_load_lds_dwordx4 v136, s[46:47]
	s_mov_b32 m0, s53
	s_nop 0
	global_load_lds_dwordx4 v130, s[100:101]
	s_mov_b32 m0, s54
	s_nop 0
	global_load_lds_dwordx4 v134, s[100:101]
	s_waitcnt vmcnt(8)
	s_waitcnt lgkmcnt(0)
	s_setprio 1
	s_barrier
	v_mfma_f32_16x16x32_bf16 v[62:65], v[156:159], v[192:195], v[62:65]
	v_mfma_f32_16x16x32_bf16 v[54:57], v[164:167], v[192:195], v[54:57]
	v_mfma_f32_16x16x32_bf16 v[46:49], v[156:159], v[200:203], v[46:49]
	v_mfma_f32_16x16x32_bf16 v[38:41], v[164:167], v[200:203], v[38:41]
	v_mfma_f32_16x16x32_bf16 v[30:33], v[156:159], v[208:211], v[30:33]
	v_mfma_f32_16x16x32_bf16 v[22:25], v[164:167], v[208:211], v[22:25]
	v_mfma_f32_16x16x32_bf16 v[14:17], v[156:159], v[216:219], v[14:17]
	v_mfma_f32_16x16x32_bf16 v[6:9], v[164:167], v[216:219], v[6:9]
	v_mfma_f32_16x16x32_bf16 v[62:65], v[160:163], v[196:199], v[62:65]
	v_mfma_f32_16x16x32_bf16 v[54:57], v[172:175], v[196:199], v[54:57]
	v_mfma_f32_16x16x32_bf16 v[46:49], v[160:163], v[204:207], v[46:49]
	v_mfma_f32_16x16x32_bf16 v[38:41], v[172:175], v[204:207], v[38:41]
	v_mfma_f32_16x16x32_bf16 v[30:33], v[160:163], v[212:215], v[30:33]
	v_mfma_f32_16x16x32_bf16 v[22:25], v[172:175], v[212:215], v[22:25]
	v_mfma_f32_16x16x32_bf16 v[14:17], v[160:163], v[220:223], v[14:17]
	v_mfma_f32_16x16x32_bf16 v[6:9], v[172:175], v[220:223], v[6:9]
	v_mfma_f32_16x16x32_bf16 v[58:61], v[176:179], v[192:195], v[58:61]
	v_mfma_f32_16x16x32_bf16 v[50:53], v[184:187], v[192:195], v[50:53]
	v_mfma_f32_16x16x32_bf16 v[42:45], v[176:179], v[200:203], v[42:45]
	v_mfma_f32_16x16x32_bf16 v[34:37], v[184:187], v[200:203], v[34:37]
	v_mfma_f32_16x16x32_bf16 v[26:29], v[176:179], v[208:211], v[26:29]
	v_mfma_f32_16x16x32_bf16 v[18:21], v[184:187], v[208:211], v[18:21]
	v_mfma_f32_16x16x32_bf16 v[10:13], v[176:179], v[216:219], v[10:13]
	v_mfma_f32_16x16x32_bf16 v[2:5], v[184:187], v[216:219], v[2:5]
	v_mfma_f32_16x16x32_bf16 v[58:61], v[180:183], v[196:199], v[58:61]
	v_mfma_f32_16x16x32_bf16 v[50:53], v[188:191], v[196:199], v[50:53]
	v_mfma_f32_16x16x32_bf16 v[42:45], v[180:183], v[204:207], v[42:45]
	v_mfma_f32_16x16x32_bf16 v[34:37], v[188:191], v[204:207], v[34:37]
	v_mfma_f32_16x16x32_bf16 v[26:29], v[180:183], v[212:215], v[26:29]
	v_mfma_f32_16x16x32_bf16 v[18:21], v[188:191], v[212:215], v[18:21]
	v_mfma_f32_16x16x32_bf16 v[10:13], v[180:183], v[220:223], v[10:13]
	v_mfma_f32_16x16x32_bf16 v[2:5], v[188:191], v[220:223], v[2:5]
	s_barrier
	s_setprio 0
	s_add_i32 s67, s67, 2
	s_add_u32 s44, s44, 0x100
	s_addc_u32 s45, s45, 0
	s_add_u32 s65, s65, 0x100
	s_addc_u32 s66, s66, 0
	s_cmp_gt_u32 s67, 13
	s_cbranch_scc0 .LBB0_884
	s_and_b64 vcc, exec, s[14:15]
	s_cbranch_vccz .LBB0_887
	s_barrier

; #define PG8_STAGE(bufoff, gbase, voff) do { _Pragma("unroll") for (int _i = 0; _i < 2; ++_i) \
;         __builtin_amdgcn_global_load_lds((const unsigned*)((const char*)(gbase) + (voff)[_i]), (LAS unsigned*)(lds + (bufoff) + ldsw + _i * 8192), 16, 0, 0); } while (0)
; #define PG8_LDA(dst, b, h) do { _Pragma("unroll") for (int m = 0; m < 4; ++m) _Pragma("unroll") for (int k = 0; k < 2; ++k) dst[m][k] = *(const LAS bf16x8*)(lds + PG8_SA(b, h) + aoff + m * 2048 + k * 1024); } while (0)
; #define PG8_LDB(dst, b, h) do { _Pragma("unroll") for (int n = 0; n < 2; ++n) _Pragma("unroll") for (int k = 0; k < 2; ++k) dst[n][k] = *(const LAS bf16x8*)(lds + PG8_SB(b, h) + boff + n * 2048 + k * 1024); } while (0)
; #define PG8_MMA(ai, bj, At, Bt) do { __builtin_amdgcn_s_setprio(1); _Pragma("unroll") for (int m = 0; m < 4; ++m) _Pragma("unroll") for (int n = 0; n < 2; ++n) _Pragma("unroll") for (int k = 0; k < 2; ++k) \
;         acc[ai][bj][m][n] = __builtin_amdgcn_mfma_f32_16x16x32_bf16(Bt[n][k], At[m][k], acc[ai][bj][m][n], 0, 0, 0); __builtin_amdgcn_s_setprio(0); } while (0)
; #define PG8_WAIT_V(n) asm volatile("s_waitcnt vmcnt(" #n ")" ::: "memory")
; #define PG8_WAIT_L(n) asm volatile("s_waitcnt lgkmcnt(" #n ")" ::: "memory")
; #define PG8_BAR __builtin_amdgcn_s_barrier()
; template <class Epi>
; __device__ __forceinline__ void gemm_phase(LAS unsigned char* lds, const Gemm g, const StaticOrder& S, const Epi& E) {
;     ...
;             const bool last = (t == nt - 2);
;             const char* a1 = cA + (size_t)(t + 1) * kstep;
;             const char* a2 = last ? nA : cA + (size_t)(t + 2) * kstep; const char* b2 = last ? nB : cB + (size_t)(t + 2) * kstep;
;             const char* a3 = a2 + kstep; const char* b3 = b2 + kstep;
;             if constexpr (Epi::MIDK > 0) { if (t == Epi::MIDK) E.mid(acc, cur, wr, wc, fr, fq); }
;             PG8_LDB(B0, 0, 0); PG8_LDB(B1, 0, 1); PG8_SCHED; PG8_LDA(At, 0, 0); PG8_STAGE(PG8_SA(1, 1), a1 + hstep, voffA);
;             PG8_WAIT_V(8); PG8_WAIT_L(0); PG8_BAR; PG8_MMA(0, 0, At, B0); PG8_MMA(0, 1, At, B1); PG8_BAR; PG8_SCHED;
;             PG8_LDA(At, 0, 1); PG8_STAGE(PG8_SB(0, 0), b2, voffB); PG8_STAGE(PG8_SB(0, 1), b2 + hstep, voffB); PG8_STAGE(PG8_SA(0, 0), a2, voffA);
;             PG8_WAIT_V(8); PG8_WAIT_L(0); PG8_BAR; PG8_MMA(1, 0, At, B0); PG8_MMA(1, 1, At, B1); PG8_BAR; PG8_SCHED;
.LBB0_971:
	ds_read_b128 v[130:133], v162
	ds_read_b128 v[134:137], v162 offset:1024
	ds_read_b128 v[154:157], v162 offset:2048
	ds_read_b128 v[166:169], v162 offset:3072
	ds_read_b128 v[172:175], v163
	ds_read_b128 v[176:179], v163 offset:1024
	ds_read_b128 v[180:183], v163 offset:2048
	ds_read_b128 v[184:187], v163 offset:3072
	s_add_u32 s24, s22, 0xfff50080
	s_addc_u32 s25, s23, -1
	s_cmp_eq_u32 s59, 40
	s_cselect_b32 s27, s5, s25
	s_cselect_b32 s26, s4, s24
	s_cselect_b32 s25, s21, s58
	s_cselect_b32 s24, s20, s57
	s_add_i32 m0, s39, 0xc000
	ds_read_b128 v[188:191], v164
	ds_read_b128 v[192:195], v164 offset:1024
	ds_read_b128 v[196:199], v164 offset:2048
	ds_read_b128 v[200:203], v164 offset:3072
	ds_read_b128 v[204:207], v164 offset:4096
	ds_read_b128 v[208:211], v164 offset:5120
	ds_read_b128 v[212:215], v164 offset:6144
	ds_read_b128 v[216:219], v164 offset:7168
	global_load_lds_dwordx4 v146, s[22:23]
	s_add_i32 m0, s39, 0xe000
	s_nop 0
	global_load_lds_dwordx4 v148, s[22:23]
	s_waitcnt vmcnt(8)
	s_waitcnt lgkmcnt(0)
	s_setprio 1
	s_barrier
	v_mfma_f32_16x16x32_bf16 v[126:129], v[130:133], v[188:191], v[126:129]
	v_mfma_f32_16x16x32_bf16 v[122:125], v[154:157], v[188:191], v[122:125]
	v_mfma_f32_16x16x32_bf16 v[110:113], v[130:133], v[196:199], v[110:113]
	v_mfma_f32_16x16x32_bf16 v[106:109], v[154:157], v[196:199], v[106:109]
	v_mfma_f32_16x16x32_bf16 v[94:97], v[130:133], v[204:207], v[94:97]
	v_mfma_f32_16x16x32_bf16 v[90:93], v[154:157], v[204:207], v[90:93]
	v_mfma_f32_16x16x32_bf16 v[78:81], v[130:133], v[212:215], v[78:81]
	v_mfma_f32_16x16x32_bf16 v[74:77], v[154:157], v[212:215], v[74:77]
	v_mfma_f32_16x16x32_bf16 v[126:129], v[134:137], v[192:195], v[126:129]
	v_mfma_f32_16x16x32_bf16 v[122:125], v[166:169], v[192:195], v[122:125]
	v_mfma_f32_16x16x32_bf16 v[110:113], v[134:137], v[200:203], v[110:113]
	v_mfma_f32_16x16x32_bf16 v[106:109], v[166:169], v[200:203], v[106:109]
	v_mfma_f32_16x16x32_bf16 v[94:97], v[134:137], v[208:211], v[94:97]
	v_mfma_f32_16x16x32_bf16 v[90:93], v[166:169], v[208:211], v[90:93]
	v_mfma_f32_16x16x32_bf16 v[78:81], v[134:137], v[216:219], v[78:81]
	v_mfma_f32_16x16x32_bf16 v[74:77], v[166:169], v[216:219], v[74:77]
	v_mfma_f32_16x16x32_bf16 v[118:121], v[172:175], v[188:191], v[118:121]
	v_mfma_f32_16x16x32_bf16 v[114:117], v[180:183], v[188:191], v[114:117]
	v_mfma_f32_16x16x32_bf16 v[102:105], v[172:175], v[196:199], v[102:105]
	v_mfma_f32_16x16x32_bf16 v[98:101], v[180:183], v[196:199], v[98:101]
	v_mfma_f32_16x16x32_bf16 v[86:89], v[172:175], v[204:207], v[86:89]
	v_mfma_f32_16x16x32_bf16 v[82:85], v[180:183], v[204:207], v[82:85]
	v_mfma_f32_16x16x32_bf16 v[70:73], v[172:175], v[212:215], v[70:73]
	v_mfma_f32_16x16x32_bf16 v[66:69], v[180:183], v[212:215], v[66:69]
	v_mfma_f32_16x16x32_bf16 v[118:121], v[176:179], v[192:195], v[118:121]
	v_mfma_f32_16x16x32_bf16 v[114:117], v[184:187], v[192:195], v[114:117]
	v_mfma_f32_16x16x32_bf16 v[102:105], v[176:179], v[200:203], v[102:105]
	v_mfma_f32_16x16x32_bf16 v[98:101], v[184:187], v[200:203], v[98:101]
	v_mfma_f32_16x16x32_bf16 v[86:89], v[176:179], v[208:211], v[86:89]
	v_mfma_f32_16x16x32_bf16 v[82:85], v[184:187], v[208:211], v[82:85]
	v_mfma_f32_16x16x32_bf16 v[70:73], v[176:179], v[216:219], v[70:73]
	v_mfma_f32_16x16x32_bf16 v[66:69], v[184:187], v[216:219], v[66:69]
	s_barrier
	s_setprio 0
	s_add_u32 s98, s24, s14
	s_addc_u32 s99, s25, s15
	s_add_u32 s100, s26, s14
	s_addc_u32 s101, s27, s15
	s_add_i32 s60, s51, s38
	s_mov_b32 m0, s60
	ds_read_b128 v[188:191], v164 offset:16384
	ds_read_b128 v[192:195], v164 offset:17408
	ds_read_b128 v[196:199], v164 offset:18432
	ds_read_b128 v[200:203], v164 offset:19456
	ds_read_b128 v[204:207], v164 offset:20480
	ds_read_b128 v[208:211], v164 offset:21504
	ds_read_b128 v[212:215], v164 offset:22528
	ds_read_b128 v[216:219], v164 offset:23552
	global_load_lds_dwordx4 v140, s[24:25]
	s_add_i32 m0, s60, 0x2000
	s_add_u32 s60, s24, 0xb0000
	s_addc_u32 s61, s25, 0
	s_add_i32 s62, s52, s38
	global_load_lds_dwordx4 v144, s[24:25]
	s_mov_b32 m0, s62
	s_nop 0
	global_load_lds_dwordx4 v140, s[60:61]
	s_add_i32 m0, s62, 0x2000
	s_nop 0
	global_load_lds_dwordx4 v144, s[60:61]
	s_mov_b32 m0, s39
	s_nop 0
	global_load_lds_dwordx4 v138, s[26:27]
	s_mov_b32 m0, s40
	s_nop 0
	global_load_lds_dwordx4 v142, s[26:27]
	s_waitcnt vmcnt(8)
	s_waitcnt lgkmcnt(0)
	s_setprio 1
	s_barrier
	v_mfma_f32_16x16x32_bf16 v[62:65], v[130:133], v[188:191], v[62:65]
	v_mfma_f32_16x16x32_bf16 v[58:61], v[154:157], v[188:191], v[58:61]
	v_mfma_f32_16x16x32_bf16 v[46:49], v[130:133], v[196:199], v[46:49]
	v_mfma_f32_16x16x32_bf16 v[42:45], v[154:157], v[196:199], v[42:45]
	v_mfma_f32_16x16x32_bf16 v[30:33], v[130:133], v[204:207], v[30:33]
	v_mfma_f32_16x16x32_bf16 v[26:29], v[154:157], v[204:207], v[26:29]
	v_mfma_f32_16x16x32_bf16 v[14:17], v[130:133], v[212:215], v[14:17]
	v_mfma_f32_16x16x32_bf16 v[10:13], v[154:157], v[212:215], v[10:13]
	v_mfma_f32_16x16x32_bf16 v[62:65], v[134:137], v[192:195], v[62:65]
	v_mfma_f32_16x16x32_bf16 v[58:61], v[166:169], v[192:195], v[58:61]
	v_mfma_f32_16x16x32_bf16 v[46:49], v[134:137], v[200:203], v[46:49]
	v_mfma_f32_16x16x32_bf16 v[42:45], v[166:169], v[200:203], v[42:45]
	v_mfma_f32_16x16x32_bf16 v[30:33], v[134:137], v[208:211], v[30:33]
	v_mfma_f32_16x16x32_bf16 v[26:29], v[166:169], v[208:211], v[26:29]
	v_mfma_f32_16x16x32_bf16 v[14:17], v[134:137], v[216:219], v[14:17]
	v_mfma_f32_16x16x32_bf16 v[10:13], v[166:169], v[216:219], v[10:13]
	v_mfma_f32_16x16x32_bf16 v[54:57], v[172:175], v[188:191], v[54:57]
	v_mfma_f32_16x16x32_bf16 v[50:53], v[180:183], v[188:191], v[50:53]
	v_mfma_f32_16x16x32_bf16 v[38:41], v[172:175], v[196:199], v[38:41]
	v_mfma_f32_16x16x32_bf16 v[34:37], v[180:183], v[196:199], v[34:37]
	v_mfma_f32_16x16x32_bf16 v[22:25], v[172:175], v[204:207], v[22:25]
	v_mfma_f32_16x16x32_bf16 v[18:21], v[180:183], v[204:207], v[18:21]
	v_mfma_f32_16x16x32_bf16 v[6:9], v[172:175], v[212:215], v[6:9]
	v_mfma_f32_16x16x32_bf16 v[2:5], v[180:183], v[212:215], v[2:5]
	v_mfma_f32_16x16x32_bf16 v[54:57], v[176:179], v[192:195], v[54:57]
	v_mfma_f32_16x16x32_bf16 v[50:53], v[184:187], v[192:195], v[50:53]
	v_mfma_f32_16x16x32_bf16 v[38:41], v[176:179], v[200:203], v[38:41]
	v_mfma_f32_16x16x32_bf16 v[34:37], v[184:187], v[200:203], v[34:37]
	v_mfma_f32_16x16x32_bf16 v[22:25], v[176:179], v[208:211], v[22:25]
	v_mfma_f32_16x16x32_bf16 v[18:21], v[184:187], v[208:211], v[18:21]
	v_mfma_f32_16x16x32_bf16 v[6:9], v[176:179], v[216:219], v[6:9]
	v_mfma_f32_16x16x32_bf16 v[2:5], v[184:187], v[216:219], v[2:5]
	s_barrier
; #define PG8_STAGE(bufoff, gbase, voff) do { _Pragma("unroll") for (int _i = 0; _i < 2; ++_i) \
;         __builtin_amdgcn_global_load_lds((const unsigned*)((const char*)(gbase) + (voff)[_i]), (LAS unsigned*)(lds + (bufoff) + ldsw + _i * 8192), 16, 0, 0); } while (0)
; #define PG8_LDA(dst, b, h) do { _Pragma("unroll") for (int m = 0; m < 4; ++m) _Pragma("unroll") for (int k = 0; k < 2; ++k) dst[m][k] = *(const LAS bf16x8*)(lds + PG8_SA(b, h) + aoff + m * 2048 + k * 1024); } while (0)
; #define PG8_LDB(dst, b, h) do { _Pragma("unroll") for (int n = 0; n < 2; ++n) _Pragma("unroll") for (int k = 0; k < 2; ++k) dst[n][k] = *(const LAS bf16x8*)(lds + PG8_SB(b, h) + boff + n * 2048 + k * 1024); } while (0)
; #define PG8_MMA(ai, bj, At, Bt) do { __builtin_amdgcn_s_setprio(1); _Pragma("unroll") for (int m = 0; m < 4; ++m) _Pragma("unroll") for (int n = 0; n < 2; ++n) _Pragma("unroll") for (int k = 0; k < 2; ++k) \
;         acc[ai][bj][m][n] = __builtin_amdgcn_mfma_f32_16x16x32_bf16(Bt[n][k], At[m][k], acc[ai][bj][m][n], 0, 0, 0); __builtin_amdgcn_s_setprio(0); } while (0)
; #define PG8_WAIT_V(n) asm volatile("s_waitcnt vmcnt(" #n ")" ::: "memory")
; #define PG8_WAIT_L(n) asm volatile("s_waitcnt lgkmcnt(" #n ")" ::: "memory")
; #define PG8_BAR __builtin_amdgcn_s_barrier()
; #define PG8_SCHED __builtin_amdgcn_sched_barrier(0)
; template <class Epi>
; __device__ __forceinline__ void gemm_phase(LAS unsigned char* lds, const Gemm g, const StaticOrder& S, const Epi& E) {
;     ...
;             PG8_LDB(B0, 1, 0); PG8_LDB(B1, 1, 1); PG8_SCHED; PG8_LDA(At, 1, 0); PG8_STAGE(PG8_SA(0, 1), a2 + hstep, voffA);
;             PG8_WAIT_V(8); PG8_WAIT_L(0); PG8_BAR; PG8_MMA(0, 0, At, B0); PG8_MMA(0, 1, At, B1); PG8_BAR; PG8_SCHED;
;             PG8_LDA(At, 1, 1); PG8_STAGE(PG8_SB(1, 0), b3, voffB); PG8_STAGE(PG8_SB(1, 1), b3 + hstep, voffB); PG8_STAGE(PG8_SA(1, 0), a3, voffA);
;             PG8_WAIT_V(8); PG8_WAIT_L(0); PG8_BAR; PG8_MMA(1, 0, At, B0); PG8_MMA(1, 1, At, B1); PG8_BAR; PG8_SCHED;
;         }
;         if (wr == 0) PG8_BAR;
	s_setprio 0
	s_add_i32 s60, 0, 0x18000
	s_add_i32 s61, 0, 0x1c000
	v_add_u32_e32 v166, s60, v160
	v_add_u32_e32 v184, s61, v160
	ds_read_b128 v[130:133], v166
	ds_read_b128 v[134:137], v166 offset:1024
	ds_read_b128 v[154:157], v166 offset:2048
	ds_read_b128 v[166:169], v166 offset:3072
	ds_read_b128 v[172:175], v184
	ds_read_b128 v[176:179], v184 offset:1024
	ds_read_b128 v[180:183], v184 offset:2048
	ds_read_b128 v[184:187], v184 offset:3072
	s_add_u32 s26, s26, 0xb0000
	s_addc_u32 s27, s27, 0
	s_mov_b32 m0, s41
	ds_read_b128 v[188:191], v164 offset:32768
	ds_read_b128 v[192:195], v164 offset:33792
	ds_read_b128 v[196:199], v164 offset:34816
	ds_read_b128 v[200:203], v164 offset:35840
	ds_read_b128 v[204:207], v164 offset:36864
	ds_read_b128 v[208:211], v164 offset:37888
	ds_read_b128 v[212:215], v164 offset:38912
	ds_read_b128 v[216:219], v164 offset:39936
	global_load_lds_dwordx4 v138, s[26:27]
	s_mov_b32 m0, s42
	s_nop 0
	global_load_lds_dwordx4 v142, s[26:27]
	s_waitcnt vmcnt(8)
	s_waitcnt lgkmcnt(0)
	s_setprio 1
	s_barrier
	v_mfma_f32_16x16x32_bf16 v[126:129], v[130:133], v[188:191], v[126:129]
	v_mfma_f32_16x16x32_bf16 v[122:125], v[154:157], v[188:191], v[122:125]
	v_mfma_f32_16x16x32_bf16 v[110:113], v[130:133], v[196:199], v[110:113]
	v_mfma_f32_16x16x32_bf16 v[106:109], v[154:157], v[196:199], v[106:109]
	v_mfma_f32_16x16x32_bf16 v[94:97], v[130:133], v[204:207], v[94:97]
	v_mfma_f32_16x16x32_bf16 v[90:93], v[154:157], v[204:207], v[90:93]
	v_mfma_f32_16x16x32_bf16 v[78:81], v[130:133], v[212:215], v[78:81]
	v_mfma_f32_16x16x32_bf16 v[74:77], v[154:157], v[212:215], v[74:77]
	v_mfma_f32_16x16x32_bf16 v[126:129], v[134:137], v[192:195], v[126:129]
	v_mfma_f32_16x16x32_bf16 v[122:125], v[166:169], v[192:195], v[122:125]
	v_mfma_f32_16x16x32_bf16 v[110:113], v[134:137], v[200:203], v[110:113]
	v_mfma_f32_16x16x32_bf16 v[106:109], v[166:169], v[200:203], v[106:109]
	v_mfma_f32_16x16x32_bf16 v[94:97], v[134:137], v[208:211], v[94:97]
	v_mfma_f32_16x16x32_bf16 v[90:93], v[166:169], v[208:211], v[90:93]
	v_mfma_f32_16x16x32_bf16 v[78:81], v[134:137], v[216:219], v[78:81]
	v_mfma_f32_16x16x32_bf16 v[74:77], v[166:169], v[216:219], v[74:77]
	v_mfma_f32_16x16x32_bf16 v[118:121], v[172:175], v[188:191], v[118:121]
	v_mfma_f32_16x16x32_bf16 v[114:117], v[180:183], v[188:191], v[114:117]
	v_mfma_f32_16x16x32_bf16 v[102:105], v[172:175], v[196:199], v[102:105]
	v_mfma_f32_16x16x32_bf16 v[98:101], v[180:183], v[196:199], v[98:101]
	v_mfma_f32_16x16x32_bf16 v[86:89], v[172:175], v[204:207], v[86:89]
	v_mfma_f32_16x16x32_bf16 v[82:85], v[180:183], v[204:207], v[82:85]
	v_mfma_f32_16x16x32_bf16 v[70:73], v[172:175], v[212:215], v[70:73]
	v_mfma_f32_16x16x32_bf16 v[66:69], v[180:183], v[212:215], v[66:69]
	v_mfma_f32_16x16x32_bf16 v[118:121], v[176:179], v[192:195], v[118:121]
	v_mfma_f32_16x16x32_bf16 v[114:117], v[184:187], v[192:195], v[114:117]
	v_mfma_f32_16x16x32_bf16 v[102:105], v[176:179], v[200:203], v[102:105]
	v_mfma_f32_16x16x32_bf16 v[98:101], v[184:187], v[200:203], v[98:101]
	v_mfma_f32_16x16x32_bf16 v[86:89], v[176:179], v[208:211], v[86:89]
	v_mfma_f32_16x16x32_bf16 v[82:85], v[184:187], v[208:211], v[82:85]
	v_mfma_f32_16x16x32_bf16 v[70:73], v[176:179], v[216:219], v[70:73]
	v_mfma_f32_16x16x32_bf16 v[66:69], v[184:187], v[216:219], v[66:69]
	s_barrier
	s_setprio 0
	s_add_i32 s26, s60, s38
	s_mov_b32 m0, s26
	ds_read_b128 v[188:191], v164 offset:49152
	ds_read_b128 v[192:195], v164 offset:50176
	ds_read_b128 v[196:199], v164 offset:51200
	ds_read_b128 v[200:203], v164 offset:52224
	ds_read_b128 v[204:207], v164 offset:53248
	ds_read_b128 v[208:211], v164 offset:54272
	ds_read_b128 v[212:215], v164 offset:55296
	ds_read_b128 v[216:219], v164 offset:56320
	global_load_lds_dwordx4 v140, s[98:99]
	s_add_i32 m0, s26, 0x2000
	s_add_u32 s24, s24, 0xb0080
	s_addc_u32 s25, s25, 0
	s_add_i32 s26, s61, s38
	global_load_lds_dwordx4 v144, s[98:99]
	s_mov_b32 m0, s26
	s_nop 0
	global_load_lds_dwordx4 v140, s[24:25]
	s_add_i32 m0, s26, 0x2000
	s_nop 0
	global_load_lds_dwordx4 v144, s[24:25]
	s_mov_b32 m0, s44
	s_nop 0
	global_load_lds_dwordx4 v138, s[100:101]
	s_mov_b32 m0, s45
	s_nop 0
	global_load_lds_dwordx4 v142, s[100:101]
	s_waitcnt vmcnt(8)
	s_waitcnt lgkmcnt(0)
	s_setprio 1
	s_barrier
	v_mfma_f32_16x16x32_bf16 v[62:65], v[130:133], v[188:191], v[62:65]
	v_mfma_f32_16x16x32_bf16 v[58:61], v[154:157], v[188:191], v[58:61]
	v_mfma_f32_16x16x32_bf16 v[46:49], v[130:133], v[196:199], v[46:49]
	v_mfma_f32_16x16x32_bf16 v[42:45], v[154:157], v[196:199], v[42:45]
	v_mfma_f32_16x16x32_bf16 v[30:33], v[130:133], v[204:207], v[30:33]
	v_mfma_f32_16x16x32_bf16 v[26:29], v[154:157], v[204:207], v[26:29]
	v_mfma_f32_16x16x32_bf16 v[14:17], v[130:133], v[212:215], v[14:17]
	v_mfma_f32_16x16x32_bf16 v[10:13], v[154:157], v[212:215], v[10:13]
	v_mfma_f32_16x16x32_bf16 v[62:65], v[134:137], v[192:195], v[62:65]
	v_mfma_f32_16x16x32_bf16 v[58:61], v[166:169], v[192:195], v[58:61]
	v_mfma_f32_16x16x32_bf16 v[46:49], v[134:137], v[200:203], v[46:49]
	v_mfma_f32_16x16x32_bf16 v[42:45], v[166:169], v[200:203], v[42:45]
	v_mfma_f32_16x16x32_bf16 v[30:33], v[134:137], v[208:211], v[30:33]
	v_mfma_f32_16x16x32_bf16 v[26:29], v[166:169], v[208:211], v[26:29]
	v_mfma_f32_16x16x32_bf16 v[14:17], v[134:137], v[216:219], v[14:17]
	v_mfma_f32_16x16x32_bf16 v[10:13], v[166:169], v[216:219], v[10:13]
	v_mfma_f32_16x16x32_bf16 v[54:57], v[172:175], v[188:191], v[54:57]
	v_mfma_f32_16x16x32_bf16 v[50:53], v[180:183], v[188:191], v[50:53]
	v_mfma_f32_16x16x32_bf16 v[38:41], v[172:175], v[196:199], v[38:41]
	v_mfma_f32_16x16x32_bf16 v[34:37], v[180:183], v[196:199], v[34:37]
	v_mfma_f32_16x16x32_bf16 v[22:25], v[172:175], v[204:207], v[22:25]
	v_mfma_f32_16x16x32_bf16 v[18:21], v[180:183], v[204:207], v[18:21]
	v_mfma_f32_16x16x32_bf16 v[6:9], v[172:175], v[212:215], v[6:9]
	v_mfma_f32_16x16x32_bf16 v[2:5], v[180:183], v[212:215], v[2:5]
	v_mfma_f32_16x16x32_bf16 v[54:57], v[176:179], v[192:195], v[54:57]
	v_mfma_f32_16x16x32_bf16 v[50:53], v[184:187], v[192:195], v[50:53]
	v_mfma_f32_16x16x32_bf16 v[38:41], v[176:179], v[200:203], v[38:41]
	v_mfma_f32_16x16x32_bf16 v[34:37], v[184:187], v[200:203], v[34:37]
	v_mfma_f32_16x16x32_bf16 v[22:25], v[176:179], v[208:211], v[22:25]
	v_mfma_f32_16x16x32_bf16 v[18:21], v[184:187], v[208:211], v[18:21]
	v_mfma_f32_16x16x32_bf16 v[6:9], v[176:179], v[216:219], v[6:9]
	v_mfma_f32_16x16x32_bf16 v[2:5], v[184:187], v[216:219], v[2:5]
	s_barrier
	s_setprio 0
	s_add_i32 s59, s59, 2
	s_add_u32 s22, s22, 0x100
	s_addc_u32 s23, s23, 0
	s_add_u32 s57, s57, 0x100
	s_addc_u32 s58, s58, 0
	s_cmp_gt_u32 s59, 41
	s_cbranch_scc0 .LBB0_971
	s_and_b64 vcc, exec, s[18:19]
	s_cbranch_vccz .LBB0_974
	s_barrier
